# hipcc per-block s_setprio flips removed from GEMM loops; priority raised only inside the DMA-heavy (6-piece) load segments
# speedup vs baseline: 1.0419x; 1.0031x over previous
; __device__ __forceinline__ int lane_id_() { int l; asm volatile("v_mbcnt_lo_u32_b32 %0, -1, 0\n\tv_mbcnt_hi_u32_b32 %0, -1, %0" : "=v"(l)); return l; }
; #define PG8_LAS __attribute__((address_space(3)))
;     __device__ __forceinline__ void prefetch(PG8_LAS unsigned char* lds, int wid, const Unit& u, int wr, int fr, int fq) const {
;         { const int l_ = lane_id_(); fr = l_ & 15; fq = l_ >> 4; }
; #pragma unroll
;         for (int j = 0; j < 2; ++j) { const int i = 2 * fq + j;
;             __builtin_amdgcn_global_load_lds((const unsigned*)(ssq + u.pm * BM + wr * 64 + fr + (i >> 2) * HALF + (i & 3) * 16), (PG8_LAS unsigned*)(lds + PRE_SLOT + wid * 512 + j * 256), 4, 0, 0); }
;     }
.LBB0_102:
	s_lshl_b32 s2, s14, 8
	s_ashr_i32 s3, s2, 31
	s_lshl_b64 s[2:3], s[2:3], 2
	v_mbcnt_lo_u32_b32 v6, -1, 0
	v_mbcnt_hi_u32_b32 v6, -1, v6
	s_add_u32 s2, s60, s2
	v_and_b32_e32 v0, 15, v6
	v_lshlrev_b32_e32 v2, 2, v6
	v_and_b32_e32 v2, 0xffffff80, v2
	s_addc_u32 s3, s61, s3
	v_lshlrev_b32_e32 v0, 2, v0
	v_ashrrev_i32_e32 v3, 31, v2
	v_lshl_add_u64 v[4:5], s[2:3], 0, v[0:1]
	v_lshlrev_b32_e32 v0, 3, v6
	v_lshl_add_u64 v[2:3], v[2:3], 2, v[4:5]
	v_and_b32_e32 v0, 0x80, v0
	s_mov_b32 m0, s41
	v_lshl_add_u64 v[2:3], v[2:3], 0, v[0:1]
	global_load_lds_dword v[2:3], off
	v_lshl_add_u64 v[2:3], v[2:3], 0, 64
	s_add_i32 m0, s41, 0x100
	s_add_u32 s20, s16, 0x100
	global_load_lds_dword v[2:3], off
	ds_read_b128 v[2:5], v151
	ds_read_b128 v[6:9], v151 offset:1024
	ds_read_b128 v[10:13], v151 offset:2048
	ds_read_b128 v[14:17], v151 offset:3072
	ds_read_b128 v[18:21], v150
	ds_read_b128 v[22:25], v150 offset:1024
	ds_read_b128 v[26:29], v150 offset:2048
	ds_read_b128 v[30:33], v150 offset:3072
	s_addc_u32 s21, s17, 0
	s_add_u32 s2, s16, 0x180
	s_addc_u32 s3, s17, 0
	s_add_u32 s22, s18, 0x100
	s_addc_u32 s23, s19, 0
	s_add_u32 s24, s16, 0x40080
	s_addc_u32 s25, s17, 0
	s_mov_b32 m0, s69
	ds_read_b128 v[34:37], v149
	ds_read_b128 v[38:41], v149 offset:1024
	ds_read_b128 v[42:45], v149 offset:2048
	ds_read_b128 v[46:49], v149 offset:3072
	ds_read_b128 v[50:53], v149 offset:4096
	ds_read_b128 v[54:57], v149 offset:5120
	ds_read_b128 v[58:61], v149 offset:6144
	ds_read_b128 v[62:65], v149 offset:7168
	s_nop 0
	global_load_lds_dwordx4 v138, s[24:25]
	s_mov_b32 m0, s6
	s_nop 0
	global_load_lds_dwordx4 v134, s[24:25]
	s_waitcnt vmcnt(18)
	s_waitcnt lgkmcnt(0)
	s_barrier
	s_waitcnt lgkmcnt(0)
	v_mfma_f32_16x16x32_bf16 v[90:93], v[2:5], v[58:61], 0
	v_mfma_f32_16x16x32_bf16 v[66:69], v[2:5], v[34:37], 0
	v_mfma_f32_16x16x32_bf16 v[70:73], v[10:13], v[34:37], 0
	v_mfma_f32_16x16x32_bf16 v[74:77], v[2:5], v[42:45], 0
	v_mfma_f32_16x16x32_bf16 v[78:81], v[10:13], v[42:45], 0
	v_mfma_f32_16x16x32_bf16 v[82:85], v[2:5], v[50:53], 0
	v_mfma_f32_16x16x32_bf16 v[86:89], v[10:13], v[50:53], 0
	v_mfma_f32_16x16x32_bf16 v[96:99], v[6:9], v[62:65], v[90:93]
	v_mfma_f32_16x16x32_bf16 v[90:93], v[10:13], v[58:61], 0
	v_mfma_f32_16x16x32_bf16 v[66:69], v[6:9], v[38:41], v[66:69]
	v_mfma_f32_16x16x32_bf16 v[70:73], v[14:17], v[38:41], v[70:73]
	v_mfma_f32_16x16x32_bf16 v[74:77], v[6:9], v[46:49], v[74:77]
	v_mfma_f32_16x16x32_bf16 v[78:81], v[14:17], v[46:49], v[78:81]
	v_mfma_f32_16x16x32_bf16 v[82:85], v[6:9], v[54:57], v[82:85]
	v_mfma_f32_16x16x32_bf16 v[86:89], v[14:17], v[54:57], v[86:89]
	v_mfma_f32_16x16x32_bf16 v[104:107], v[14:17], v[62:65], v[90:93]
	v_mfma_f32_16x16x32_bf16 v[90:93], v[18:21], v[34:37], 0
	v_mfma_f32_16x16x32_bf16 v[34:37], v[26:29], v[34:37], 0
	v_mfma_f32_16x16x32_bf16 v[112:115], v[22:25], v[38:41], v[90:93]
	v_mfma_f32_16x16x32_bf16 v[34:37], v[30:33], v[38:41], v[34:37]
	v_mfma_f32_16x16x32_bf16 v[38:41], v[18:21], v[42:45], 0
	v_mfma_f32_16x16x32_bf16 v[42:45], v[26:29], v[42:45], 0
	v_mfma_f32_16x16x32_bf16 v[38:41], v[22:25], v[46:49], v[38:41]
	v_mfma_f32_16x16x32_bf16 v[42:45], v[30:33], v[46:49], v[42:45]
	v_mfma_f32_16x16x32_bf16 v[46:49], v[18:21], v[50:53], 0
	v_mfma_f32_16x16x32_bf16 v[50:53], v[26:29], v[50:53], 0
	v_mfma_f32_16x16x32_bf16 v[46:49], v[22:25], v[54:57], v[46:49]
	v_mfma_f32_16x16x32_bf16 v[50:53], v[30:33], v[54:57], v[50:53]
	v_mfma_f32_16x16x32_bf16 v[54:57], v[18:21], v[58:61], 0
	v_mfma_f32_16x16x32_bf16 v[54:57], v[22:25], v[62:65], v[54:57]
	v_mfma_f32_16x16x32_bf16 v[58:61], v[26:29], v[58:61], 0
	v_mfma_f32_16x16x32_bf16 v[154:157], v[30:33], v[62:65], v[58:61]
	s_barrier
	s_setprio 1
	s_mov_b32 m0, s68
	s_nop 3
	ds_read_b128 v[58:61], v149 offset:16384
	ds_read_b128 v[62:65], v149 offset:17408
	ds_read_b128 v[90:93], v149 offset:18432
	ds_read_b128 v[100:103], v149 offset:19456
	ds_read_b128 v[108:111], v149 offset:20480
	ds_read_b128 v[116:119], v149 offset:21504
	ds_read_b128 v[120:123], v149 offset:22528
	ds_read_b128 v[124:127], v149 offset:23552
	s_nop 0
	global_load_lds_dwordx4 v136, s[22:23]
	s_mov_b64 s[98:99], s[22:23]
	s_add_u32 s22, s18, 0x40100
	s_mov_b32 m0, s13
	s_addc_u32 s23, s19, 0
	global_load_lds_dwordx4 v132, s[98:99]
	s_mov_b32 m0, s15
	s_nop 0
	global_load_lds_dwordx4 v136, s[22:23]
	s_mov_b32 m0, s67
	s_nop 0
	global_load_lds_dwordx4 v132, s[22:23]
	s_mov_b32 m0, s42
	s_nop 0
	global_load_lds_dwordx4 v138, s[20:21]
	s_mov_b32 m0, s43
	s_nop 0
	global_load_lds_dwordx4 v134, s[20:21]
	s_setprio 0
	s_waitcnt vmcnt(18)
	s_waitcnt lgkmcnt(0)
	s_barrier
	s_waitcnt lgkmcnt(0)
	v_mfma_f32_16x16x32_bf16 v[128:131], v[2:5], v[58:61], 0
	v_mfma_f32_16x16x32_bf16 v[158:161], v[6:9], v[62:65], v[128:131]
	v_mfma_f32_16x16x32_bf16 v[128:131], v[10:13], v[58:61], 0
	v_mfma_f32_16x16x32_bf16 v[162:165], v[14:17], v[62:65], v[128:131]
	v_mfma_f32_16x16x32_bf16 v[128:131], v[2:5], v[90:93], 0
	v_mfma_f32_16x16x32_bf16 v[166:169], v[6:9], v[100:103], v[128:131]
	v_mfma_f32_16x16x32_bf16 v[128:131], v[10:13], v[90:93], 0
	v_mfma_f32_16x16x32_bf16 v[170:173], v[14:17], v[100:103], v[128:131]
	v_mfma_f32_16x16x32_bf16 v[128:131], v[2:5], v[108:111], 0
	v_mfma_f32_16x16x32_bf16 v[2:5], v[2:5], v[120:123], 0
	v_mfma_f32_16x16x32_bf16 v[176:179], v[6:9], v[116:119], v[128:131]
	v_mfma_f32_16x16x32_bf16 v[2:5], v[6:9], v[124:127], v[2:5]
	v_mfma_f32_16x16x32_bf16 v[6:9], v[10:13], v[120:123], 0
	v_mfma_f32_16x16x32_bf16 v[128:131], v[10:13], v[108:111], 0
	v_mfma_f32_16x16x32_bf16 v[6:9], v[14:17], v[124:127], v[6:9]
	v_mfma_f32_16x16x32_bf16 v[180:183], v[14:17], v[116:119], v[128:131]
	v_mfma_f32_16x16x32_bf16 v[14:17], v[26:29], v[58:61], 0
	v_mfma_f32_16x16x32_bf16 v[184:187], v[30:33], v[62:65], v[14:17]
	v_mfma_f32_16x16x32_bf16 v[14:17], v[18:21], v[90:93], 0
	v_mfma_f32_16x16x32_bf16 v[188:191], v[22:25], v[100:103], v[14:17]
	v_mfma_f32_16x16x32_bf16 v[14:17], v[26:29], v[90:93], 0
	v_mfma_f32_16x16x32_bf16 v[192:195], v[30:33], v[100:103], v[14:17]
	v_mfma_f32_16x16x32_bf16 v[14:17], v[18:21], v[108:111], 0
	v_mfma_f32_16x16x32_bf16 v[196:199], v[22:25], v[116:119], v[14:17]
	v_mfma_f32_16x16x32_bf16 v[14:17], v[26:29], v[108:111], 0
	v_mfma_f32_16x16x32_bf16 v[10:13], v[18:21], v[58:61], 0
	v_mfma_f32_16x16x32_bf16 v[200:203], v[30:33], v[116:119], v[14:17]
	v_mfma_f32_16x16x32_bf16 v[14:17], v[18:21], v[120:123], 0
	v_mfma_f32_16x16x32_bf16 v[10:13], v[22:25], v[62:65], v[10:13]
	v_mfma_f32_16x16x32_bf16 v[204:207], v[22:25], v[124:127], v[14:17]
	v_mfma_f32_16x16x32_bf16 v[14:17], v[26:29], v[120:123], 0
	v_mfma_f32_16x16x32_bf16 v[208:211], v[30:33], v[124:127], v[14:17]
	s_barrier
	s_nop 4
	ds_read_b128 v[14:17], v152
	ds_read_b128 v[18:21], v152 offset:1024
	ds_read_b128 v[28:31], v152 offset:2048
	ds_read_b128 v[212:215], v152 offset:3072
	ds_read_b128 v[216:219], v153
	ds_read_b128 v[220:223], v153 offset:1024
	ds_read_b128 v[224:227], v153 offset:2048
	ds_read_b128 v[150:153], v153 offset:3072
	s_add_u32 s20, s16, 0x40100
	s_addc_u32 s21, s17, 0
	s_mov_b32 m0, s52
	ds_read_b128 v[22:25], v149 offset:32768
	ds_read_b128 v[120:123], v149 offset:33792
	ds_read_b128 v[228:231], v149 offset:34816
	ds_read_b128 v[232:235], v149 offset:35840
	ds_read_b128 v[236:239], v149 offset:36864
	ds_read_b128 v[240:243], v149 offset:37888
	ds_read_b128 v[244:247], v149 offset:38912
	ds_read_b128 v[248:251], v149 offset:39936
	s_nop 0
	global_load_lds_dwordx4 v138, s[20:21]
	s_mov_b32 m0, s53
	s_nop 0
	global_load_lds_dwordx4 v134, s[20:21]
	s_waitcnt vmcnt(18)
	s_waitcnt lgkmcnt(0)
	s_barrier
	s_waitcnt lgkmcnt(0)
	v_mfma_f32_16x16x32_bf16 v[58:61], v[14:17], v[22:25], v[66:69]
	v_mfma_f32_16x16x32_bf16 v[124:127], v[18:21], v[120:123], v[58:61]
	v_mfma_f32_16x16x32_bf16 v[58:61], v[28:31], v[22:25], v[70:73]
	v_mfma_f32_16x16x32_bf16 v[116:119], v[212:215], v[120:123], v[58:61]
	v_mfma_f32_16x16x32_bf16 v[58:61], v[14:17], v[228:231], v[74:77]
	v_mfma_f32_16x16x32_bf16 v[108:111], v[18:21], v[232:235], v[58:61]
	v_mfma_f32_16x16x32_bf16 v[58:61], v[28:31], v[228:231], v[78:81]
	v_mfma_f32_16x16x32_bf16 v[100:103], v[212:215], v[232:235], v[58:61]
	v_mfma_f32_16x16x32_bf16 v[58:61], v[14:17], v[236:239], v[82:85]
	v_mfma_f32_16x16x32_bf16 v[92:95], v[18:21], v[240:243], v[58:61]
	v_mfma_f32_16x16x32_bf16 v[58:61], v[28:31], v[236:239], v[86:89]
	v_mfma_f32_16x16x32_bf16 v[84:87], v[212:215], v[240:243], v[58:61]
	v_mfma_f32_16x16x32_bf16 v[58:61], v[14:17], v[244:247], v[96:99]
	v_mfma_f32_16x16x32_bf16 v[76:79], v[18:21], v[248:251], v[58:61]
	v_mfma_f32_16x16x32_bf16 v[58:61], v[28:31], v[244:247], v[104:107]
	v_mfma_f32_16x16x32_bf16 v[60:63], v[212:215], v[248:251], v[58:61]
	v_mfma_f32_16x16x32_bf16 v[64:67], v[216:219], v[22:25], v[112:115]
	v_mfma_f32_16x16x32_bf16 v[22:25], v[224:227], v[22:25], v[34:37]
	v_mfma_f32_16x16x32_bf16 v[128:131], v[220:223], v[120:123], v[64:67]
	v_mfma_f32_16x16x32_bf16 v[120:123], v[150:153], v[120:123], v[22:25]
	v_mfma_f32_16x16x32_bf16 v[22:25], v[216:219], v[228:231], v[38:41]
	v_mfma_f32_16x16x32_bf16 v[112:115], v[220:223], v[232:235], v[22:25]
	v_mfma_f32_16x16x32_bf16 v[22:25], v[224:227], v[228:231], v[42:45]
	v_mfma_f32_16x16x32_bf16 v[104:107], v[150:153], v[232:235], v[22:25]
	v_mfma_f32_16x16x32_bf16 v[22:25], v[216:219], v[236:239], v[46:49]
	v_mfma_f32_16x16x32_bf16 v[96:99], v[220:223], v[240:243], v[22:25]
	v_mfma_f32_16x16x32_bf16 v[22:25], v[224:227], v[236:239], v[50:53]
	v_mfma_f32_16x16x32_bf16 v[88:91], v[150:153], v[240:243], v[22:25]
	v_mfma_f32_16x16x32_bf16 v[22:25], v[216:219], v[244:247], v[54:57]
	v_mfma_f32_16x16x32_bf16 v[80:83], v[220:223], v[248:251], v[22:25]
	v_mfma_f32_16x16x32_bf16 v[22:25], v[224:227], v[244:247], v[154:157]
	v_mfma_f32_16x16x32_bf16 v[72:75], v[150:153], v[248:251], v[22:25]
	s_barrier
	s_setprio 1
	s_add_u32 s20, s18, 0x180
	s_addc_u32 s21, s19, 0
	s_mov_b32 m0, s29
	ds_read_b128 v[36:39], v149 offset:49152
	ds_read_b128 v[44:47], v149 offset:50176
	ds_read_b128 v[154:157], v149 offset:51200
	ds_read_b128 v[228:231], v149 offset:52224
	ds_read_b128 v[232:235], v149 offset:53248
	ds_read_b128 v[236:239], v149 offset:54272
	ds_read_b128 v[240:243], v149 offset:55296
	ds_read_b128 v[244:247], v149 offset:56320
	s_nop 0
	global_load_lds_dwordx4 v136, s[20:21]
	s_mov_b64 s[98:99], s[20:21]
	s_add_u32 s20, s18, 0x40180
	s_mov_b32 m0, s28
	s_addc_u32 s21, s19, 0
	global_load_lds_dwordx4 v132, s[98:99]
	s_mov_b32 m0, s26
	s_nop 0
	global_load_lds_dwordx4 v136, s[20:21]
	s_mov_b32 m0, s27
	s_nop 0
	global_load_lds_dwordx4 v132, s[20:21]
	s_mov_b32 m0, s55
	s_nop 0
	global_load_lds_dwordx4 v138, s[2:3]
	s_mov_b32 m0, s58
	s_nop 0
	global_load_lds_dwordx4 v134, s[2:3]
	s_setprio 0
	s_waitcnt vmcnt(18)
	s_waitcnt lgkmcnt(0)
	s_barrier
	s_waitcnt lgkmcnt(0)
	v_mfma_f32_16x16x32_bf16 v[22:25], v[14:17], v[36:39], v[158:161]
	v_mfma_f32_16x16x32_bf16 v[68:71], v[18:21], v[44:47], v[22:25]
	v_mfma_f32_16x16x32_bf16 v[22:25], v[28:31], v[36:39], v[162:165]
	v_mfma_f32_16x16x32_bf16 v[56:59], v[212:215], v[44:47], v[22:25]
	v_mfma_f32_16x16x32_bf16 v[22:25], v[14:17], v[154:157], v[166:169]
	v_mfma_f32_16x16x32_bf16 v[48:51], v[18:21], v[228:231], v[22:25]
	v_mfma_f32_16x16x32_bf16 v[22:25], v[28:31], v[154:157], v[170:173]
	v_mfma_f32_16x16x32_bf16 v[40:43], v[212:215], v[228:231], v[22:25]
	v_mfma_f32_16x16x32_bf16 v[22:25], v[14:17], v[232:235], v[176:179]
	v_mfma_f32_16x16x32_bf16 v[2:5], v[14:17], v[240:243], v[2:5]
	v_mfma_f32_16x16x32_bf16 v[32:35], v[18:21], v[236:239], v[22:25]
	v_mfma_f32_16x16x32_bf16 v[22:25], v[28:31], v[232:235], v[180:183]
	v_mfma_f32_16x16x32_bf16 v[16:19], v[18:21], v[244:247], v[2:5]
	v_mfma_f32_16x16x32_bf16 v[2:5], v[28:31], v[240:243], v[6:9]
	v_mfma_f32_16x16x32_bf16 v[24:27], v[212:215], v[236:239], v[22:25]
	v_mfma_f32_16x16x32_bf16 v[4:7], v[212:215], v[244:247], v[2:5]
	v_mfma_f32_16x16x32_bf16 v[8:11], v[216:219], v[36:39], v[10:13]
	v_mfma_f32_16x16x32_bf16 v[64:67], v[220:223], v[44:47], v[8:11]
	v_mfma_f32_16x16x32_bf16 v[8:11], v[224:227], v[36:39], v[184:187]
	v_mfma_f32_16x16x32_bf16 v[52:55], v[150:153], v[44:47], v[8:11]
	v_mfma_f32_16x16x32_bf16 v[8:11], v[216:219], v[154:157], v[188:191]
	v_mfma_f32_16x16x32_bf16 v[44:47], v[220:223], v[228:231], v[8:11]
	v_mfma_f32_16x16x32_bf16 v[8:11], v[224:227], v[154:157], v[192:195]
	v_mfma_f32_16x16x32_bf16 v[36:39], v[150:153], v[228:231], v[8:11]
	v_mfma_f32_16x16x32_bf16 v[8:11], v[216:219], v[232:235], v[196:199]
	v_mfma_f32_16x16x32_bf16 v[28:31], v[220:223], v[236:239], v[8:11]
	v_mfma_f32_16x16x32_bf16 v[8:11], v[224:227], v[232:235], v[200:203]
	v_mfma_f32_16x16x32_bf16 v[20:23], v[150:153], v[236:239], v[8:11]
	v_mfma_f32_16x16x32_bf16 v[8:11], v[216:219], v[240:243], v[204:207]
	v_mfma_f32_16x16x32_bf16 v[12:15], v[220:223], v[244:247], v[8:11]
	v_mfma_f32_16x16x32_bf16 v[8:11], v[224:227], v[240:243], v[208:211]
	v_mfma_f32_16x16x32_bf16 v[8:11], v[150:153], v[244:247], v[8:11]
	s_barrier
	s_mov_b64 s[2:3], 0

; template <class Epi, class Sched, bool ALIGN_EPI = false, bool SP2 = false>
; __device__ __forceinline__ void gemm_phase(PG8_LAS unsigned char* lds, const Gemm g, const Sched& S, const Epi& E, int wave_s) {
;     ...
;             const char* a1 = cA + (size_t)(t + 1) * kstep;
;             const char* a2 = last ? nA : cA + (size_t)(t + 2) * kstep; const char* b2 = last ? nB : cB + (size_t)(t + 2) * kstep;
;             const char* a3 = a2 + kstep; const char* b3 = b2 + kstep;
.LBB0_107:
	v_add_u32_e32 v151, s63, v146
	v_add_u32_e32 v150, s64, v146
	ds_read_b128 v[152:155], v151
	ds_read_b128 v[156:159], v151 offset:1024
	ds_read_b128 v[160:163], v151 offset:2048
	ds_read_b128 v[164:167], v151 offset:3072
	ds_read_b128 v[168:171], v150
	ds_read_b128 v[176:179], v150 offset:1024
	ds_read_b128 v[180:183], v150 offset:2048
	ds_read_b128 v[184:187], v150 offset:3072
	s_add_u32 s22, s30, 0x100
	s_addc_u32 s23, s31, 0
	s_cmp_eq_u32 s76, 12
	s_cselect_b32 s28, s73, s22
	s_cselect_b32 s29, s72, s23
	s_cselect_b32 s26, s75, s77
	s_cselect_b32 s27, s74, s78
	s_add_u32 s24, s28, 0x80
	s_addc_u32 s25, s29, 0
	s_add_u32 s30, s30, 0x40080
	s_addc_u32 s31, s31, 0
	s_add_i32 s69, s42, 0xc000
	ds_read_b128 v[188:191], v149
	ds_read_b128 v[192:195], v149 offset:1024
	ds_read_b128 v[196:199], v149 offset:2048
	ds_read_b128 v[200:203], v149 offset:3072
	ds_read_b128 v[204:207], v149 offset:4096
	ds_read_b128 v[208:211], v149 offset:5120
	ds_read_b128 v[212:215], v149 offset:6144
	ds_read_b128 v[216:219], v149 offset:7168
	s_mov_b32 m0, s69
	s_add_i32 s6, s42, 0xe000
	global_load_lds_dwordx4 v138, s[30:31]
	s_mov_b32 m0, s6
	s_nop 0
	global_load_lds_dwordx4 v134, s[30:31]
	s_waitcnt vmcnt(8)
	s_waitcnt lgkmcnt(0)
	s_barrier
	s_waitcnt lgkmcnt(0)
	v_mfma_f32_16x16x32_bf16 v[124:127], v[152:155], v[188:191], v[124:127]
	v_mfma_f32_16x16x32_bf16 v[116:119], v[160:163], v[188:191], v[116:119]
	v_mfma_f32_16x16x32_bf16 v[108:111], v[152:155], v[196:199], v[108:111]
	v_mfma_f32_16x16x32_bf16 v[100:103], v[160:163], v[196:199], v[100:103]
	v_mfma_f32_16x16x32_bf16 v[92:95], v[152:155], v[204:207], v[92:95]
	v_mfma_f32_16x16x32_bf16 v[84:87], v[160:163], v[204:207], v[84:87]
	v_mfma_f32_16x16x32_bf16 v[76:79], v[152:155], v[212:215], v[76:79]
	v_mfma_f32_16x16x32_bf16 v[60:63], v[160:163], v[212:215], v[60:63]
	v_mfma_f32_16x16x32_bf16 v[124:127], v[156:159], v[192:195], v[124:127]
	v_mfma_f32_16x16x32_bf16 v[116:119], v[164:167], v[192:195], v[116:119]
	v_mfma_f32_16x16x32_bf16 v[108:111], v[156:159], v[200:203], v[108:111]
	v_mfma_f32_16x16x32_bf16 v[100:103], v[164:167], v[200:203], v[100:103]
	v_mfma_f32_16x16x32_bf16 v[92:95], v[156:159], v[208:211], v[92:95]
	v_mfma_f32_16x16x32_bf16 v[84:87], v[164:167], v[208:211], v[84:87]
	v_mfma_f32_16x16x32_bf16 v[76:79], v[156:159], v[216:219], v[76:79]
	v_mfma_f32_16x16x32_bf16 v[60:63], v[164:167], v[216:219], v[60:63]
	v_mfma_f32_16x16x32_bf16 v[128:131], v[168:171], v[188:191], v[128:131]
	v_mfma_f32_16x16x32_bf16 v[120:123], v[180:183], v[188:191], v[120:123]
	v_mfma_f32_16x16x32_bf16 v[112:115], v[168:171], v[196:199], v[112:115]
	v_mfma_f32_16x16x32_bf16 v[104:107], v[180:183], v[196:199], v[104:107]
	v_mfma_f32_16x16x32_bf16 v[96:99], v[168:171], v[204:207], v[96:99]
	v_mfma_f32_16x16x32_bf16 v[88:91], v[180:183], v[204:207], v[88:91]
	v_mfma_f32_16x16x32_bf16 v[80:83], v[168:171], v[212:215], v[80:83]
	v_mfma_f32_16x16x32_bf16 v[72:75], v[180:183], v[212:215], v[72:75]
	v_mfma_f32_16x16x32_bf16 v[128:131], v[176:179], v[192:195], v[128:131]
	v_mfma_f32_16x16x32_bf16 v[120:123], v[184:187], v[192:195], v[120:123]
	v_mfma_f32_16x16x32_bf16 v[112:115], v[176:179], v[200:203], v[112:115]
	v_mfma_f32_16x16x32_bf16 v[104:107], v[184:187], v[200:203], v[104:107]
	v_mfma_f32_16x16x32_bf16 v[96:99], v[176:179], v[208:211], v[96:99]
	v_mfma_f32_16x16x32_bf16 v[88:91], v[184:187], v[208:211], v[88:91]
	v_mfma_f32_16x16x32_bf16 v[80:83], v[176:179], v[216:219], v[80:83]
	v_mfma_f32_16x16x32_bf16 v[72:75], v[184:187], v[216:219], v[72:75]
	s_barrier
	s_setprio 1
	s_mov_b64 s[30:31], s[26:27]
	s_add_i32 s68, s63, s38
	ds_read_b128 v[188:191], v149 offset:16384
	ds_read_b128 v[192:195], v149 offset:17408
	ds_read_b128 v[196:199], v149 offset:18432
	ds_read_b128 v[200:203], v149 offset:19456
	ds_read_b128 v[204:207], v149 offset:20480
	ds_read_b128 v[208:211], v149 offset:21504
	ds_read_b128 v[212:215], v149 offset:22528
	ds_read_b128 v[216:219], v149 offset:23552
	s_mov_b32 m0, s68
	s_add_i32 s13, s68, 0x2000
	global_load_lds_dwordx4 v136, s[30:31]
	s_mov_b64 s[98:99], s[30:31]
	s_add_u32 s30, s26, 0x40000
	s_mov_b32 m0, s13
	s_addc_u32 s31, s27, 0
	s_add_i32 s15, s64, s38
	global_load_lds_dwordx4 v132, s[98:99]
	s_mov_b32 m0, s15
	s_add_i32 s67, s15, 0x2000
	global_load_lds_dwordx4 v136, s[30:31]
	s_mov_b64 s[98:99], s[30:31]
	s_mov_b32 m0, s67
	s_mov_b64 s[30:31], s[28:29]
	global_load_lds_dwordx4 v132, s[98:99]
	s_mov_b32 m0, s42
	s_nop 0
	global_load_lds_dwordx4 v138, s[30:31]
	s_mov_b32 m0, s43
	s_nop 0
	global_load_lds_dwordx4 v134, s[30:31]
	s_setprio 0
	s_waitcnt vmcnt(8)
	s_waitcnt lgkmcnt(0)
	s_barrier
	s_waitcnt lgkmcnt(0)
	v_mfma_f32_16x16x32_bf16 v[68:71], v[152:155], v[188:191], v[68:71]
	v_mfma_f32_16x16x32_bf16 v[56:59], v[160:163], v[188:191], v[56:59]
	v_mfma_f32_16x16x32_bf16 v[48:51], v[152:155], v[196:199], v[48:51]
	v_mfma_f32_16x16x32_bf16 v[40:43], v[160:163], v[196:199], v[40:43]
	v_mfma_f32_16x16x32_bf16 v[32:35], v[152:155], v[204:207], v[32:35]
	v_mfma_f32_16x16x32_bf16 v[24:27], v[160:163], v[204:207], v[24:27]
	v_mfma_f32_16x16x32_bf16 v[16:19], v[152:155], v[212:215], v[16:19]
	v_mfma_f32_16x16x32_bf16 v[2:5], v[160:163], v[212:215], v[4:7]
	v_mfma_f32_16x16x32_bf16 v[68:71], v[156:159], v[192:195], v[68:71]
	v_mfma_f32_16x16x32_bf16 v[56:59], v[164:167], v[192:195], v[56:59]
	v_mfma_f32_16x16x32_bf16 v[48:51], v[156:159], v[200:203], v[48:51]
	v_mfma_f32_16x16x32_bf16 v[40:43], v[164:167], v[200:203], v[40:43]
	v_mfma_f32_16x16x32_bf16 v[32:35], v[156:159], v[208:211], v[32:35]
	v_mfma_f32_16x16x32_bf16 v[24:27], v[164:167], v[208:211], v[24:27]
	v_mfma_f32_16x16x32_bf16 v[16:19], v[156:159], v[216:219], v[16:19]
	v_mfma_f32_16x16x32_bf16 v[2:5], v[164:167], v[216:219], v[2:5]
	v_mfma_f32_16x16x32_bf16 v[64:67], v[168:171], v[188:191], v[64:67]
	v_mfma_f32_16x16x32_bf16 v[52:55], v[180:183], v[188:191], v[52:55]
	v_mfma_f32_16x16x32_bf16 v[44:47], v[168:171], v[196:199], v[44:47]
	v_mfma_f32_16x16x32_bf16 v[36:39], v[180:183], v[196:199], v[36:39]
	v_mfma_f32_16x16x32_bf16 v[28:31], v[168:171], v[204:207], v[28:31]
	v_mfma_f32_16x16x32_bf16 v[20:23], v[180:183], v[204:207], v[20:23]
	v_mfma_f32_16x16x32_bf16 v[12:15], v[168:171], v[212:215], v[12:15]
	v_mfma_f32_16x16x32_bf16 v[6:9], v[180:183], v[212:215], v[8:11]
	v_mfma_f32_16x16x32_bf16 v[64:67], v[176:179], v[192:195], v[64:67]
	v_mfma_f32_16x16x32_bf16 v[52:55], v[184:187], v[192:195], v[52:55]
	v_mfma_f32_16x16x32_bf16 v[44:47], v[176:179], v[200:203], v[44:47]
	v_mfma_f32_16x16x32_bf16 v[36:39], v[184:187], v[200:203], v[36:39]
	v_mfma_f32_16x16x32_bf16 v[28:31], v[176:179], v[208:211], v[28:31]
	v_mfma_f32_16x16x32_bf16 v[20:23], v[184:187], v[208:211], v[20:23]
	v_mfma_f32_16x16x32_bf16 v[12:15], v[176:179], v[216:219], v[12:15]
	v_mfma_f32_16x16x32_bf16 v[8:11], v[184:187], v[216:219], v[6:9]
	s_barrier
	s_add_i32 s79, 0, 0x18000
	s_add_i32 s82, 0, 0x1c000
	v_add_u32_e32 v152, s79, v146
	v_add_u32_e32 v153, s82, v146
	ds_read_b128 v[154:157], v152
	ds_read_b128 v[158:161], v152 offset:1024
	ds_read_b128 v[162:165], v152 offset:2048
	ds_read_b128 v[166:169], v152 offset:3072
	ds_read_b128 v[170:173], v153
	ds_read_b128 v[176:179], v153 offset:1024
	ds_read_b128 v[180:183], v153 offset:2048
	ds_read_b128 v[184:187], v153 offset:3072
	s_add_u32 s28, s28, 0x40000
	s_addc_u32 s29, s29, 0
	s_mov_b32 m0, s52
	ds_read_b128 v[188:191], v149 offset:32768
	ds_read_b128 v[192:195], v149 offset:33792
	ds_read_b128 v[196:199], v149 offset:34816
	ds_read_b128 v[200:203], v149 offset:35840
	ds_read_b128 v[204:207], v149 offset:36864
	ds_read_b128 v[208:211], v149 offset:37888
	ds_read_b128 v[212:215], v149 offset:38912
	ds_read_b128 v[216:219], v149 offset:39936
	s_nop 0
	global_load_lds_dwordx4 v138, s[28:29]
	s_mov_b32 m0, s53
	s_nop 0
	global_load_lds_dwordx4 v134, s[28:29]
	s_waitcnt vmcnt(8)
	s_waitcnt lgkmcnt(0)
	s_barrier
	s_waitcnt lgkmcnt(0)
	v_mfma_f32_16x16x32_bf16 v[124:127], v[154:157], v[188:191], v[124:127]
	v_mfma_f32_16x16x32_bf16 v[116:119], v[162:165], v[188:191], v[116:119]
	v_mfma_f32_16x16x32_bf16 v[108:111], v[154:157], v[196:199], v[108:111]
	v_mfma_f32_16x16x32_bf16 v[100:103], v[162:165], v[196:199], v[100:103]
	v_mfma_f32_16x16x32_bf16 v[92:95], v[154:157], v[204:207], v[92:95]
	v_mfma_f32_16x16x32_bf16 v[84:87], v[162:165], v[204:207], v[84:87]
	v_mfma_f32_16x16x32_bf16 v[76:79], v[154:157], v[212:215], v[76:79]
	v_mfma_f32_16x16x32_bf16 v[60:63], v[162:165], v[212:215], v[60:63]
	v_mfma_f32_16x16x32_bf16 v[124:127], v[158:161], v[192:195], v[124:127]
	v_mfma_f32_16x16x32_bf16 v[116:119], v[166:169], v[192:195], v[116:119]
	v_mfma_f32_16x16x32_bf16 v[108:111], v[158:161], v[200:203], v[108:111]
	v_mfma_f32_16x16x32_bf16 v[100:103], v[166:169], v[200:203], v[100:103]
	v_mfma_f32_16x16x32_bf16 v[92:95], v[158:161], v[208:211], v[92:95]
	v_mfma_f32_16x16x32_bf16 v[84:87], v[166:169], v[208:211], v[84:87]
	v_mfma_f32_16x16x32_bf16 v[76:79], v[158:161], v[216:219], v[76:79]
	v_mfma_f32_16x16x32_bf16 v[60:63], v[166:169], v[216:219], v[60:63]
	v_mfma_f32_16x16x32_bf16 v[128:131], v[170:173], v[188:191], v[128:131]
	v_mfma_f32_16x16x32_bf16 v[120:123], v[180:183], v[188:191], v[120:123]
	v_mfma_f32_16x16x32_bf16 v[112:115], v[170:173], v[196:199], v[112:115]
	v_mfma_f32_16x16x32_bf16 v[104:107], v[180:183], v[196:199], v[104:107]
	v_mfma_f32_16x16x32_bf16 v[96:99], v[170:173], v[204:207], v[96:99]
	v_mfma_f32_16x16x32_bf16 v[88:91], v[180:183], v[204:207], v[88:91]
	v_mfma_f32_16x16x32_bf16 v[80:83], v[170:173], v[212:215], v[80:83]
	v_mfma_f32_16x16x32_bf16 v[72:75], v[180:183], v[212:215], v[72:75]
	v_mfma_f32_16x16x32_bf16 v[128:131], v[176:179], v[192:195], v[128:131]
	v_mfma_f32_16x16x32_bf16 v[120:123], v[184:187], v[192:195], v[120:123]
	v_mfma_f32_16x16x32_bf16 v[112:115], v[176:179], v[200:203], v[112:115]
	v_mfma_f32_16x16x32_bf16 v[104:107], v[184:187], v[200:203], v[104:107]
	v_mfma_f32_16x16x32_bf16 v[96:99], v[176:179], v[208:211], v[96:99]
	v_mfma_f32_16x16x32_bf16 v[88:91], v[184:187], v[208:211], v[88:91]
	v_mfma_f32_16x16x32_bf16 v[80:83], v[176:179], v[216:219], v[80:83]
	v_mfma_f32_16x16x32_bf16 v[72:75], v[184:187], v[216:219], v[72:75]
	s_barrier
; #define PG8_BAR __builtin_amdgcn_s_barrier()
; template <class Epi, class Sched, bool ALIGN_EPI = false, bool SP2 = false>
; __device__ __forceinline__ void gemm_phase(PG8_LAS unsigned char* lds, const Gemm g, const Sched& S, const Epi& E, int wave_s) {
;     ...
;         }
;         if constexpr (ALIGN_EPI) { if (wr == 0) PG8_BAR; }
	s_setprio 1
	s_add_u32 s30, s26, 0x80
	s_addc_u32 s31, s27, 0
	s_add_i32 s29, s79, s38
	ds_read_b128 v[188:191], v149 offset:49152
	ds_read_b128 v[192:195], v149 offset:50176
	ds_read_b128 v[196:199], v149 offset:51200
	ds_read_b128 v[200:203], v149 offset:52224
	ds_read_b128 v[204:207], v149 offset:53248
	ds_read_b128 v[208:211], v149 offset:54272
	ds_read_b128 v[212:215], v149 offset:55296
	ds_read_b128 v[216:219], v149 offset:56320
	s_mov_b32 m0, s29
	s_add_i32 s28, s29, 0x2000
	global_load_lds_dwordx4 v136, s[30:31]
	s_mov_b64 s[98:99], s[30:31]
	s_add_u32 s30, s26, 0x40080
	s_mov_b32 m0, s28
	s_addc_u32 s31, s27, 0
	s_add_i32 s26, s82, s38
	global_load_lds_dwordx4 v132, s[98:99]
	s_mov_b32 m0, s26
	s_add_i32 s27, s26, 0x2000
	global_load_lds_dwordx4 v136, s[30:31]
	s_mov_b32 m0, s27
	s_nop 0
	global_load_lds_dwordx4 v132, s[30:31]
	s_mov_b32 m0, s55
	s_nop 0
	global_load_lds_dwordx4 v138, s[24:25]
	s_mov_b32 m0, s58
	s_nop 0
	global_load_lds_dwordx4 v134, s[24:25]
	s_setprio 0
	s_waitcnt vmcnt(8)
	s_waitcnt lgkmcnt(0)
	s_barrier
	s_waitcnt lgkmcnt(0)
	v_mfma_f32_16x16x32_bf16 v[68:71], v[154:157], v[188:191], v[68:71]
	v_mfma_f32_16x16x32_bf16 v[56:59], v[162:165], v[188:191], v[56:59]
	v_mfma_f32_16x16x32_bf16 v[48:51], v[154:157], v[196:199], v[48:51]
	v_mfma_f32_16x16x32_bf16 v[40:43], v[162:165], v[196:199], v[40:43]
	v_mfma_f32_16x16x32_bf16 v[32:35], v[154:157], v[204:207], v[32:35]
	v_mfma_f32_16x16x32_bf16 v[24:27], v[162:165], v[204:207], v[24:27]
	v_mfma_f32_16x16x32_bf16 v[16:19], v[154:157], v[212:215], v[16:19]
	v_mfma_f32_16x16x32_bf16 v[2:5], v[162:165], v[212:215], v[2:5]
	v_mfma_f32_16x16x32_bf16 v[68:71], v[158:161], v[192:195], v[68:71]
	v_mfma_f32_16x16x32_bf16 v[56:59], v[166:169], v[192:195], v[56:59]
	v_mfma_f32_16x16x32_bf16 v[48:51], v[158:161], v[200:203], v[48:51]
	v_mfma_f32_16x16x32_bf16 v[40:43], v[166:169], v[200:203], v[40:43]
	v_mfma_f32_16x16x32_bf16 v[32:35], v[158:161], v[208:211], v[32:35]
	v_mfma_f32_16x16x32_bf16 v[24:27], v[166:169], v[208:211], v[24:27]
	v_mfma_f32_16x16x32_bf16 v[16:19], v[158:161], v[216:219], v[16:19]
	v_mfma_f32_16x16x32_bf16 v[4:7], v[166:169], v[216:219], v[2:5]
	v_mfma_f32_16x16x32_bf16 v[64:67], v[170:173], v[188:191], v[64:67]
	v_mfma_f32_16x16x32_bf16 v[52:55], v[180:183], v[188:191], v[52:55]
	v_mfma_f32_16x16x32_bf16 v[44:47], v[170:173], v[196:199], v[44:47]
	v_mfma_f32_16x16x32_bf16 v[36:39], v[180:183], v[196:199], v[36:39]
	v_mfma_f32_16x16x32_bf16 v[28:31], v[170:173], v[204:207], v[28:31]
	v_mfma_f32_16x16x32_bf16 v[20:23], v[180:183], v[204:207], v[20:23]
	v_mfma_f32_16x16x32_bf16 v[12:15], v[170:173], v[212:215], v[12:15]
	v_mfma_f32_16x16x32_bf16 v[8:11], v[180:183], v[212:215], v[8:11]
	v_mfma_f32_16x16x32_bf16 v[64:67], v[176:179], v[192:195], v[64:67]
	v_mfma_f32_16x16x32_bf16 v[52:55], v[184:187], v[192:195], v[52:55]
	v_mfma_f32_16x16x32_bf16 v[44:47], v[176:179], v[200:203], v[44:47]
	v_mfma_f32_16x16x32_bf16 v[36:39], v[184:187], v[200:203], v[36:39]
	v_mfma_f32_16x16x32_bf16 v[28:31], v[176:179], v[208:211], v[28:31]
	v_mfma_f32_16x16x32_bf16 v[20:23], v[184:187], v[208:211], v[20:23]
	v_mfma_f32_16x16x32_bf16 v[12:15], v[176:179], v[216:219], v[12:15]
	v_mfma_f32_16x16x32_bf16 v[8:11], v[184:187], v[216:219], v[8:11]
	s_barrier
	s_add_i32 s76, s76, 2
	s_add_u32 s77, s77, 0x100
	s_addc_u32 s78, s78, 0
	s_cmp_gt_u32 s76, 13
	s_mov_b64 s[30:31], s[22:23]
	s_cbranch_scc0 .LBB0_107
	s_and_b64 vcc, exec, s[10:11]
	s_cbranch_vccz .LBB0_110
	s_barrier

; template <class Epi, class Sched, bool ALIGN_EPI = false, bool SP2 = false>
; __device__ __forceinline__ void gemm_phase(PG8_LAS unsigned char* lds, const Gemm g, const Sched& S, const Epi& E, int wave_s) {
;     ...
;         for (int t = peeled ? 2 : 0; t < nt; t += 2) {
;             const bool last = (t == nt - 2);
;             const char* a1 = cA + (size_t)(t + 1) * kstep;
;             const char* a2 = last ? nA : cA + (size_t)(t + 2) * kstep; const char* b2 = last ? nB : cB + (size_t)(t + 2) * kstep;
;             const char* a3 = a2 + kstep; const char* b3 = b2 + kstep;
;             if (last && has_next) S.a_ready(nxt);
.LBB0_329:
	ds_read_b128 v[140:143], v147
	ds_read_b128 v[160:163], v147 offset:1024
	ds_read_b128 v[164:167], v147 offset:2048
	ds_read_b128 v[168:171], v147 offset:3072
	ds_read_b128 v[176:179], v148
	ds_read_b128 v[180:183], v148 offset:1024
	ds_read_b128 v[184:187], v148 offset:2048
	ds_read_b128 v[188:191], v148 offset:3072
	s_add_u32 s30, s28, 0x100
	s_addc_u32 s31, s29, 0
	s_cmp_eq_u32 s82, 40
	s_cselect_b32 s38, s10, s30
	s_cselect_b32 s39, s11, s31
	s_cselect_b32 s36, s26, s78
	s_cselect_b32 s37, s27, s79
	s_add_u32 s34, s38, 0x80
	s_addc_u32 s35, s39, 0
	s_add_u32 s28, s28, 0xb0080
	s_addc_u32 s29, s29, 0
	ds_read_b128 v[192:195], v149
	ds_read_b128 v[196:199], v149 offset:1024
	ds_read_b128 v[200:203], v149 offset:2048
	ds_read_b128 v[204:207], v149 offset:3072
	ds_read_b128 v[208:211], v149 offset:4096
	ds_read_b128 v[212:215], v149 offset:5120
	ds_read_b128 v[216:219], v149 offset:6144
	ds_read_b128 v[220:223], v149 offset:7168
	s_add_i32 m0, s43, 0xc000
	s_nop 0
	global_load_lds_dwordx4 v128, s[28:29]
	s_add_i32 m0, s43, 0xe000
	s_nop 0
	global_load_lds_dwordx4 v132, s[28:29]
	s_waitcnt vmcnt(8)
	s_waitcnt lgkmcnt(0)
	s_barrier
	s_waitcnt lgkmcnt(0)
	v_mfma_f32_16x16x32_bf16 v[124:127], v[140:143], v[192:195], v[124:127]
	v_mfma_f32_16x16x32_bf16 v[120:123], v[164:167], v[192:195], v[120:123]
	v_mfma_f32_16x16x32_bf16 v[108:111], v[140:143], v[200:203], v[108:111]
	v_mfma_f32_16x16x32_bf16 v[104:107], v[164:167], v[200:203], v[104:107]
	v_mfma_f32_16x16x32_bf16 v[92:95], v[140:143], v[208:211], v[92:95]
	v_mfma_f32_16x16x32_bf16 v[88:91], v[164:167], v[208:211], v[88:91]
	v_mfma_f32_16x16x32_bf16 v[76:79], v[140:143], v[216:219], v[76:79]
	v_mfma_f32_16x16x32_bf16 v[72:75], v[164:167], v[216:219], v[72:75]
	v_mfma_f32_16x16x32_bf16 v[124:127], v[160:163], v[196:199], v[124:127]
	v_mfma_f32_16x16x32_bf16 v[120:123], v[168:171], v[196:199], v[120:123]
	v_mfma_f32_16x16x32_bf16 v[108:111], v[160:163], v[204:207], v[108:111]
	v_mfma_f32_16x16x32_bf16 v[104:107], v[168:171], v[204:207], v[104:107]
	v_mfma_f32_16x16x32_bf16 v[92:95], v[160:163], v[212:215], v[92:95]
	v_mfma_f32_16x16x32_bf16 v[88:91], v[168:171], v[212:215], v[88:91]
	v_mfma_f32_16x16x32_bf16 v[76:79], v[160:163], v[220:223], v[76:79]
	v_mfma_f32_16x16x32_bf16 v[72:75], v[168:171], v[220:223], v[72:75]
	v_mfma_f32_16x16x32_bf16 v[116:119], v[176:179], v[192:195], v[116:119]
	v_mfma_f32_16x16x32_bf16 v[112:115], v[184:187], v[192:195], v[112:115]
	v_mfma_f32_16x16x32_bf16 v[100:103], v[176:179], v[200:203], v[100:103]
	v_mfma_f32_16x16x32_bf16 v[96:99], v[184:187], v[200:203], v[96:99]
	v_mfma_f32_16x16x32_bf16 v[84:87], v[176:179], v[208:211], v[84:87]
	v_mfma_f32_16x16x32_bf16 v[80:83], v[184:187], v[208:211], v[80:83]
	v_mfma_f32_16x16x32_bf16 v[68:71], v[176:179], v[216:219], v[68:71]
	v_mfma_f32_16x16x32_bf16 v[64:67], v[184:187], v[216:219], v[64:67]
	v_mfma_f32_16x16x32_bf16 v[116:119], v[180:183], v[196:199], v[116:119]
	v_mfma_f32_16x16x32_bf16 v[112:115], v[188:191], v[196:199], v[112:115]
	v_mfma_f32_16x16x32_bf16 v[100:103], v[180:183], v[204:207], v[100:103]
	v_mfma_f32_16x16x32_bf16 v[96:99], v[188:191], v[204:207], v[96:99]
	v_mfma_f32_16x16x32_bf16 v[84:87], v[180:183], v[212:215], v[84:87]
	v_mfma_f32_16x16x32_bf16 v[80:83], v[188:191], v[212:215], v[80:83]
	v_mfma_f32_16x16x32_bf16 v[68:71], v[180:183], v[220:223], v[68:71]
	v_mfma_f32_16x16x32_bf16 v[64:67], v[188:191], v[220:223], v[64:67]
	s_barrier
	s_setprio 1
	s_mov_b64 s[28:29], s[36:37]
	s_add_i32 s87, s72, s42
	ds_read_b128 v[192:195], v149 offset:16384
	ds_read_b128 v[196:199], v149 offset:17408
	ds_read_b128 v[200:203], v149 offset:18432
	ds_read_b128 v[204:207], v149 offset:19456
	ds_read_b128 v[208:211], v149 offset:20480
	ds_read_b128 v[212:215], v149 offset:21504
	ds_read_b128 v[216:219], v149 offset:22528
	ds_read_b128 v[220:223], v149 offset:23552
	s_mov_b32 m0, s87
	s_nop 0
	global_load_lds_dwordx4 v130, s[28:29]
	s_add_i32 m0, s87, 0x2000
	s_nop 0
	global_load_lds_dwordx4 v134, s[28:29]
	s_add_u32 s28, s36, 0xb0000
	s_addc_u32 s29, s37, 0
	s_add_i32 s87, s73, s42
	s_mov_b32 m0, s87
	s_nop 0
	global_load_lds_dwordx4 v130, s[28:29]
	s_mov_b64 s[98:99], s[28:29]
	s_add_i32 m0, s87, 0x2000
	s_mov_b64 s[28:29], s[38:39]
	global_load_lds_dwordx4 v134, s[98:99]
	s_mov_b32 m0, s43
	s_nop 0
	global_load_lds_dwordx4 v128, s[28:29]
	s_mov_b32 m0, s52
	s_nop 0
	global_load_lds_dwordx4 v132, s[28:29]
	s_setprio 0
	s_waitcnt vmcnt(8)
	s_waitcnt lgkmcnt(0)
	s_barrier
	s_waitcnt lgkmcnt(0)
	v_mfma_f32_16x16x32_bf16 v[60:63], v[140:143], v[192:195], v[60:63]
	v_mfma_f32_16x16x32_bf16 v[56:59], v[164:167], v[192:195], v[56:59]
	v_mfma_f32_16x16x32_bf16 v[44:47], v[140:143], v[200:203], v[44:47]
	v_mfma_f32_16x16x32_bf16 v[40:43], v[164:167], v[200:203], v[40:43]
	v_mfma_f32_16x16x32_bf16 v[28:31], v[140:143], v[208:211], v[28:31]
	v_mfma_f32_16x16x32_bf16 v[24:27], v[164:167], v[208:211], v[24:27]
	v_mfma_f32_16x16x32_bf16 v[12:15], v[140:143], v[216:219], v[12:15]
	v_mfma_f32_16x16x32_bf16 v[8:11], v[164:167], v[216:219], v[8:11]
	v_mfma_f32_16x16x32_bf16 v[60:63], v[160:163], v[196:199], v[60:63]
	v_mfma_f32_16x16x32_bf16 v[56:59], v[168:171], v[196:199], v[56:59]
	v_mfma_f32_16x16x32_bf16 v[44:47], v[160:163], v[204:207], v[44:47]
	v_mfma_f32_16x16x32_bf16 v[40:43], v[168:171], v[204:207], v[40:43]
	v_mfma_f32_16x16x32_bf16 v[28:31], v[160:163], v[212:215], v[28:31]
	v_mfma_f32_16x16x32_bf16 v[24:27], v[168:171], v[212:215], v[24:27]
	v_mfma_f32_16x16x32_bf16 v[12:15], v[160:163], v[220:223], v[12:15]
	v_mfma_f32_16x16x32_bf16 v[8:11], v[168:171], v[220:223], v[8:11]
	v_mfma_f32_16x16x32_bf16 v[52:55], v[176:179], v[192:195], v[52:55]
	v_mfma_f32_16x16x32_bf16 v[48:51], v[184:187], v[192:195], v[48:51]
	v_mfma_f32_16x16x32_bf16 v[36:39], v[176:179], v[200:203], v[36:39]
	v_mfma_f32_16x16x32_bf16 v[32:35], v[184:187], v[200:203], v[32:35]
	v_mfma_f32_16x16x32_bf16 v[20:23], v[176:179], v[208:211], v[20:23]
	v_mfma_f32_16x16x32_bf16 v[16:19], v[184:187], v[208:211], v[16:19]
	v_mfma_f32_16x16x32_bf16 v[4:7], v[176:179], v[216:219], v[4:7]
	v_mfma_f32_16x16x32_bf16 v[0:3], v[184:187], v[216:219], v[0:3]
	v_mfma_f32_16x16x32_bf16 v[52:55], v[180:183], v[196:199], v[52:55]
	v_mfma_f32_16x16x32_bf16 v[48:51], v[188:191], v[196:199], v[48:51]
	v_mfma_f32_16x16x32_bf16 v[36:39], v[180:183], v[204:207], v[36:39]
	v_mfma_f32_16x16x32_bf16 v[32:35], v[188:191], v[204:207], v[32:35]
	v_mfma_f32_16x16x32_bf16 v[20:23], v[180:183], v[212:215], v[20:23]
	v_mfma_f32_16x16x32_bf16 v[16:19], v[188:191], v[212:215], v[16:19]
	v_mfma_f32_16x16x32_bf16 v[4:7], v[180:183], v[220:223], v[4:7]
	v_mfma_f32_16x16x32_bf16 v[0:3], v[188:191], v[220:223], v[0:3]
	s_barrier
; #define PG8_BAR __builtin_amdgcn_s_barrier()
; template <class Epi, class Sched, bool ALIGN_EPI = false, bool SP2 = false>
; __device__ __forceinline__ void gemm_phase(PG8_LAS unsigned char* lds, const Gemm g, const Sched& S, const Epi& E, int wave_s) {
;     ...
;         }
;         if constexpr (ALIGN_EPI) { if (wr == 0) PG8_BAR; }
	s_add_i32 s87, 0, 0x18000
	v_add_u32_e32 v159, s87, v145
	s_add_i32 s88, 0, 0x1c000
	ds_read_b128 v[140:143], v159
	ds_read_b128 v[160:163], v159 offset:1024
	ds_read_b128 v[164:167], v159 offset:2048
	ds_read_b128 v[168:171], v159 offset:3072
	v_add_u32_e32 v159, s88, v145
	ds_read_b128 v[176:179], v159
	ds_read_b128 v[180:183], v159 offset:1024
	ds_read_b128 v[184:187], v159 offset:2048
	ds_read_b128 v[188:191], v159 offset:3072
	s_add_u32 s28, s38, 0xb0000
	s_addc_u32 s29, s39, 0
	s_mov_b32 m0, s53
	ds_read_b128 v[192:195], v149 offset:32768
	ds_read_b128 v[196:199], v149 offset:33792
	ds_read_b128 v[200:203], v149 offset:34816
	ds_read_b128 v[204:207], v149 offset:35840
	ds_read_b128 v[208:211], v149 offset:36864
	ds_read_b128 v[212:215], v149 offset:37888
	ds_read_b128 v[216:219], v149 offset:38912
	ds_read_b128 v[220:223], v149 offset:39936
	s_nop 0
	global_load_lds_dwordx4 v128, s[28:29]
	s_mov_b32 m0, s58
	s_nop 0
	global_load_lds_dwordx4 v132, s[28:29]
	s_waitcnt vmcnt(8)
	s_waitcnt lgkmcnt(0)
	s_barrier
	s_waitcnt lgkmcnt(0)
	v_mfma_f32_16x16x32_bf16 v[124:127], v[140:143], v[192:195], v[124:127]
	v_mfma_f32_16x16x32_bf16 v[120:123], v[164:167], v[192:195], v[120:123]
	v_mfma_f32_16x16x32_bf16 v[108:111], v[140:143], v[200:203], v[108:111]
	v_mfma_f32_16x16x32_bf16 v[104:107], v[164:167], v[200:203], v[104:107]
	v_mfma_f32_16x16x32_bf16 v[92:95], v[140:143], v[208:211], v[92:95]
	v_mfma_f32_16x16x32_bf16 v[88:91], v[164:167], v[208:211], v[88:91]
	v_mfma_f32_16x16x32_bf16 v[76:79], v[140:143], v[216:219], v[76:79]
	v_mfma_f32_16x16x32_bf16 v[72:75], v[164:167], v[216:219], v[72:75]
	v_mfma_f32_16x16x32_bf16 v[124:127], v[160:163], v[196:199], v[124:127]
	v_mfma_f32_16x16x32_bf16 v[120:123], v[168:171], v[196:199], v[120:123]
	v_mfma_f32_16x16x32_bf16 v[108:111], v[160:163], v[204:207], v[108:111]
	v_mfma_f32_16x16x32_bf16 v[104:107], v[168:171], v[204:207], v[104:107]
	v_mfma_f32_16x16x32_bf16 v[92:95], v[160:163], v[212:215], v[92:95]
	v_mfma_f32_16x16x32_bf16 v[88:91], v[168:171], v[212:215], v[88:91]
	v_mfma_f32_16x16x32_bf16 v[76:79], v[160:163], v[220:223], v[76:79]
	v_mfma_f32_16x16x32_bf16 v[72:75], v[168:171], v[220:223], v[72:75]
	v_mfma_f32_16x16x32_bf16 v[116:119], v[176:179], v[192:195], v[116:119]
	v_mfma_f32_16x16x32_bf16 v[112:115], v[184:187], v[192:195], v[112:115]
	v_mfma_f32_16x16x32_bf16 v[100:103], v[176:179], v[200:203], v[100:103]
	v_mfma_f32_16x16x32_bf16 v[96:99], v[184:187], v[200:203], v[96:99]
	v_mfma_f32_16x16x32_bf16 v[84:87], v[176:179], v[208:211], v[84:87]
	v_mfma_f32_16x16x32_bf16 v[80:83], v[184:187], v[208:211], v[80:83]
	v_mfma_f32_16x16x32_bf16 v[68:71], v[176:179], v[216:219], v[68:71]
	v_mfma_f32_16x16x32_bf16 v[64:67], v[184:187], v[216:219], v[64:67]
	v_mfma_f32_16x16x32_bf16 v[116:119], v[180:183], v[196:199], v[116:119]
	v_mfma_f32_16x16x32_bf16 v[112:115], v[188:191], v[196:199], v[112:115]
	v_mfma_f32_16x16x32_bf16 v[100:103], v[180:183], v[204:207], v[100:103]
	v_mfma_f32_16x16x32_bf16 v[96:99], v[188:191], v[204:207], v[96:99]
	v_mfma_f32_16x16x32_bf16 v[84:87], v[180:183], v[212:215], v[84:87]
	v_mfma_f32_16x16x32_bf16 v[80:83], v[188:191], v[212:215], v[80:83]
	v_mfma_f32_16x16x32_bf16 v[68:71], v[180:183], v[220:223], v[68:71]
	v_mfma_f32_16x16x32_bf16 v[64:67], v[188:191], v[220:223], v[64:67]
	s_barrier
	s_setprio 1
	s_add_u32 s28, s36, 0x80
	s_addc_u32 s29, s37, 0
	s_add_i32 s38, s87, s42
	ds_read_b128 v[192:195], v149 offset:49152
	ds_read_b128 v[196:199], v149 offset:50176
	ds_read_b128 v[200:203], v149 offset:51200
	ds_read_b128 v[204:207], v149 offset:52224
	ds_read_b128 v[208:211], v149 offset:53248
	ds_read_b128 v[212:215], v149 offset:54272
	ds_read_b128 v[216:219], v149 offset:55296
	ds_read_b128 v[220:223], v149 offset:56320
	s_mov_b32 m0, s38
	s_nop 0
	global_load_lds_dwordx4 v130, s[28:29]
	s_add_i32 m0, s38, 0x2000
	s_nop 0
	global_load_lds_dwordx4 v134, s[28:29]
	s_add_u32 s28, s36, 0xb0080
	s_addc_u32 s29, s37, 0
	s_add_i32 s36, s88, s42
	s_mov_b32 m0, s36
	s_nop 0
	global_load_lds_dwordx4 v130, s[28:29]
	s_add_i32 m0, s36, 0x2000
	s_nop 0
	global_load_lds_dwordx4 v134, s[28:29]
	s_mov_b32 m0, s60
	s_nop 0
	global_load_lds_dwordx4 v128, s[34:35]
	s_mov_b32 m0, s61
	s_nop 0
	global_load_lds_dwordx4 v132, s[34:35]
	s_setprio 0
	s_waitcnt vmcnt(8)
	s_waitcnt lgkmcnt(0)
	s_barrier
	s_waitcnt lgkmcnt(0)
	v_mfma_f32_16x16x32_bf16 v[60:63], v[140:143], v[192:195], v[60:63]
	v_mfma_f32_16x16x32_bf16 v[56:59], v[164:167], v[192:195], v[56:59]
	v_mfma_f32_16x16x32_bf16 v[44:47], v[140:143], v[200:203], v[44:47]
	v_mfma_f32_16x16x32_bf16 v[40:43], v[164:167], v[200:203], v[40:43]
	v_mfma_f32_16x16x32_bf16 v[28:31], v[140:143], v[208:211], v[28:31]
	v_mfma_f32_16x16x32_bf16 v[24:27], v[164:167], v[208:211], v[24:27]
	v_mfma_f32_16x16x32_bf16 v[12:15], v[140:143], v[216:219], v[12:15]
	v_mfma_f32_16x16x32_bf16 v[8:11], v[164:167], v[216:219], v[8:11]
	v_mfma_f32_16x16x32_bf16 v[60:63], v[160:163], v[196:199], v[60:63]
	v_mfma_f32_16x16x32_bf16 v[56:59], v[168:171], v[196:199], v[56:59]
	v_mfma_f32_16x16x32_bf16 v[44:47], v[160:163], v[204:207], v[44:47]
	v_mfma_f32_16x16x32_bf16 v[40:43], v[168:171], v[204:207], v[40:43]
	v_mfma_f32_16x16x32_bf16 v[28:31], v[160:163], v[212:215], v[28:31]
	v_mfma_f32_16x16x32_bf16 v[24:27], v[168:171], v[212:215], v[24:27]
	v_mfma_f32_16x16x32_bf16 v[12:15], v[160:163], v[220:223], v[12:15]
	v_mfma_f32_16x16x32_bf16 v[8:11], v[168:171], v[220:223], v[8:11]
	v_mfma_f32_16x16x32_bf16 v[52:55], v[176:179], v[192:195], v[52:55]
	v_mfma_f32_16x16x32_bf16 v[48:51], v[184:187], v[192:195], v[48:51]
	v_mfma_f32_16x16x32_bf16 v[36:39], v[176:179], v[200:203], v[36:39]
	v_mfma_f32_16x16x32_bf16 v[32:35], v[184:187], v[200:203], v[32:35]
	v_mfma_f32_16x16x32_bf16 v[20:23], v[176:179], v[208:211], v[20:23]
	v_mfma_f32_16x16x32_bf16 v[16:19], v[184:187], v[208:211], v[16:19]
	v_mfma_f32_16x16x32_bf16 v[4:7], v[176:179], v[216:219], v[4:7]
	v_mfma_f32_16x16x32_bf16 v[0:3], v[184:187], v[216:219], v[0:3]
	v_mfma_f32_16x16x32_bf16 v[52:55], v[180:183], v[196:199], v[52:55]
	v_mfma_f32_16x16x32_bf16 v[48:51], v[188:191], v[196:199], v[48:51]
	v_mfma_f32_16x16x32_bf16 v[36:39], v[180:183], v[204:207], v[36:39]
	v_mfma_f32_16x16x32_bf16 v[32:35], v[188:191], v[204:207], v[32:35]
	v_mfma_f32_16x16x32_bf16 v[20:23], v[180:183], v[212:215], v[20:23]
	v_mfma_f32_16x16x32_bf16 v[16:19], v[188:191], v[212:215], v[16:19]
	v_mfma_f32_16x16x32_bf16 v[4:7], v[180:183], v[220:223], v[4:7]
	v_mfma_f32_16x16x32_bf16 v[0:3], v[188:191], v[220:223], v[0:3]
	s_barrier
	s_add_i32 s82, s82, 2
	s_add_u32 s78, s78, 0x100
	s_addc_u32 s79, s79, 0
	s_cmp_gt_u32 s82, 41
	s_mov_b64 s[28:29], s[30:31]
	s_cbranch_scc0 .LBB0_329
	s_and_b64 vcc, exec, s[14:15]
	s_cbranch_vccz .LBB0_332
	s_barrier

; __device__ __forceinline__ int lane_id_() { int l; asm volatile("v_mbcnt_lo_u32_b32 %0, -1, 0\n\tv_mbcnt_hi_u32_b32 %0, -1, %0" : "=v"(l)); return l; }
; #define PG8_LAS __attribute__((address_space(3)))
;     __device__ __forceinline__ void prefetch(PG8_LAS unsigned char* lds, int wid, const Unit& u, int wr, int fr, int fq) const {
;         { const int l_ = lane_id_(); fr = l_ & 15; fq = l_ >> 4; }
; #pragma unroll
;         for (int j = 0; j < 2; ++j) { const int i = 2 * fq + j;
;             __builtin_amdgcn_global_load_lds((const unsigned*)(ssq + u.pm * BM + wr * 64 + fr + (i >> 2) * HALF + (i & 3) * 16), (PG8_LAS unsigned*)(lds + PRE_SLOT + wid * 512 + j * 256), 4, 0, 0); }
;     }
.LBB0_414:
	s_lshl_b32 s6, s26, 8
	s_ashr_i32 s7, s6, 31
	s_lshl_b64 s[6:7], s[6:7], 2
	v_mbcnt_lo_u32_b32 v6, -1, 0
	v_mbcnt_hi_u32_b32 v6, -1, v6
	s_add_u32 s6, s75, s6
	v_and_b32_e32 v0, 15, v6
	v_lshlrev_b32_e32 v2, 2, v6
	v_and_b32_e32 v2, 0xffffff80, v2
	s_addc_u32 s7, s76, s7
	v_lshlrev_b32_e32 v0, 2, v0
	v_ashrrev_i32_e32 v3, 31, v2
	v_lshl_add_u64 v[4:5], s[6:7], 0, v[0:1]
	v_lshlrev_b32_e32 v0, 3, v6
	v_lshl_add_u64 v[2:3], v[2:3], 2, v[4:5]
	v_and_b32_e32 v0, 0x80, v0
	s_mov_b32 m0, s59
	v_lshl_add_u64 v[2:3], v[2:3], 0, v[0:1]
	global_load_lds_dword v[2:3], off
	v_lshl_add_u64 v[2:3], v[2:3], 0, 64
	s_add_i32 m0, s59, 0x100
	s_add_u32 s8, s28, 0x100
	global_load_lds_dword v[2:3], off
	ds_read_b128 v[2:5], v151
	ds_read_b128 v[6:9], v151 offset:1024
	ds_read_b128 v[10:13], v151 offset:2048
	ds_read_b128 v[14:17], v151 offset:3072
	ds_read_b128 v[18:21], v150
	ds_read_b128 v[22:25], v150 offset:1024
	ds_read_b128 v[26:29], v150 offset:2048
	ds_read_b128 v[30:33], v150 offset:3072
	s_addc_u32 s9, s29, 0
	s_add_u32 s6, s28, 0x180
	s_addc_u32 s7, s29, 0
	s_add_u32 s38, s30, 0x100
	s_addc_u32 s39, s31, 0
	s_add_u32 s40, s28, 0x40080
	s_addc_u32 s41, s29, 0
	s_mov_b32 m0, s91
	ds_read_b128 v[34:37], v149
	ds_read_b128 v[38:41], v149 offset:1024
	ds_read_b128 v[42:45], v149 offset:2048
	ds_read_b128 v[46:49], v149 offset:3072
	ds_read_b128 v[50:53], v149 offset:4096
	ds_read_b128 v[54:57], v149 offset:5120
	ds_read_b128 v[58:61], v149 offset:6144
	ds_read_b128 v[62:65], v149 offset:7168
	s_nop 0
	global_load_lds_dwordx4 v132, s[40:41]
	s_mov_b32 m0, s10
	s_nop 0
	global_load_lds_dwordx4 v136, s[40:41]
	s_waitcnt vmcnt(26)
	s_waitcnt lgkmcnt(0)
	s_barrier
	s_waitcnt lgkmcnt(0)
	v_mfma_f32_16x16x32_bf16 v[90:93], v[2:5], v[58:61], 0
	v_mfma_f32_16x16x32_bf16 v[66:69], v[2:5], v[34:37], 0
	v_mfma_f32_16x16x32_bf16 v[70:73], v[10:13], v[34:37], 0
	v_mfma_f32_16x16x32_bf16 v[74:77], v[2:5], v[42:45], 0
	v_mfma_f32_16x16x32_bf16 v[78:81], v[10:13], v[42:45], 0
	v_mfma_f32_16x16x32_bf16 v[82:85], v[2:5], v[50:53], 0
	v_mfma_f32_16x16x32_bf16 v[86:89], v[10:13], v[50:53], 0
	v_mfma_f32_16x16x32_bf16 v[100:103], v[6:9], v[62:65], v[90:93]
	v_mfma_f32_16x16x32_bf16 v[90:93], v[10:13], v[58:61], 0
	v_mfma_f32_16x16x32_bf16 v[66:69], v[6:9], v[38:41], v[66:69]
	v_mfma_f32_16x16x32_bf16 v[70:73], v[14:17], v[38:41], v[70:73]
	v_mfma_f32_16x16x32_bf16 v[74:77], v[6:9], v[46:49], v[74:77]
	v_mfma_f32_16x16x32_bf16 v[78:81], v[14:17], v[46:49], v[78:81]
	v_mfma_f32_16x16x32_bf16 v[82:85], v[6:9], v[54:57], v[82:85]
	v_mfma_f32_16x16x32_bf16 v[86:89], v[14:17], v[54:57], v[86:89]
	v_mfma_f32_16x16x32_bf16 v[104:107], v[14:17], v[62:65], v[90:93]
	v_mfma_f32_16x16x32_bf16 v[90:93], v[18:21], v[34:37], 0
	v_mfma_f32_16x16x32_bf16 v[34:37], v[26:29], v[34:37], 0
	v_mfma_f32_16x16x32_bf16 v[116:119], v[22:25], v[38:41], v[90:93]
	v_mfma_f32_16x16x32_bf16 v[34:37], v[30:33], v[38:41], v[34:37]
	v_mfma_f32_16x16x32_bf16 v[38:41], v[18:21], v[42:45], 0
	v_mfma_f32_16x16x32_bf16 v[42:45], v[26:29], v[42:45], 0
	v_mfma_f32_16x16x32_bf16 v[38:41], v[22:25], v[46:49], v[38:41]
	v_mfma_f32_16x16x32_bf16 v[42:45], v[30:33], v[46:49], v[42:45]
	v_mfma_f32_16x16x32_bf16 v[46:49], v[18:21], v[50:53], 0
	v_mfma_f32_16x16x32_bf16 v[50:53], v[26:29], v[50:53], 0
	v_mfma_f32_16x16x32_bf16 v[46:49], v[22:25], v[54:57], v[46:49]
	v_mfma_f32_16x16x32_bf16 v[50:53], v[30:33], v[54:57], v[50:53]
	v_mfma_f32_16x16x32_bf16 v[54:57], v[18:21], v[58:61], 0
	v_mfma_f32_16x16x32_bf16 v[58:61], v[26:29], v[58:61], 0
	v_mfma_f32_16x16x32_bf16 v[54:57], v[22:25], v[62:65], v[54:57]
	v_mfma_f32_16x16x32_bf16 v[58:61], v[30:33], v[62:65], v[58:61]
	s_barrier
	s_setprio 1
	s_mov_b32 m0, s90
	ds_read_b128 v[62:65], v149 offset:16384
	ds_read_b128 v[90:93], v149 offset:17408
	ds_read_b128 v[94:97], v149 offset:18432
	ds_read_b128 v[108:111], v149 offset:19456
	ds_read_b128 v[112:115], v149 offset:20480
	ds_read_b128 v[120:123], v149 offset:21504
	ds_read_b128 v[124:127], v149 offset:22528
	ds_read_b128 v[128:131], v149 offset:23552
	s_nop 0
	global_load_lds_dwordx4 v134, s[38:39]
	s_mov_b64 s[98:99], s[38:39]
	s_add_u32 s38, s30, 0x40100
	s_mov_b32 m0, s25
	s_addc_u32 s39, s31, 0
	global_load_lds_dwordx4 v138, s[98:99]
	s_mov_b32 m0, s27
	s_nop 0
	global_load_lds_dwordx4 v134, s[38:39]
	s_mov_b32 m0, s88
	s_nop 0
	global_load_lds_dwordx4 v138, s[38:39]
	s_mov_b32 m0, s35
	s_nop 0
	global_load_lds_dwordx4 v132, s[8:9]
	s_mov_b32 m0, s37
	s_nop 0
	global_load_lds_dwordx4 v136, s[8:9]
	s_setprio 0
	s_waitcnt vmcnt(26)
	s_waitcnt lgkmcnt(0)
	s_barrier
	s_waitcnt lgkmcnt(0)
	v_mfma_f32_16x16x32_bf16 v[154:157], v[2:5], v[62:65], 0
	v_mfma_f32_16x16x32_bf16 v[162:165], v[2:5], v[94:97], 0
	v_mfma_f32_16x16x32_bf16 v[170:173], v[2:5], v[112:115], 0
	v_mfma_f32_16x16x32_bf16 v[2:5], v[2:5], v[124:127], 0
	v_mfma_f32_16x16x32_bf16 v[154:157], v[6:9], v[90:93], v[154:157]
	v_mfma_f32_16x16x32_bf16 v[162:165], v[6:9], v[108:111], v[162:165]
	v_mfma_f32_16x16x32_bf16 v[170:173], v[6:9], v[120:123], v[170:173]
	v_mfma_f32_16x16x32_bf16 v[2:5], v[6:9], v[128:131], v[2:5]
	v_mfma_f32_16x16x32_bf16 v[6:9], v[10:13], v[124:127], 0
	v_mfma_f32_16x16x32_bf16 v[158:161], v[10:13], v[62:65], 0
	v_mfma_f32_16x16x32_bf16 v[166:169], v[10:13], v[94:97], 0
	v_mfma_f32_16x16x32_bf16 v[176:179], v[10:13], v[112:115], 0
	v_mfma_f32_16x16x32_bf16 v[6:9], v[14:17], v[128:131], v[6:9]
	v_mfma_f32_16x16x32_bf16 v[158:161], v[14:17], v[90:93], v[158:161]
	v_mfma_f32_16x16x32_bf16 v[166:169], v[14:17], v[108:111], v[166:169]
	v_mfma_f32_16x16x32_bf16 v[176:179], v[14:17], v[120:123], v[176:179]
	v_mfma_f32_16x16x32_bf16 v[10:13], v[18:21], v[62:65], 0
	v_mfma_f32_16x16x32_bf16 v[180:183], v[22:25], v[90:93], v[10:13]
	v_mfma_f32_16x16x32_bf16 v[10:13], v[26:29], v[62:65], 0
	v_mfma_f32_16x16x32_bf16 v[184:187], v[30:33], v[90:93], v[10:13]
	v_mfma_f32_16x16x32_bf16 v[10:13], v[18:21], v[94:97], 0
	v_mfma_f32_16x16x32_bf16 v[188:191], v[22:25], v[108:111], v[10:13]
	v_mfma_f32_16x16x32_bf16 v[10:13], v[26:29], v[94:97], 0
	v_mfma_f32_16x16x32_bf16 v[192:195], v[30:33], v[108:111], v[10:13]
	v_mfma_f32_16x16x32_bf16 v[10:13], v[18:21], v[112:115], 0
	v_mfma_f32_16x16x32_bf16 v[196:199], v[22:25], v[120:123], v[10:13]
	v_mfma_f32_16x16x32_bf16 v[10:13], v[26:29], v[112:115], 0
	v_mfma_f32_16x16x32_bf16 v[200:203], v[30:33], v[120:123], v[10:13]
	v_mfma_f32_16x16x32_bf16 v[10:13], v[18:21], v[124:127], 0
	v_mfma_f32_16x16x32_bf16 v[204:207], v[22:25], v[128:131], v[10:13]
	v_mfma_f32_16x16x32_bf16 v[10:13], v[26:29], v[124:127], 0
	v_mfma_f32_16x16x32_bf16 v[208:211], v[30:33], v[128:131], v[10:13]
	s_barrier
; #define PG8_WAIT_V8_RELAX() do { if constexpr (Epi::NSTORES + Epi::NPRE == 10) asm volatile("s_waitcnt vmcnt(18)" ::: "memory"); else if constexpr (Epi::NSTORES + Epi::NPRE == 18) asm volatile("s_waitcnt vmcnt(26)" ::: "memory"); else asm volatile("s_waitcnt vmcnt(8)" ::: "memory"); } while (0)
; template <class Epi, class Sched, bool ALIGN_EPI = false, bool SP2 = false>
; __device__ __forceinline__ void gemm_phase(PG8_LAS unsigned char* lds, const Gemm g, const Sched& S, const Epi& E, int wave_s) {
;     ...
;         if constexpr (SP2 && Epi::NSTORES > 0 && !Epi::AFTER_DRAIN) {
;             const char* a1 = cA + kstep; const char* a2 = cA + 2 * kstep; const char* b2 = cB + 2 * kstep; const char* a3 = a2 + kstep; const char* b3 = b2 + kstep;
;             PG8_SP2_PAIR(PG8_WAIT_V8_RELAX);
;             peeled = true;
	s_nop 4
	ds_read_b128 v[10:13], v152
	ds_read_b128 v[14:17], v152 offset:1024
	ds_read_b128 v[20:23], v152 offset:2048
	ds_read_b128 v[24:27], v152 offset:3072
	ds_read_b128 v[212:215], v153
	ds_read_b128 v[216:219], v153 offset:1024
	ds_read_b128 v[220:223], v153 offset:2048
	ds_read_b128 v[150:153], v153 offset:3072
	s_add_u32 s8, s28, 0x40100
	s_addc_u32 s9, s29, 0
	s_mov_b32 m0, s60
	ds_read_b128 v[28:31], v149 offset:32768
	ds_read_b128 v[62:65], v149 offset:33792
	ds_read_b128 v[224:227], v149 offset:34816
	ds_read_b128 v[228:231], v149 offset:35840
	ds_read_b128 v[232:235], v149 offset:36864
	ds_read_b128 v[236:239], v149 offset:37888
	ds_read_b128 v[240:243], v149 offset:38912
	ds_read_b128 v[244:247], v149 offset:39936
	s_nop 0
	global_load_lds_dwordx4 v132, s[8:9]
	s_mov_b32 m0, s61
	s_nop 0
	global_load_lds_dwordx4 v136, s[8:9]
	s_waitcnt vmcnt(26)
	s_waitcnt lgkmcnt(0)
	s_barrier
	s_waitcnt lgkmcnt(0)
	v_mfma_f32_16x16x32_bf16 v[66:69], v[10:13], v[28:31], v[66:69]
	v_mfma_f32_16x16x32_bf16 v[128:131], v[14:17], v[62:65], v[66:69]
	v_mfma_f32_16x16x32_bf16 v[66:69], v[20:23], v[28:31], v[70:73]
	v_mfma_f32_16x16x32_bf16 v[124:127], v[24:27], v[62:65], v[66:69]
	v_mfma_f32_16x16x32_bf16 v[66:69], v[10:13], v[224:227], v[74:77]
	v_mfma_f32_16x16x32_bf16 v[112:115], v[14:17], v[228:231], v[66:69]
	v_mfma_f32_16x16x32_bf16 v[66:69], v[20:23], v[224:227], v[78:81]
	v_mfma_f32_16x16x32_bf16 v[108:111], v[24:27], v[228:231], v[66:69]
	v_mfma_f32_16x16x32_bf16 v[66:69], v[10:13], v[232:235], v[82:85]
	v_mfma_f32_16x16x32_bf16 v[96:99], v[14:17], v[236:239], v[66:69]
	v_mfma_f32_16x16x32_bf16 v[66:69], v[20:23], v[232:235], v[86:89]
	v_mfma_f32_16x16x32_bf16 v[92:95], v[24:27], v[236:239], v[66:69]
	v_mfma_f32_16x16x32_bf16 v[66:69], v[10:13], v[240:243], v[100:103]
	v_mfma_f32_16x16x32_bf16 v[80:83], v[14:17], v[244:247], v[66:69]
	v_mfma_f32_16x16x32_bf16 v[66:69], v[20:23], v[240:243], v[104:107]
	v_mfma_f32_16x16x32_bf16 v[76:79], v[24:27], v[244:247], v[66:69]
	v_mfma_f32_16x16x32_bf16 v[66:69], v[212:215], v[28:31], v[116:119]
	v_mfma_f32_16x16x32_bf16 v[28:31], v[220:223], v[28:31], v[34:37]
	v_mfma_f32_16x16x32_bf16 v[116:119], v[150:153], v[62:65], v[28:31]
	v_mfma_f32_16x16x32_bf16 v[28:31], v[212:215], v[224:227], v[38:41]
	v_mfma_f32_16x16x32_bf16 v[104:107], v[216:219], v[228:231], v[28:31]
	v_mfma_f32_16x16x32_bf16 v[28:31], v[220:223], v[224:227], v[42:45]
	v_mfma_f32_16x16x32_bf16 v[100:103], v[150:153], v[228:231], v[28:31]
	v_mfma_f32_16x16x32_bf16 v[28:31], v[212:215], v[232:235], v[46:49]
	v_mfma_f32_16x16x32_bf16 v[88:91], v[216:219], v[236:239], v[28:31]
	v_mfma_f32_16x16x32_bf16 v[28:31], v[220:223], v[232:235], v[50:53]
	v_mfma_f32_16x16x32_bf16 v[84:87], v[150:153], v[236:239], v[28:31]
	v_mfma_f32_16x16x32_bf16 v[28:31], v[212:215], v[240:243], v[54:57]
	v_mfma_f32_16x16x32_bf16 v[72:75], v[216:219], v[244:247], v[28:31]
	v_mfma_f32_16x16x32_bf16 v[28:31], v[220:223], v[240:243], v[58:61]
	v_mfma_f32_16x16x32_bf16 v[120:123], v[216:219], v[62:65], v[66:69]
	v_mfma_f32_16x16x32_bf16 v[68:71], v[150:153], v[244:247], v[28:31]
	s_barrier
	s_setprio 1
	s_add_u32 s8, s30, 0x180
	s_addc_u32 s9, s31, 0
	s_mov_b32 m0, s92
	ds_read_b128 v[36:39], v149 offset:49152
	ds_read_b128 v[40:43], v149 offset:50176
	ds_read_b128 v[224:227], v149 offset:51200
	ds_read_b128 v[228:231], v149 offset:52224
	ds_read_b128 v[232:235], v149 offset:53248
	ds_read_b128 v[236:239], v149 offset:54272
	ds_read_b128 v[240:243], v149 offset:55296
	ds_read_b128 v[244:247], v149 offset:56320
	s_nop 0
	global_load_lds_dwordx4 v134, s[8:9]
	s_mov_b64 s[98:99], s[8:9]
	s_add_u32 s8, s30, 0x40180
	s_mov_b32 m0, s42
	s_addc_u32 s9, s31, 0
	global_load_lds_dwordx4 v138, s[98:99]
	s_mov_b32 m0, s43
	s_nop 0
	global_load_lds_dwordx4 v134, s[8:9]
	s_mov_b32 m0, s89
	s_nop 0
	global_load_lds_dwordx4 v138, s[8:9]
	s_mov_b32 m0, s63
	s_nop 0
	global_load_lds_dwordx4 v132, s[6:7]
	s_mov_b32 m0, s72
	s_nop 0
	global_load_lds_dwordx4 v136, s[6:7]
	s_setprio 0
	s_waitcnt vmcnt(26)
	s_waitcnt lgkmcnt(0)
	s_barrier
	s_waitcnt lgkmcnt(0)
	v_mfma_f32_16x16x32_bf16 v[28:31], v[10:13], v[36:39], v[154:157]
	v_mfma_f32_16x16x32_bf16 v[64:67], v[14:17], v[40:43], v[28:31]
	v_mfma_f32_16x16x32_bf16 v[28:31], v[20:23], v[36:39], v[158:161]
	v_mfma_f32_16x16x32_bf16 v[60:63], v[24:27], v[40:43], v[28:31]
	v_mfma_f32_16x16x32_bf16 v[28:31], v[10:13], v[224:227], v[162:165]
	v_mfma_f32_16x16x32_bf16 v[48:51], v[14:17], v[228:231], v[28:31]
	v_mfma_f32_16x16x32_bf16 v[28:31], v[20:23], v[224:227], v[166:169]
	v_mfma_f32_16x16x32_bf16 v[44:47], v[24:27], v[228:231], v[28:31]
	v_mfma_f32_16x16x32_bf16 v[28:31], v[10:13], v[232:235], v[170:173]
	v_mfma_f32_16x16x32_bf16 v[2:5], v[10:13], v[240:243], v[2:5]
	v_mfma_f32_16x16x32_bf16 v[32:35], v[14:17], v[236:239], v[28:31]
	v_mfma_f32_16x16x32_bf16 v[28:31], v[20:23], v[232:235], v[176:179]
	v_mfma_f32_16x16x32_bf16 v[16:19], v[14:17], v[244:247], v[2:5]
	v_mfma_f32_16x16x32_bf16 v[2:5], v[20:23], v[240:243], v[6:9]
	v_mfma_f32_16x16x32_bf16 v[28:31], v[24:27], v[236:239], v[28:31]
	v_mfma_f32_16x16x32_bf16 v[12:15], v[24:27], v[244:247], v[2:5]
	v_mfma_f32_16x16x32_bf16 v[2:5], v[212:215], v[36:39], v[180:183]
	v_mfma_f32_16x16x32_bf16 v[56:59], v[216:219], v[40:43], v[2:5]
	v_mfma_f32_16x16x32_bf16 v[2:5], v[220:223], v[36:39], v[184:187]
	v_mfma_f32_16x16x32_bf16 v[52:55], v[150:153], v[40:43], v[2:5]
	v_mfma_f32_16x16x32_bf16 v[2:5], v[212:215], v[224:227], v[188:191]
	v_mfma_f32_16x16x32_bf16 v[40:43], v[216:219], v[228:231], v[2:5]
	v_mfma_f32_16x16x32_bf16 v[2:5], v[220:223], v[224:227], v[192:195]
	v_mfma_f32_16x16x32_bf16 v[36:39], v[150:153], v[228:231], v[2:5]
	v_mfma_f32_16x16x32_bf16 v[2:5], v[212:215], v[232:235], v[196:199]
	v_mfma_f32_16x16x32_bf16 v[24:27], v[216:219], v[236:239], v[2:5]
	v_mfma_f32_16x16x32_bf16 v[2:5], v[220:223], v[232:235], v[200:203]
	v_mfma_f32_16x16x32_bf16 v[20:23], v[150:153], v[236:239], v[2:5]
	v_mfma_f32_16x16x32_bf16 v[2:5], v[212:215], v[240:243], v[204:207]
	v_mfma_f32_16x16x32_bf16 v[8:11], v[216:219], v[244:247], v[2:5]
	v_mfma_f32_16x16x32_bf16 v[2:5], v[220:223], v[240:243], v[208:211]
	v_mfma_f32_16x16x32_bf16 v[4:7], v[150:153], v[244:247], v[2:5]
	s_barrier
	s_mov_b64 s[6:7], 0

; template <class Epi, class Sched, bool ALIGN_EPI = false, bool SP2 = false>
; __device__ __forceinline__ void gemm_phase(PG8_LAS unsigned char* lds, const Gemm g, const Sched& S, const Epi& E, int wave_s) {
;     ...
;         for (int t = peeled ? 2 : 0; t < nt; t += 2) {
;             const bool last = (t == nt - 2);
;             const char* a1 = cA + (size_t)(t + 1) * kstep;
;             const char* a2 = last ? nA : cA + (size_t)(t + 2) * kstep; const char* b2 = last ? nB : cB + (size_t)(t + 2) * kstep;
;             const char* a3 = a2 + kstep; const char* b3 = b2 + kstep;
;             if (last && has_next) S.a_ready(nxt);
.LBB0_419:
	v_add_u32_e32 v151, s78, v146
	v_add_u32_e32 v150, s79, v146
	ds_read_b128 v[152:155], v151
	ds_read_b128 v[156:159], v151 offset:1024
	ds_read_b128 v[160:163], v151 offset:2048
	ds_read_b128 v[164:167], v151 offset:3072
	ds_read_b128 v[168:171], v150
	ds_read_b128 v[176:179], v150 offset:1024
	ds_read_b128 v[180:183], v150 offset:2048
	ds_read_b128 v[184:187], v150 offset:3072
	s_add_u32 s8, s52, 0x100
	s_addc_u32 s9, s53, 0
	s_cmp_eq_u32 s96, 12
	s_cselect_b32 s42, s93, s8
	s_cselect_b32 s43, s82, s9
	s_cselect_b32 s40, s95, s97
	s_cselect_b32 s41, s94, vcc_lo
	s_add_u32 s38, s42, 0x80
	s_addc_u32 s39, s43, 0
	s_add_u32 s52, s52, 0x40080
	s_addc_u32 s53, s53, 0
	s_add_i32 s91, s35, 0xc000
	ds_read_b128 v[188:191], v149
	ds_read_b128 v[192:195], v149 offset:1024
	ds_read_b128 v[196:199], v149 offset:2048
	ds_read_b128 v[200:203], v149 offset:3072
	ds_read_b128 v[204:207], v149 offset:4096
	ds_read_b128 v[208:211], v149 offset:5120
	ds_read_b128 v[212:215], v149 offset:6144
	ds_read_b128 v[216:219], v149 offset:7168
	s_mov_b32 m0, s91
	s_add_i32 s10, s35, 0xe000
	global_load_lds_dwordx4 v132, s[52:53]
	s_mov_b32 m0, s10
	s_nop 0
	global_load_lds_dwordx4 v136, s[52:53]
	s_waitcnt vmcnt(8)
	s_waitcnt lgkmcnt(0)
	s_barrier
	s_waitcnt lgkmcnt(0)
	v_mfma_f32_16x16x32_bf16 v[128:131], v[152:155], v[188:191], v[128:131]
	v_mfma_f32_16x16x32_bf16 v[124:127], v[160:163], v[188:191], v[124:127]
	v_mfma_f32_16x16x32_bf16 v[112:115], v[152:155], v[196:199], v[112:115]
	v_mfma_f32_16x16x32_bf16 v[108:111], v[160:163], v[196:199], v[108:111]
	v_mfma_f32_16x16x32_bf16 v[96:99], v[152:155], v[204:207], v[96:99]
	v_mfma_f32_16x16x32_bf16 v[92:95], v[160:163], v[204:207], v[92:95]
	v_mfma_f32_16x16x32_bf16 v[80:83], v[152:155], v[212:215], v[80:83]
	v_mfma_f32_16x16x32_bf16 v[76:79], v[160:163], v[212:215], v[76:79]
	v_mfma_f32_16x16x32_bf16 v[128:131], v[156:159], v[192:195], v[128:131]
	v_mfma_f32_16x16x32_bf16 v[124:127], v[164:167], v[192:195], v[124:127]
	v_mfma_f32_16x16x32_bf16 v[112:115], v[156:159], v[200:203], v[112:115]
	v_mfma_f32_16x16x32_bf16 v[108:111], v[164:167], v[200:203], v[108:111]
	v_mfma_f32_16x16x32_bf16 v[96:99], v[156:159], v[208:211], v[96:99]
	v_mfma_f32_16x16x32_bf16 v[92:95], v[164:167], v[208:211], v[92:95]
	v_mfma_f32_16x16x32_bf16 v[80:83], v[156:159], v[216:219], v[80:83]
	v_mfma_f32_16x16x32_bf16 v[76:79], v[164:167], v[216:219], v[76:79]
	v_mfma_f32_16x16x32_bf16 v[120:123], v[168:171], v[188:191], v[120:123]
	v_mfma_f32_16x16x32_bf16 v[116:119], v[180:183], v[188:191], v[116:119]
	v_mfma_f32_16x16x32_bf16 v[104:107], v[168:171], v[196:199], v[104:107]
	v_mfma_f32_16x16x32_bf16 v[100:103], v[180:183], v[196:199], v[100:103]
	v_mfma_f32_16x16x32_bf16 v[88:91], v[168:171], v[204:207], v[88:91]
	v_mfma_f32_16x16x32_bf16 v[84:87], v[180:183], v[204:207], v[84:87]
	v_mfma_f32_16x16x32_bf16 v[72:75], v[168:171], v[212:215], v[72:75]
	v_mfma_f32_16x16x32_bf16 v[68:71], v[180:183], v[212:215], v[68:71]
	v_mfma_f32_16x16x32_bf16 v[120:123], v[176:179], v[192:195], v[120:123]
	v_mfma_f32_16x16x32_bf16 v[116:119], v[184:187], v[192:195], v[116:119]
	v_mfma_f32_16x16x32_bf16 v[104:107], v[176:179], v[200:203], v[104:107]
	v_mfma_f32_16x16x32_bf16 v[100:103], v[184:187], v[200:203], v[100:103]
	v_mfma_f32_16x16x32_bf16 v[88:91], v[176:179], v[208:211], v[88:91]
	v_mfma_f32_16x16x32_bf16 v[84:87], v[184:187], v[208:211], v[84:87]
	v_mfma_f32_16x16x32_bf16 v[72:75], v[176:179], v[216:219], v[72:75]
	v_mfma_f32_16x16x32_bf16 v[68:71], v[184:187], v[216:219], v[68:71]
	s_barrier
	s_setprio 1
	s_mov_b64 s[52:53], s[40:41]
	s_add_i32 s90, s78, s58
	ds_read_b128 v[188:191], v149 offset:16384
	ds_read_b128 v[192:195], v149 offset:17408
	ds_read_b128 v[196:199], v149 offset:18432
	ds_read_b128 v[200:203], v149 offset:19456
	ds_read_b128 v[204:207], v149 offset:20480
	ds_read_b128 v[208:211], v149 offset:21504
	ds_read_b128 v[212:215], v149 offset:22528
	ds_read_b128 v[216:219], v149 offset:23552
	s_mov_b32 m0, s90
	s_add_i32 s25, s90, 0x2000
	global_load_lds_dwordx4 v134, s[52:53]
	s_mov_b64 s[98:99], s[52:53]
	s_add_u32 s52, s40, 0x40000
	s_mov_b32 m0, s25
	s_addc_u32 s53, s41, 0
	s_add_i32 s27, s79, s58
	global_load_lds_dwordx4 v138, s[98:99]
	s_mov_b32 m0, s27
	s_add_i32 s88, s27, 0x2000
	global_load_lds_dwordx4 v134, s[52:53]
	s_mov_b64 s[98:99], s[52:53]
	s_mov_b32 m0, s88
	s_mov_b64 s[52:53], s[42:43]
	global_load_lds_dwordx4 v138, s[98:99]
	s_mov_b32 m0, s35
	s_nop 0
	global_load_lds_dwordx4 v132, s[52:53]
	s_mov_b32 m0, s37
	s_nop 0
	global_load_lds_dwordx4 v136, s[52:53]
	s_setprio 0
	s_waitcnt vmcnt(8)
	s_waitcnt lgkmcnt(0)
	s_barrier
	s_waitcnt lgkmcnt(0)
	v_mfma_f32_16x16x32_bf16 v[64:67], v[152:155], v[188:191], v[64:67]
	v_mfma_f32_16x16x32_bf16 v[60:63], v[160:163], v[188:191], v[60:63]
	v_mfma_f32_16x16x32_bf16 v[48:51], v[152:155], v[196:199], v[48:51]
	v_mfma_f32_16x16x32_bf16 v[44:47], v[160:163], v[196:199], v[44:47]
	v_mfma_f32_16x16x32_bf16 v[32:35], v[152:155], v[204:207], v[32:35]
	v_mfma_f32_16x16x32_bf16 v[28:31], v[160:163], v[204:207], v[28:31]
	v_mfma_f32_16x16x32_bf16 v[16:19], v[152:155], v[212:215], v[16:19]
	v_mfma_f32_16x16x32_bf16 v[12:15], v[160:163], v[212:215], v[12:15]
	v_mfma_f32_16x16x32_bf16 v[64:67], v[156:159], v[192:195], v[64:67]
	v_mfma_f32_16x16x32_bf16 v[60:63], v[164:167], v[192:195], v[60:63]
	v_mfma_f32_16x16x32_bf16 v[48:51], v[156:159], v[200:203], v[48:51]
	v_mfma_f32_16x16x32_bf16 v[44:47], v[164:167], v[200:203], v[44:47]
	v_mfma_f32_16x16x32_bf16 v[32:35], v[156:159], v[208:211], v[32:35]
	v_mfma_f32_16x16x32_bf16 v[28:31], v[164:167], v[208:211], v[28:31]
	v_mfma_f32_16x16x32_bf16 v[16:19], v[156:159], v[216:219], v[16:19]
	v_mfma_f32_16x16x32_bf16 v[12:15], v[164:167], v[216:219], v[12:15]
	v_mfma_f32_16x16x32_bf16 v[56:59], v[168:171], v[188:191], v[56:59]
	v_mfma_f32_16x16x32_bf16 v[52:55], v[180:183], v[188:191], v[52:55]
	v_mfma_f32_16x16x32_bf16 v[40:43], v[168:171], v[196:199], v[40:43]
	v_mfma_f32_16x16x32_bf16 v[36:39], v[180:183], v[196:199], v[36:39]
	v_mfma_f32_16x16x32_bf16 v[24:27], v[168:171], v[204:207], v[24:27]
	v_mfma_f32_16x16x32_bf16 v[20:23], v[180:183], v[204:207], v[20:23]
	v_mfma_f32_16x16x32_bf16 v[8:11], v[168:171], v[212:215], v[8:11]
	v_mfma_f32_16x16x32_bf16 v[2:5], v[180:183], v[212:215], v[4:7]
	v_mfma_f32_16x16x32_bf16 v[56:59], v[176:179], v[192:195], v[56:59]
	v_mfma_f32_16x16x32_bf16 v[52:55], v[184:187], v[192:195], v[52:55]
	v_mfma_f32_16x16x32_bf16 v[40:43], v[176:179], v[200:203], v[40:43]
	v_mfma_f32_16x16x32_bf16 v[36:39], v[184:187], v[200:203], v[36:39]
	v_mfma_f32_16x16x32_bf16 v[24:27], v[176:179], v[208:211], v[24:27]
	v_mfma_f32_16x16x32_bf16 v[20:23], v[184:187], v[208:211], v[20:23]
	v_mfma_f32_16x16x32_bf16 v[8:11], v[176:179], v[216:219], v[8:11]
	v_mfma_f32_16x16x32_bf16 v[2:5], v[184:187], v[216:219], v[2:5]
	s_barrier
	s_add_i32 s92, 0, 0x18000
	s_add_i32 s52, 0, 0x1c000
	v_add_u32_e32 v152, s92, v146
	v_add_u32_e32 v153, s52, v146
	ds_read_b128 v[154:157], v152
	ds_read_b128 v[158:161], v152 offset:1024
	ds_read_b128 v[162:165], v152 offset:2048
	ds_read_b128 v[166:169], v152 offset:3072
	ds_read_b128 v[170:173], v153
	ds_read_b128 v[176:179], v153 offset:1024
	ds_read_b128 v[180:183], v153 offset:2048
	ds_read_b128 v[184:187], v153 offset:3072
	s_add_u32 s42, s42, 0x40000
	s_addc_u32 s43, s43, 0
	s_mov_b32 m0, s60
	ds_read_b128 v[188:191], v149 offset:32768
	ds_read_b128 v[192:195], v149 offset:33792
	ds_read_b128 v[196:199], v149 offset:34816
	ds_read_b128 v[200:203], v149 offset:35840
	ds_read_b128 v[204:207], v149 offset:36864
	ds_read_b128 v[208:211], v149 offset:37888
	ds_read_b128 v[212:215], v149 offset:38912
	ds_read_b128 v[216:219], v149 offset:39936
	s_nop 0
	global_load_lds_dwordx4 v132, s[42:43]
	s_mov_b32 m0, s61
	s_nop 0
	global_load_lds_dwordx4 v136, s[42:43]
	s_waitcnt vmcnt(8)
	s_waitcnt lgkmcnt(0)
	s_barrier
	s_waitcnt lgkmcnt(0)
	v_mfma_f32_16x16x32_bf16 v[128:131], v[154:157], v[188:191], v[128:131]
	v_mfma_f32_16x16x32_bf16 v[124:127], v[162:165], v[188:191], v[124:127]
	v_mfma_f32_16x16x32_bf16 v[112:115], v[154:157], v[196:199], v[112:115]
	v_mfma_f32_16x16x32_bf16 v[108:111], v[162:165], v[196:199], v[108:111]
	v_mfma_f32_16x16x32_bf16 v[96:99], v[154:157], v[204:207], v[96:99]
	v_mfma_f32_16x16x32_bf16 v[92:95], v[162:165], v[204:207], v[92:95]
	v_mfma_f32_16x16x32_bf16 v[80:83], v[154:157], v[212:215], v[80:83]
	v_mfma_f32_16x16x32_bf16 v[76:79], v[162:165], v[212:215], v[76:79]
	v_mfma_f32_16x16x32_bf16 v[128:131], v[158:161], v[192:195], v[128:131]
	v_mfma_f32_16x16x32_bf16 v[124:127], v[166:169], v[192:195], v[124:127]
	v_mfma_f32_16x16x32_bf16 v[112:115], v[158:161], v[200:203], v[112:115]
	v_mfma_f32_16x16x32_bf16 v[108:111], v[166:169], v[200:203], v[108:111]
	v_mfma_f32_16x16x32_bf16 v[96:99], v[158:161], v[208:211], v[96:99]
	v_mfma_f32_16x16x32_bf16 v[92:95], v[166:169], v[208:211], v[92:95]
	v_mfma_f32_16x16x32_bf16 v[80:83], v[158:161], v[216:219], v[80:83]
	v_mfma_f32_16x16x32_bf16 v[76:79], v[166:169], v[216:219], v[76:79]
	v_mfma_f32_16x16x32_bf16 v[120:123], v[170:173], v[188:191], v[120:123]
	v_mfma_f32_16x16x32_bf16 v[116:119], v[180:183], v[188:191], v[116:119]
	v_mfma_f32_16x16x32_bf16 v[104:107], v[170:173], v[196:199], v[104:107]
	v_mfma_f32_16x16x32_bf16 v[100:103], v[180:183], v[196:199], v[100:103]
	v_mfma_f32_16x16x32_bf16 v[88:91], v[170:173], v[204:207], v[88:91]
	v_mfma_f32_16x16x32_bf16 v[84:87], v[180:183], v[204:207], v[84:87]
	v_mfma_f32_16x16x32_bf16 v[72:75], v[170:173], v[212:215], v[72:75]
	v_mfma_f32_16x16x32_bf16 v[68:71], v[180:183], v[212:215], v[68:71]
	v_mfma_f32_16x16x32_bf16 v[120:123], v[176:179], v[192:195], v[120:123]
	v_mfma_f32_16x16x32_bf16 v[116:119], v[184:187], v[192:195], v[116:119]
	v_mfma_f32_16x16x32_bf16 v[104:107], v[176:179], v[200:203], v[104:107]
	v_mfma_f32_16x16x32_bf16 v[100:103], v[184:187], v[200:203], v[100:103]
	v_mfma_f32_16x16x32_bf16 v[88:91], v[176:179], v[208:211], v[88:91]
	v_mfma_f32_16x16x32_bf16 v[84:87], v[184:187], v[208:211], v[84:87]
	v_mfma_f32_16x16x32_bf16 v[72:75], v[176:179], v[216:219], v[72:75]
	v_mfma_f32_16x16x32_bf16 v[68:71], v[184:187], v[216:219], v[68:71]
	s_barrier
; #define PG8_BAR __builtin_amdgcn_s_barrier()
; template <class Epi, class Sched, bool ALIGN_EPI = false, bool SP2 = false>
; __device__ __forceinline__ void gemm_phase(PG8_LAS unsigned char* lds, const Gemm g, const Sched& S, const Epi& E, int wave_s) {
;     ...
;         }
;         if constexpr (ALIGN_EPI) { if (wr == 0) PG8_BAR; }
	s_setprio 1
	s_add_u32 s42, s40, 0x80
	s_addc_u32 s43, s41, 0
	s_add_i32 s92, s92, s58
	ds_read_b128 v[188:191], v149 offset:49152
	ds_read_b128 v[192:195], v149 offset:50176
	ds_read_b128 v[196:199], v149 offset:51200
	ds_read_b128 v[200:203], v149 offset:52224
	ds_read_b128 v[204:207], v149 offset:53248
	ds_read_b128 v[208:211], v149 offset:54272
	ds_read_b128 v[212:215], v149 offset:55296
	ds_read_b128 v[216:219], v149 offset:56320
	s_mov_b32 m0, s92
	s_nop 0
	global_load_lds_dwordx4 v134, s[42:43]
	s_mov_b64 s[98:99], s[42:43]
	s_add_i32 s42, s92, 0x2000
	s_add_u32 s40, s40, 0x40080
	s_mov_b32 m0, s42
	s_addc_u32 s41, s41, 0
	s_add_i32 s43, s52, s58
	global_load_lds_dwordx4 v138, s[98:99]
	s_mov_b32 m0, s43
	s_add_i32 s89, s43, 0x2000
	global_load_lds_dwordx4 v134, s[40:41]
	s_mov_b32 m0, s89
	s_nop 0
	global_load_lds_dwordx4 v138, s[40:41]
	s_mov_b32 m0, s63
	s_nop 0
	global_load_lds_dwordx4 v132, s[38:39]
	s_mov_b32 m0, s72
	s_nop 0
	global_load_lds_dwordx4 v136, s[38:39]
	s_setprio 0
	s_waitcnt vmcnt(8)
	s_waitcnt lgkmcnt(0)
	s_barrier
	s_waitcnt lgkmcnt(0)
	v_mfma_f32_16x16x32_bf16 v[64:67], v[154:157], v[188:191], v[64:67]
	v_mfma_f32_16x16x32_bf16 v[60:63], v[162:165], v[188:191], v[60:63]
	v_mfma_f32_16x16x32_bf16 v[48:51], v[154:157], v[196:199], v[48:51]
	v_mfma_f32_16x16x32_bf16 v[44:47], v[162:165], v[196:199], v[44:47]
	v_mfma_f32_16x16x32_bf16 v[32:35], v[154:157], v[204:207], v[32:35]
	v_mfma_f32_16x16x32_bf16 v[28:31], v[162:165], v[204:207], v[28:31]
	v_mfma_f32_16x16x32_bf16 v[16:19], v[154:157], v[212:215], v[16:19]
	v_mfma_f32_16x16x32_bf16 v[12:15], v[162:165], v[212:215], v[12:15]
	v_mfma_f32_16x16x32_bf16 v[64:67], v[158:161], v[192:195], v[64:67]
	v_mfma_f32_16x16x32_bf16 v[60:63], v[166:169], v[192:195], v[60:63]
	v_mfma_f32_16x16x32_bf16 v[48:51], v[158:161], v[200:203], v[48:51]
	v_mfma_f32_16x16x32_bf16 v[44:47], v[166:169], v[200:203], v[44:47]
	v_mfma_f32_16x16x32_bf16 v[32:35], v[158:161], v[208:211], v[32:35]
	v_mfma_f32_16x16x32_bf16 v[28:31], v[166:169], v[208:211], v[28:31]
	v_mfma_f32_16x16x32_bf16 v[16:19], v[158:161], v[216:219], v[16:19]
	v_mfma_f32_16x16x32_bf16 v[12:15], v[166:169], v[216:219], v[12:15]
	v_mfma_f32_16x16x32_bf16 v[56:59], v[170:173], v[188:191], v[56:59]
	v_mfma_f32_16x16x32_bf16 v[52:55], v[180:183], v[188:191], v[52:55]
	v_mfma_f32_16x16x32_bf16 v[40:43], v[170:173], v[196:199], v[40:43]
	v_mfma_f32_16x16x32_bf16 v[36:39], v[180:183], v[196:199], v[36:39]
	v_mfma_f32_16x16x32_bf16 v[24:27], v[170:173], v[204:207], v[24:27]
	v_mfma_f32_16x16x32_bf16 v[20:23], v[180:183], v[204:207], v[20:23]
	v_mfma_f32_16x16x32_bf16 v[6:9], v[170:173], v[212:215], v[8:11]
	v_mfma_f32_16x16x32_bf16 v[2:5], v[180:183], v[212:215], v[2:5]
	v_mfma_f32_16x16x32_bf16 v[56:59], v[176:179], v[192:195], v[56:59]
	v_mfma_f32_16x16x32_bf16 v[52:55], v[184:187], v[192:195], v[52:55]
	v_mfma_f32_16x16x32_bf16 v[40:43], v[176:179], v[200:203], v[40:43]
	v_mfma_f32_16x16x32_bf16 v[36:39], v[184:187], v[200:203], v[36:39]
	v_mfma_f32_16x16x32_bf16 v[24:27], v[176:179], v[208:211], v[24:27]
	v_mfma_f32_16x16x32_bf16 v[20:23], v[184:187], v[208:211], v[20:23]
	v_mfma_f32_16x16x32_bf16 v[8:11], v[176:179], v[216:219], v[6:9]
	v_mfma_f32_16x16x32_bf16 v[4:7], v[184:187], v[216:219], v[2:5]
	s_barrier
	s_add_i32 s96, s96, 2
	s_add_u32 s97, s97, 0x100
	s_addc_u32 vcc_lo, vcc_lo, 0
	s_cmp_gt_u32 s96, 13
	s_mov_b64 s[52:53], s[8:9]
	s_cbranch_scc0 .LBB0_419
	s_and_b64 vcc, exec, s[16:17]
	s_cbranch_vccz .LBB0_422
	s_barrier

; template <class Epi, class Sched, bool ALIGN_EPI = false, bool SP2 = false>
; __device__ __forceinline__ void gemm_phase(PG8_LAS unsigned char* lds, const Gemm g, const Sched& S, const Epi& E, int wave_s) {
;     ...
;         for (int t = peeled ? 2 : 0; t < nt; t += 2) {
;             const bool last = (t == nt - 2);
;             const char* a1 = cA + (size_t)(t + 1) * kstep;
;             const char* a2 = last ? nA : cA + (size_t)(t + 2) * kstep; const char* b2 = last ? nB : cB + (size_t)(t + 2) * kstep;
;             const char* a3 = a2 + kstep; const char* b3 = b2 + kstep;
;             if (last && has_next) S.a_ready(nxt);
.LBB0_822:
	ds_read_b128 v[140:143], v147
	ds_read_b128 v[160:163], v147 offset:1024
	ds_read_b128 v[164:167], v147 offset:2048
	ds_read_b128 v[168:171], v147 offset:3072
	ds_read_b128 v[176:179], v148
	ds_read_b128 v[180:183], v148 offset:1024
	ds_read_b128 v[184:187], v148 offset:2048
	ds_read_b128 v[188:191], v148 offset:3072
	s_add_u32 s42, s40, 0x100
	s_addc_u32 s43, s41, 0
	s_cmp_eq_u32 vcc_lo, 12
	s_cselect_b32 s76, s37, s42
	s_cselect_b32 s77, s29, s43
	s_cselect_b32 s74, s39, s60
	s_cselect_b32 s75, s27, s61
	s_add_u32 s72, s76, 0x80
	s_addc_u32 s73, s77, 0
	s_add_u32 s40, s40, 0x40080
	s_addc_u32 s41, s41, 0
	ds_read_b128 v[192:195], v149
	ds_read_b128 v[196:199], v149 offset:1024
	ds_read_b128 v[200:203], v149 offset:2048
	ds_read_b128 v[204:207], v149 offset:3072
	ds_read_b128 v[208:211], v149 offset:4096
	ds_read_b128 v[212:215], v149 offset:5120
	ds_read_b128 v[216:219], v149 offset:6144
	ds_read_b128 v[220:223], v149 offset:7168
	s_add_i32 m0, s87, 0xc000
	s_nop 0
	global_load_lds_dwordx4 v128, s[40:41]
	s_add_i32 m0, s87, 0xe000
	s_nop 0
	global_load_lds_dwordx4 v132, s[40:41]
	s_waitcnt vmcnt(8)
	s_waitcnt lgkmcnt(0)
	s_barrier
	s_waitcnt lgkmcnt(0)
	v_mfma_f32_16x16x32_bf16 v[124:127], v[140:143], v[192:195], v[124:127]
	v_mfma_f32_16x16x32_bf16 v[120:123], v[164:167], v[192:195], v[120:123]
	v_mfma_f32_16x16x32_bf16 v[108:111], v[140:143], v[200:203], v[108:111]
	v_mfma_f32_16x16x32_bf16 v[104:107], v[164:167], v[200:203], v[104:107]
	v_mfma_f32_16x16x32_bf16 v[92:95], v[140:143], v[208:211], v[92:95]
	v_mfma_f32_16x16x32_bf16 v[88:91], v[164:167], v[208:211], v[88:91]
	v_mfma_f32_16x16x32_bf16 v[76:79], v[140:143], v[216:219], v[76:79]
	v_mfma_f32_16x16x32_bf16 v[72:75], v[164:167], v[216:219], v[72:75]
	v_mfma_f32_16x16x32_bf16 v[124:127], v[160:163], v[196:199], v[124:127]
	v_mfma_f32_16x16x32_bf16 v[120:123], v[168:171], v[196:199], v[120:123]
	v_mfma_f32_16x16x32_bf16 v[108:111], v[160:163], v[204:207], v[108:111]
	v_mfma_f32_16x16x32_bf16 v[104:107], v[168:171], v[204:207], v[104:107]
	v_mfma_f32_16x16x32_bf16 v[92:95], v[160:163], v[212:215], v[92:95]
	v_mfma_f32_16x16x32_bf16 v[88:91], v[168:171], v[212:215], v[88:91]
	v_mfma_f32_16x16x32_bf16 v[76:79], v[160:163], v[220:223], v[76:79]
	v_mfma_f32_16x16x32_bf16 v[72:75], v[168:171], v[220:223], v[72:75]
	v_mfma_f32_16x16x32_bf16 v[116:119], v[176:179], v[192:195], v[116:119]
	v_mfma_f32_16x16x32_bf16 v[112:115], v[184:187], v[192:195], v[112:115]
	v_mfma_f32_16x16x32_bf16 v[100:103], v[176:179], v[200:203], v[100:103]
	v_mfma_f32_16x16x32_bf16 v[96:99], v[184:187], v[200:203], v[96:99]
	v_mfma_f32_16x16x32_bf16 v[84:87], v[176:179], v[208:211], v[84:87]
	v_mfma_f32_16x16x32_bf16 v[80:83], v[184:187], v[208:211], v[80:83]
	v_mfma_f32_16x16x32_bf16 v[68:71], v[176:179], v[216:219], v[68:71]
	v_mfma_f32_16x16x32_bf16 v[64:67], v[184:187], v[216:219], v[64:67]
	v_mfma_f32_16x16x32_bf16 v[116:119], v[180:183], v[196:199], v[116:119]
	v_mfma_f32_16x16x32_bf16 v[112:115], v[188:191], v[196:199], v[112:115]
	v_mfma_f32_16x16x32_bf16 v[100:103], v[180:183], v[204:207], v[100:103]
	v_mfma_f32_16x16x32_bf16 v[96:99], v[188:191], v[204:207], v[96:99]
	v_mfma_f32_16x16x32_bf16 v[84:87], v[180:183], v[212:215], v[84:87]
	v_mfma_f32_16x16x32_bf16 v[80:83], v[188:191], v[212:215], v[80:83]
	v_mfma_f32_16x16x32_bf16 v[68:71], v[180:183], v[220:223], v[68:71]
	v_mfma_f32_16x16x32_bf16 v[64:67], v[188:191], v[220:223], v[64:67]
	s_barrier
	s_setprio 1
	s_mov_b64 s[40:41], s[74:75]
	s_add_i32 vcc_hi, s97, s79
	ds_read_b128 v[192:195], v149 offset:16384
	ds_read_b128 v[196:199], v149 offset:17408
	ds_read_b128 v[200:203], v149 offset:18432
	ds_read_b128 v[204:207], v149 offset:19456
	ds_read_b128 v[208:211], v149 offset:20480
	ds_read_b128 v[212:215], v149 offset:21504
	ds_read_b128 v[216:219], v149 offset:22528
	ds_read_b128 v[220:223], v149 offset:23552
	s_mov_b32 m0, vcc_hi
	s_nop 0
	global_load_lds_dwordx4 v130, s[40:41]
	s_add_i32 m0, vcc_hi, 0x2000
	s_nop 0
	global_load_lds_dwordx4 v134, s[40:41]
	s_add_u32 s40, s74, 0x40000
	s_addc_u32 s41, s75, 0
	s_add_i32 vcc_hi, s82, s79
	s_mov_b32 m0, vcc_hi
	s_nop 0
	global_load_lds_dwordx4 v130, s[40:41]
	s_mov_b64 s[98:99], s[40:41]
	s_add_i32 m0, vcc_hi, 0x2000
	s_mov_b64 s[40:41], s[76:77]
	global_load_lds_dwordx4 v134, s[98:99]
	s_mov_b32 m0, s87
	s_nop 0
	global_load_lds_dwordx4 v128, s[40:41]
	s_mov_b32 m0, s88
	s_nop 0
	global_load_lds_dwordx4 v132, s[40:41]
	s_setprio 0
	s_waitcnt vmcnt(8)
	s_waitcnt lgkmcnt(0)
	s_barrier
	s_waitcnt lgkmcnt(0)
	v_mfma_f32_16x16x32_bf16 v[60:63], v[140:143], v[192:195], v[60:63]
	v_mfma_f32_16x16x32_bf16 v[56:59], v[164:167], v[192:195], v[56:59]
	v_mfma_f32_16x16x32_bf16 v[44:47], v[140:143], v[200:203], v[44:47]
	v_mfma_f32_16x16x32_bf16 v[40:43], v[164:167], v[200:203], v[40:43]
	v_mfma_f32_16x16x32_bf16 v[28:31], v[140:143], v[208:211], v[28:31]
	v_mfma_f32_16x16x32_bf16 v[24:27], v[164:167], v[208:211], v[24:27]
	v_mfma_f32_16x16x32_bf16 v[12:15], v[140:143], v[216:219], v[12:15]
	v_mfma_f32_16x16x32_bf16 v[8:11], v[164:167], v[216:219], v[8:11]
	v_mfma_f32_16x16x32_bf16 v[60:63], v[160:163], v[196:199], v[60:63]
	v_mfma_f32_16x16x32_bf16 v[56:59], v[168:171], v[196:199], v[56:59]
	v_mfma_f32_16x16x32_bf16 v[44:47], v[160:163], v[204:207], v[44:47]
	v_mfma_f32_16x16x32_bf16 v[40:43], v[168:171], v[204:207], v[40:43]
	v_mfma_f32_16x16x32_bf16 v[28:31], v[160:163], v[212:215], v[28:31]
	v_mfma_f32_16x16x32_bf16 v[24:27], v[168:171], v[212:215], v[24:27]
	v_mfma_f32_16x16x32_bf16 v[12:15], v[160:163], v[220:223], v[12:15]
	v_mfma_f32_16x16x32_bf16 v[8:11], v[168:171], v[220:223], v[8:11]
	v_mfma_f32_16x16x32_bf16 v[52:55], v[176:179], v[192:195], v[52:55]
	v_mfma_f32_16x16x32_bf16 v[48:51], v[184:187], v[192:195], v[48:51]
	v_mfma_f32_16x16x32_bf16 v[36:39], v[176:179], v[200:203], v[36:39]
	v_mfma_f32_16x16x32_bf16 v[32:35], v[184:187], v[200:203], v[32:35]
	v_mfma_f32_16x16x32_bf16 v[20:23], v[176:179], v[208:211], v[20:23]
	v_mfma_f32_16x16x32_bf16 v[16:19], v[184:187], v[208:211], v[16:19]
	v_mfma_f32_16x16x32_bf16 v[4:7], v[176:179], v[216:219], v[4:7]
	v_mfma_f32_16x16x32_bf16 v[0:3], v[184:187], v[216:219], v[0:3]
	v_mfma_f32_16x16x32_bf16 v[52:55], v[180:183], v[196:199], v[52:55]
	v_mfma_f32_16x16x32_bf16 v[48:51], v[188:191], v[196:199], v[48:51]
	v_mfma_f32_16x16x32_bf16 v[36:39], v[180:183], v[204:207], v[36:39]
	v_mfma_f32_16x16x32_bf16 v[32:35], v[188:191], v[204:207], v[32:35]
	v_mfma_f32_16x16x32_bf16 v[20:23], v[180:183], v[212:215], v[20:23]
	v_mfma_f32_16x16x32_bf16 v[16:19], v[188:191], v[212:215], v[16:19]
	v_mfma_f32_16x16x32_bf16 v[4:7], v[180:183], v[220:223], v[4:7]
	v_mfma_f32_16x16x32_bf16 v[0:3], v[188:191], v[220:223], v[0:3]
	s_barrier
; #define PG8_BAR __builtin_amdgcn_s_barrier()
; template <class Epi, class Sched, bool ALIGN_EPI = false, bool SP2 = false>
; __device__ __forceinline__ void gemm_phase(PG8_LAS unsigned char* lds, const Gemm g, const Sched& S, const Epi& E, int wave_s) {
;     ...
;         }
;         if constexpr (ALIGN_EPI) { if (wr == 0) PG8_BAR; }
	s_add_i32 vcc_hi, 0, 0x18000
	v_add_u32_e32 v159, vcc_hi, v145
	s_add_i32 s86, 0, 0x1c000
	ds_read_b128 v[140:143], v159
	ds_read_b128 v[160:163], v159 offset:1024
	ds_read_b128 v[164:167], v159 offset:2048
	ds_read_b128 v[168:171], v159 offset:3072
	v_add_u32_e32 v159, s86, v145
	ds_read_b128 v[176:179], v159
	ds_read_b128 v[180:183], v159 offset:1024
	ds_read_b128 v[184:187], v159 offset:2048
	ds_read_b128 v[188:191], v159 offset:3072
	s_add_u32 s40, s76, 0x40000
	s_addc_u32 s41, s77, 0
	s_mov_b32 m0, s89
	ds_read_b128 v[192:195], v149 offset:32768
	ds_read_b128 v[196:199], v149 offset:33792
	ds_read_b128 v[200:203], v149 offset:34816
	ds_read_b128 v[204:207], v149 offset:35840
	ds_read_b128 v[208:211], v149 offset:36864
	ds_read_b128 v[212:215], v149 offset:37888
	ds_read_b128 v[216:219], v149 offset:38912
	ds_read_b128 v[220:223], v149 offset:39936
	s_nop 0
	global_load_lds_dwordx4 v128, s[40:41]
	s_mov_b32 m0, s90
	s_nop 0
	global_load_lds_dwordx4 v132, s[40:41]
	s_waitcnt vmcnt(8)
	s_waitcnt lgkmcnt(0)
	s_barrier
	s_waitcnt lgkmcnt(0)
	v_mfma_f32_16x16x32_bf16 v[124:127], v[140:143], v[192:195], v[124:127]
	v_mfma_f32_16x16x32_bf16 v[120:123], v[164:167], v[192:195], v[120:123]
	v_mfma_f32_16x16x32_bf16 v[108:111], v[140:143], v[200:203], v[108:111]
	v_mfma_f32_16x16x32_bf16 v[104:107], v[164:167], v[200:203], v[104:107]
	v_mfma_f32_16x16x32_bf16 v[92:95], v[140:143], v[208:211], v[92:95]
	v_mfma_f32_16x16x32_bf16 v[88:91], v[164:167], v[208:211], v[88:91]
	v_mfma_f32_16x16x32_bf16 v[76:79], v[140:143], v[216:219], v[76:79]
	v_mfma_f32_16x16x32_bf16 v[72:75], v[164:167], v[216:219], v[72:75]
	v_mfma_f32_16x16x32_bf16 v[124:127], v[160:163], v[196:199], v[124:127]
	v_mfma_f32_16x16x32_bf16 v[120:123], v[168:171], v[196:199], v[120:123]
	v_mfma_f32_16x16x32_bf16 v[108:111], v[160:163], v[204:207], v[108:111]
	v_mfma_f32_16x16x32_bf16 v[104:107], v[168:171], v[204:207], v[104:107]
	v_mfma_f32_16x16x32_bf16 v[92:95], v[160:163], v[212:215], v[92:95]
	v_mfma_f32_16x16x32_bf16 v[88:91], v[168:171], v[212:215], v[88:91]
	v_mfma_f32_16x16x32_bf16 v[76:79], v[160:163], v[220:223], v[76:79]
	v_mfma_f32_16x16x32_bf16 v[72:75], v[168:171], v[220:223], v[72:75]
	v_mfma_f32_16x16x32_bf16 v[116:119], v[176:179], v[192:195], v[116:119]
	v_mfma_f32_16x16x32_bf16 v[112:115], v[184:187], v[192:195], v[112:115]
	v_mfma_f32_16x16x32_bf16 v[100:103], v[176:179], v[200:203], v[100:103]
	v_mfma_f32_16x16x32_bf16 v[96:99], v[184:187], v[200:203], v[96:99]
	v_mfma_f32_16x16x32_bf16 v[84:87], v[176:179], v[208:211], v[84:87]
	v_mfma_f32_16x16x32_bf16 v[80:83], v[184:187], v[208:211], v[80:83]
	v_mfma_f32_16x16x32_bf16 v[68:71], v[176:179], v[216:219], v[68:71]
	v_mfma_f32_16x16x32_bf16 v[64:67], v[184:187], v[216:219], v[64:67]
	v_mfma_f32_16x16x32_bf16 v[116:119], v[180:183], v[196:199], v[116:119]
	v_mfma_f32_16x16x32_bf16 v[112:115], v[188:191], v[196:199], v[112:115]
	v_mfma_f32_16x16x32_bf16 v[100:103], v[180:183], v[204:207], v[100:103]
	v_mfma_f32_16x16x32_bf16 v[96:99], v[188:191], v[204:207], v[96:99]
	v_mfma_f32_16x16x32_bf16 v[84:87], v[180:183], v[212:215], v[84:87]
	v_mfma_f32_16x16x32_bf16 v[80:83], v[188:191], v[212:215], v[80:83]
	v_mfma_f32_16x16x32_bf16 v[68:71], v[180:183], v[220:223], v[68:71]
	v_mfma_f32_16x16x32_bf16 v[64:67], v[188:191], v[220:223], v[64:67]
	s_barrier
	s_setprio 1
	s_add_u32 s40, s74, 0x80
	s_addc_u32 s41, s75, 0
	s_add_i32 s76, vcc_hi, s79
	ds_read_b128 v[192:195], v149 offset:49152
	ds_read_b128 v[196:199], v149 offset:50176
	ds_read_b128 v[200:203], v149 offset:51200
	ds_read_b128 v[204:207], v149 offset:52224
	ds_read_b128 v[208:211], v149 offset:53248
	ds_read_b128 v[212:215], v149 offset:54272
	ds_read_b128 v[216:219], v149 offset:55296
	ds_read_b128 v[220:223], v149 offset:56320
	s_mov_b32 m0, s76
	s_nop 0
	global_load_lds_dwordx4 v130, s[40:41]
	s_add_i32 m0, s76, 0x2000
	s_nop 0
	global_load_lds_dwordx4 v134, s[40:41]
	s_add_u32 s40, s74, 0x40080
	s_addc_u32 s41, s75, 0
	s_add_i32 s74, s86, s79
	s_mov_b32 m0, s74
	s_nop 0
	global_load_lds_dwordx4 v130, s[40:41]
	s_add_i32 m0, s74, 0x2000
	s_nop 0
	global_load_lds_dwordx4 v134, s[40:41]
	s_mov_b32 m0, s92
	s_nop 0
	global_load_lds_dwordx4 v128, s[72:73]
	s_mov_b32 m0, s93
	s_nop 0
	global_load_lds_dwordx4 v132, s[72:73]
	s_setprio 0
	s_waitcnt vmcnt(8)
	s_waitcnt lgkmcnt(0)
	s_barrier
	s_waitcnt lgkmcnt(0)
	v_mfma_f32_16x16x32_bf16 v[60:63], v[140:143], v[192:195], v[60:63]
	v_mfma_f32_16x16x32_bf16 v[56:59], v[164:167], v[192:195], v[56:59]
	v_mfma_f32_16x16x32_bf16 v[44:47], v[140:143], v[200:203], v[44:47]
	v_mfma_f32_16x16x32_bf16 v[40:43], v[164:167], v[200:203], v[40:43]
	v_mfma_f32_16x16x32_bf16 v[28:31], v[140:143], v[208:211], v[28:31]
	v_mfma_f32_16x16x32_bf16 v[24:27], v[164:167], v[208:211], v[24:27]
	v_mfma_f32_16x16x32_bf16 v[12:15], v[140:143], v[216:219], v[12:15]
	v_mfma_f32_16x16x32_bf16 v[8:11], v[164:167], v[216:219], v[8:11]
	v_mfma_f32_16x16x32_bf16 v[60:63], v[160:163], v[196:199], v[60:63]
	v_mfma_f32_16x16x32_bf16 v[56:59], v[168:171], v[196:199], v[56:59]
	v_mfma_f32_16x16x32_bf16 v[44:47], v[160:163], v[204:207], v[44:47]
	v_mfma_f32_16x16x32_bf16 v[40:43], v[168:171], v[204:207], v[40:43]
	v_mfma_f32_16x16x32_bf16 v[28:31], v[160:163], v[212:215], v[28:31]
	v_mfma_f32_16x16x32_bf16 v[24:27], v[168:171], v[212:215], v[24:27]
	v_mfma_f32_16x16x32_bf16 v[12:15], v[160:163], v[220:223], v[12:15]
	v_mfma_f32_16x16x32_bf16 v[8:11], v[168:171], v[220:223], v[8:11]
	v_mfma_f32_16x16x32_bf16 v[52:55], v[176:179], v[192:195], v[52:55]
	v_mfma_f32_16x16x32_bf16 v[48:51], v[184:187], v[192:195], v[48:51]
	v_mfma_f32_16x16x32_bf16 v[36:39], v[176:179], v[200:203], v[36:39]
	v_mfma_f32_16x16x32_bf16 v[32:35], v[184:187], v[200:203], v[32:35]
	v_mfma_f32_16x16x32_bf16 v[20:23], v[176:179], v[208:211], v[20:23]
	v_mfma_f32_16x16x32_bf16 v[16:19], v[184:187], v[208:211], v[16:19]
	v_mfma_f32_16x16x32_bf16 v[4:7], v[176:179], v[216:219], v[4:7]
	v_mfma_f32_16x16x32_bf16 v[0:3], v[184:187], v[216:219], v[0:3]
	v_mfma_f32_16x16x32_bf16 v[52:55], v[180:183], v[196:199], v[52:55]
	v_mfma_f32_16x16x32_bf16 v[48:51], v[188:191], v[196:199], v[48:51]
	v_mfma_f32_16x16x32_bf16 v[36:39], v[180:183], v[204:207], v[36:39]
	v_mfma_f32_16x16x32_bf16 v[32:35], v[188:191], v[204:207], v[32:35]
	v_mfma_f32_16x16x32_bf16 v[20:23], v[180:183], v[212:215], v[20:23]
	v_mfma_f32_16x16x32_bf16 v[16:19], v[188:191], v[212:215], v[16:19]
	v_mfma_f32_16x16x32_bf16 v[4:7], v[180:183], v[220:223], v[4:7]
	v_mfma_f32_16x16x32_bf16 v[0:3], v[188:191], v[220:223], v[0:3]
	s_barrier
	s_add_i32 vcc_lo, vcc_lo, 2
	s_add_u32 s60, s60, 0x100
	s_addc_u32 s61, s61, 0
	s_cmp_gt_u32 vcc_lo, 13
	s_mov_b64 s[40:41], s[42:43]
	s_cbranch_scc0 .LBB0_822
	s_and_b64 vcc, exec, s[16:17]
	s_cbranch_vccz .LBB0_825
	s_barrier

; __device__ __forceinline__ int lane_id_() { int l; asm volatile("v_mbcnt_lo_u32_b32 %0, -1, 0\n\tv_mbcnt_hi_u32_b32 %0, -1, %0" : "=v"(l)); return l; }
; #define PG8_LAS __attribute__((address_space(3)))
;     __device__ __forceinline__ void prefetch(PG8_LAS unsigned char* lds, int wid, const Unit& u, int wr, int fr, int fq) const {
;         { const int l_ = lane_id_(); fr = l_ & 15; fq = l_ >> 4; }
; #pragma unroll
;         for (int j = 0; j < 2; ++j) { const int i = 2 * fq + j;
;             __builtin_amdgcn_global_load_lds((const unsigned*)(ssq + u.pm * BM + wr * 64 + fr + (i >> 2) * HALF + (i & 3) * 16), (PG8_LAS unsigned*)(lds + PRE_SLOT + wid * 512 + j * 256), 4, 0, 0); }
;     }
.LBB0_907:
	s_lshl_b32 s6, s22, 8
	s_ashr_i32 s7, s6, 31
	s_lshl_b64 s[6:7], s[6:7], 2
	v_mbcnt_lo_u32_b32 v6, -1, 0
	v_mbcnt_hi_u32_b32 v6, -1, v6
	s_add_u32 s6, s63, s6
	v_and_b32_e32 v0, 15, v6
	v_lshlrev_b32_e32 v2, 2, v6
	v_and_b32_e32 v2, 0xffffff80, v2
	s_addc_u32 s7, s78, s7
	v_lshlrev_b32_e32 v0, 2, v0
	v_ashrrev_i32_e32 v3, 31, v2
	v_lshl_add_u64 v[4:5], s[6:7], 0, v[0:1]
	v_lshlrev_b32_e32 v0, 3, v6
	v_lshl_add_u64 v[2:3], v[2:3], 2, v[4:5]
	v_and_b32_e32 v0, 0x80, v0
	s_mov_b32 m0, s71
	v_lshl_add_u64 v[2:3], v[2:3], 0, v[0:1]
	global_load_lds_dword v[2:3], off
	v_lshl_add_u64 v[2:3], v[2:3], 0, 64
	s_add_i32 m0, s71, 0x100
	s_add_u32 s28, s24, 0x100
	global_load_lds_dword v[2:3], off
	ds_read_b128 v[2:5], v151
	ds_read_b128 v[6:9], v151 offset:1024
	ds_read_b128 v[10:13], v151 offset:2048
	ds_read_b128 v[14:17], v151 offset:3072
	ds_read_b128 v[18:21], v150
	ds_read_b128 v[22:25], v150 offset:1024
	ds_read_b128 v[26:29], v150 offset:2048
	ds_read_b128 v[30:33], v150 offset:3072
	s_addc_u32 s29, s25, 0
	s_add_u32 s8, s24, 0x180
	s_addc_u32 s9, s25, 0
	s_add_u32 s6, s26, 0x100
	s_addc_u32 s7, s27, 0
	s_add_u32 s30, s24, 0x40080
	s_addc_u32 s31, s25, 0
	s_mov_b32 m0, s90
	ds_read_b128 v[34:37], v149
	ds_read_b128 v[38:41], v149 offset:1024
	ds_read_b128 v[42:45], v149 offset:2048
	ds_read_b128 v[46:49], v149 offset:3072
	ds_read_b128 v[50:53], v149 offset:4096
	ds_read_b128 v[54:57], v149 offset:5120
	ds_read_b128 v[58:61], v149 offset:6144
	ds_read_b128 v[62:65], v149 offset:7168
	s_nop 0
	global_load_lds_dwordx4 v138, s[30:31]
	s_mov_b32 m0, s10
	s_nop 0
	global_load_lds_dwordx4 v134, s[30:31]
	s_waitcnt vmcnt(18)
	s_waitcnt lgkmcnt(0)
	s_barrier
	s_waitcnt lgkmcnt(0)
	v_mfma_f32_16x16x32_bf16 v[90:93], v[2:5], v[58:61], 0
	v_mfma_f32_16x16x32_bf16 v[66:69], v[2:5], v[34:37], 0
	v_mfma_f32_16x16x32_bf16 v[70:73], v[10:13], v[34:37], 0
	v_mfma_f32_16x16x32_bf16 v[74:77], v[2:5], v[42:45], 0
	v_mfma_f32_16x16x32_bf16 v[78:81], v[10:13], v[42:45], 0
	v_mfma_f32_16x16x32_bf16 v[82:85], v[2:5], v[50:53], 0
	v_mfma_f32_16x16x32_bf16 v[86:89], v[10:13], v[50:53], 0
	v_mfma_f32_16x16x32_bf16 v[96:99], v[6:9], v[62:65], v[90:93]
	v_mfma_f32_16x16x32_bf16 v[90:93], v[10:13], v[58:61], 0
	v_mfma_f32_16x16x32_bf16 v[66:69], v[6:9], v[38:41], v[66:69]
	v_mfma_f32_16x16x32_bf16 v[70:73], v[14:17], v[38:41], v[70:73]
	v_mfma_f32_16x16x32_bf16 v[74:77], v[6:9], v[46:49], v[74:77]
	v_mfma_f32_16x16x32_bf16 v[78:81], v[14:17], v[46:49], v[78:81]
	v_mfma_f32_16x16x32_bf16 v[82:85], v[6:9], v[54:57], v[82:85]
	v_mfma_f32_16x16x32_bf16 v[86:89], v[14:17], v[54:57], v[86:89]
	v_mfma_f32_16x16x32_bf16 v[104:107], v[14:17], v[62:65], v[90:93]
	v_mfma_f32_16x16x32_bf16 v[90:93], v[18:21], v[34:37], 0
	v_mfma_f32_16x16x32_bf16 v[34:37], v[26:29], v[34:37], 0
	v_mfma_f32_16x16x32_bf16 v[112:115], v[22:25], v[38:41], v[90:93]
	v_mfma_f32_16x16x32_bf16 v[34:37], v[30:33], v[38:41], v[34:37]
	v_mfma_f32_16x16x32_bf16 v[38:41], v[18:21], v[42:45], 0
	v_mfma_f32_16x16x32_bf16 v[42:45], v[26:29], v[42:45], 0
	v_mfma_f32_16x16x32_bf16 v[38:41], v[22:25], v[46:49], v[38:41]
	v_mfma_f32_16x16x32_bf16 v[42:45], v[30:33], v[46:49], v[42:45]
	v_mfma_f32_16x16x32_bf16 v[46:49], v[18:21], v[50:53], 0
	v_mfma_f32_16x16x32_bf16 v[50:53], v[26:29], v[50:53], 0
	v_mfma_f32_16x16x32_bf16 v[46:49], v[22:25], v[54:57], v[46:49]
	v_mfma_f32_16x16x32_bf16 v[50:53], v[30:33], v[54:57], v[50:53]
	v_mfma_f32_16x16x32_bf16 v[54:57], v[18:21], v[58:61], 0
	v_mfma_f32_16x16x32_bf16 v[54:57], v[22:25], v[62:65], v[54:57]
	v_mfma_f32_16x16x32_bf16 v[58:61], v[26:29], v[58:61], 0
	v_mfma_f32_16x16x32_bf16 v[154:157], v[30:33], v[62:65], v[58:61]
	s_barrier
	s_setprio 1
	s_mov_b32 m0, s61
	s_nop 3
	ds_read_b128 v[58:61], v149 offset:16384
	ds_read_b128 v[62:65], v149 offset:17408
	ds_read_b128 v[90:93], v149 offset:18432
	ds_read_b128 v[100:103], v149 offset:19456
	ds_read_b128 v[108:111], v149 offset:20480
	ds_read_b128 v[116:119], v149 offset:21504
	ds_read_b128 v[120:123], v149 offset:22528
	ds_read_b128 v[124:127], v149 offset:23552
	s_nop 0
	global_load_lds_dwordx4 v136, s[6:7]
	s_mov_b64 s[98:99], s[6:7]
	s_add_u32 s6, s26, 0x40100
	s_mov_b32 m0, s21
	s_addc_u32 s7, s27, 0
	global_load_lds_dwordx4 v132, s[98:99]
	s_mov_b32 m0, s23
	s_nop 0
	global_load_lds_dwordx4 v136, s[6:7]
	s_mov_b32 m0, s60
	s_nop 0
	global_load_lds_dwordx4 v132, s[6:7]
	s_mov_b32 m0, s72
	s_nop 0
	global_load_lds_dwordx4 v138, s[28:29]
	s_mov_b32 m0, s73
	s_nop 0
	global_load_lds_dwordx4 v134, s[28:29]
	s_setprio 0
	s_waitcnt vmcnt(18)
	s_waitcnt lgkmcnt(0)
	s_barrier
	s_waitcnt lgkmcnt(0)
	v_mfma_f32_16x16x32_bf16 v[128:131], v[2:5], v[58:61], 0
	v_mfma_f32_16x16x32_bf16 v[158:161], v[6:9], v[62:65], v[128:131]
	v_mfma_f32_16x16x32_bf16 v[128:131], v[10:13], v[58:61], 0
	v_mfma_f32_16x16x32_bf16 v[162:165], v[14:17], v[62:65], v[128:131]
	v_mfma_f32_16x16x32_bf16 v[128:131], v[2:5], v[90:93], 0
	v_mfma_f32_16x16x32_bf16 v[166:169], v[6:9], v[100:103], v[128:131]
	v_mfma_f32_16x16x32_bf16 v[128:131], v[10:13], v[90:93], 0
	v_mfma_f32_16x16x32_bf16 v[170:173], v[14:17], v[100:103], v[128:131]
	v_mfma_f32_16x16x32_bf16 v[128:131], v[2:5], v[108:111], 0
	v_mfma_f32_16x16x32_bf16 v[2:5], v[2:5], v[120:123], 0
	v_mfma_f32_16x16x32_bf16 v[176:179], v[6:9], v[116:119], v[128:131]
	v_mfma_f32_16x16x32_bf16 v[2:5], v[6:9], v[124:127], v[2:5]
	v_mfma_f32_16x16x32_bf16 v[6:9], v[10:13], v[120:123], 0
	v_mfma_f32_16x16x32_bf16 v[128:131], v[10:13], v[108:111], 0
	v_mfma_f32_16x16x32_bf16 v[6:9], v[14:17], v[124:127], v[6:9]
	v_mfma_f32_16x16x32_bf16 v[180:183], v[14:17], v[116:119], v[128:131]
	v_mfma_f32_16x16x32_bf16 v[10:13], v[18:21], v[58:61], 0
	v_mfma_f32_16x16x32_bf16 v[184:187], v[22:25], v[62:65], v[10:13]
	v_mfma_f32_16x16x32_bf16 v[10:13], v[26:29], v[58:61], 0
	v_mfma_f32_16x16x32_bf16 v[188:191], v[30:33], v[62:65], v[10:13]
	v_mfma_f32_16x16x32_bf16 v[10:13], v[18:21], v[90:93], 0
	v_mfma_f32_16x16x32_bf16 v[192:195], v[22:25], v[100:103], v[10:13]
	v_mfma_f32_16x16x32_bf16 v[10:13], v[26:29], v[90:93], 0
	v_mfma_f32_16x16x32_bf16 v[196:199], v[30:33], v[100:103], v[10:13]
	v_mfma_f32_16x16x32_bf16 v[10:13], v[18:21], v[108:111], 0
	v_mfma_f32_16x16x32_bf16 v[200:203], v[22:25], v[116:119], v[10:13]
	v_mfma_f32_16x16x32_bf16 v[10:13], v[26:29], v[108:111], 0
	v_mfma_f32_16x16x32_bf16 v[204:207], v[30:33], v[116:119], v[10:13]
	v_mfma_f32_16x16x32_bf16 v[10:13], v[18:21], v[120:123], 0
	v_mfma_f32_16x16x32_bf16 v[16:19], v[22:25], v[124:127], v[10:13]
	v_mfma_f32_16x16x32_bf16 v[10:13], v[26:29], v[120:123], 0
	v_mfma_f32_16x16x32_bf16 v[208:211], v[30:33], v[124:127], v[10:13]
	s_barrier
; #define PG8_WAIT_V8_RELAX() do { if constexpr (Epi::NSTORES + Epi::NPRE == 10) asm volatile("s_waitcnt vmcnt(18)" ::: "memory"); else if constexpr (Epi::NSTORES + Epi::NPRE == 18) asm volatile("s_waitcnt vmcnt(26)" ::: "memory"); else asm volatile("s_waitcnt vmcnt(8)" ::: "memory"); } while (0)
; template <class Epi, class Sched, bool ALIGN_EPI = false, bool SP2 = false>
; __device__ __forceinline__ void gemm_phase(PG8_LAS unsigned char* lds, const Gemm g, const Sched& S, const Epi& E, int wave_s) {
;     ...
;         if constexpr (SP2 && Epi::NSTORES > 0 && !Epi::AFTER_DRAIN) {
;             const char* a1 = cA + kstep; const char* a2 = cA + 2 * kstep; const char* b2 = cB + 2 * kstep; const char* a3 = a2 + kstep; const char* b3 = b2 + kstep;
;             PG8_SP2_PAIR(PG8_WAIT_V8_RELAX);
;             peeled = true;
	s_nop 4
	ds_read_b128 v[10:13], v152
	ds_read_b128 v[24:27], v152 offset:1024
	ds_read_b128 v[212:215], v152 offset:2048
	ds_read_b128 v[216:219], v152 offset:3072
	ds_read_b128 v[220:223], v153
	ds_read_b128 v[224:227], v153 offset:1024
	ds_read_b128 v[228:231], v153 offset:2048
	ds_read_b128 v[150:153], v153 offset:3072
	s_add_u32 s6, s24, 0x40100
	s_addc_u32 s7, s25, 0
	s_mov_b32 m0, s74
	ds_read_b128 v[20:23], v149 offset:32768
	ds_read_b128 v[28:31], v149 offset:33792
	ds_read_b128 v[232:235], v149 offset:34816
	ds_read_b128 v[236:239], v149 offset:35840
	ds_read_b128 v[240:243], v149 offset:36864
	ds_read_b128 v[244:247], v149 offset:37888
	ds_read_b128 v[248:251], v149 offset:38912
	ds_read_b128 v[140:143], v149 offset:39936
	s_nop 0
	global_load_lds_dwordx4 v138, s[6:7]
	s_mov_b32 m0, s75
	s_nop 0
	global_load_lds_dwordx4 v134, s[6:7]
	s_waitcnt vmcnt(18)
	s_waitcnt lgkmcnt(0)
	s_barrier
	s_waitcnt lgkmcnt(0)
	v_mfma_f32_16x16x32_bf16 v[58:61], v[10:13], v[20:23], v[66:69]
	v_mfma_f32_16x16x32_bf16 v[124:127], v[24:27], v[28:31], v[58:61]
	v_mfma_f32_16x16x32_bf16 v[58:61], v[212:215], v[20:23], v[70:73]
	v_mfma_f32_16x16x32_bf16 v[116:119], v[216:219], v[28:31], v[58:61]
	v_mfma_f32_16x16x32_bf16 v[58:61], v[10:13], v[232:235], v[74:77]
	v_mfma_f32_16x16x32_bf16 v[108:111], v[24:27], v[236:239], v[58:61]
	v_mfma_f32_16x16x32_bf16 v[58:61], v[212:215], v[232:235], v[78:81]
	v_mfma_f32_16x16x32_bf16 v[100:103], v[216:219], v[236:239], v[58:61]
	v_mfma_f32_16x16x32_bf16 v[58:61], v[10:13], v[240:243], v[82:85]
	v_mfma_f32_16x16x32_bf16 v[92:95], v[24:27], v[244:247], v[58:61]
	v_mfma_f32_16x16x32_bf16 v[58:61], v[212:215], v[240:243], v[86:89]
	v_mfma_f32_16x16x32_bf16 v[84:87], v[216:219], v[244:247], v[58:61]
	v_mfma_f32_16x16x32_bf16 v[58:61], v[10:13], v[248:251], v[96:99]
	v_mfma_f32_16x16x32_bf16 v[76:79], v[24:27], v[140:143], v[58:61]
	v_mfma_f32_16x16x32_bf16 v[58:61], v[212:215], v[248:251], v[104:107]
	v_mfma_f32_16x16x32_bf16 v[60:63], v[216:219], v[140:143], v[58:61]
	v_mfma_f32_16x16x32_bf16 v[64:67], v[220:223], v[20:23], v[112:115]
	v_mfma_f32_16x16x32_bf16 v[20:23], v[228:231], v[20:23], v[34:37]
	v_mfma_f32_16x16x32_bf16 v[120:123], v[150:153], v[28:31], v[20:23]
	v_mfma_f32_16x16x32_bf16 v[20:23], v[220:223], v[232:235], v[38:41]
	v_mfma_f32_16x16x32_bf16 v[112:115], v[224:227], v[236:239], v[20:23]
	v_mfma_f32_16x16x32_bf16 v[20:23], v[228:231], v[232:235], v[42:45]
	v_mfma_f32_16x16x32_bf16 v[104:107], v[150:153], v[236:239], v[20:23]
	v_mfma_f32_16x16x32_bf16 v[20:23], v[220:223], v[240:243], v[46:49]
	v_mfma_f32_16x16x32_bf16 v[96:99], v[224:227], v[244:247], v[20:23]
	v_mfma_f32_16x16x32_bf16 v[20:23], v[228:231], v[240:243], v[50:53]
	v_mfma_f32_16x16x32_bf16 v[88:91], v[150:153], v[244:247], v[20:23]
	v_mfma_f32_16x16x32_bf16 v[20:23], v[220:223], v[248:251], v[54:57]
	v_mfma_f32_16x16x32_bf16 v[80:83], v[224:227], v[140:143], v[20:23]
	v_mfma_f32_16x16x32_bf16 v[20:23], v[228:231], v[248:251], v[154:157]
	v_mfma_f32_16x16x32_bf16 v[128:131], v[224:227], v[28:31], v[64:67]
	v_mfma_f32_16x16x32_bf16 v[68:71], v[150:153], v[140:143], v[20:23]
	s_barrier
	s_setprio 1
	s_add_u32 s6, s26, 0x180
	s_addc_u32 s7, s27, 0
	s_mov_b32 m0, s39
	ds_read_b128 v[32:35], v149 offset:49152
	ds_read_b128 v[40:43], v149 offset:50176
	ds_read_b128 v[140:143], v149 offset:51200
	ds_read_b128 v[154:157], v149 offset:52224
	ds_read_b128 v[232:235], v149 offset:53248
	ds_read_b128 v[236:239], v149 offset:54272
	ds_read_b128 v[240:243], v149 offset:55296
	ds_read_b128 v[244:247], v149 offset:56320
	s_nop 0
	global_load_lds_dwordx4 v136, s[6:7]
	s_mov_b64 s[98:99], s[6:7]
	s_add_u32 s6, s26, 0x40180
	s_mov_b32 m0, s38
	s_addc_u32 s7, s27, 0
	global_load_lds_dwordx4 v132, s[98:99]
	s_mov_b32 m0, s36
	s_nop 0
	global_load_lds_dwordx4 v136, s[6:7]
	s_mov_b32 m0, s37
	s_nop 0
	global_load_lds_dwordx4 v132, s[6:7]
	s_mov_b32 m0, s76
	s_nop 0
	global_load_lds_dwordx4 v138, s[8:9]
	s_mov_b32 m0, s77
	s_nop 0
	global_load_lds_dwordx4 v134, s[8:9]
	s_setprio 0
	s_waitcnt vmcnt(18)
	s_waitcnt lgkmcnt(0)
	s_barrier
	s_waitcnt lgkmcnt(0)
	v_mfma_f32_16x16x32_bf16 v[20:23], v[10:13], v[32:35], v[158:161]
	v_mfma_f32_16x16x32_bf16 v[64:67], v[24:27], v[40:43], v[20:23]
	v_mfma_f32_16x16x32_bf16 v[20:23], v[212:215], v[32:35], v[162:165]
	v_mfma_f32_16x16x32_bf16 v[52:55], v[216:219], v[40:43], v[20:23]
	v_mfma_f32_16x16x32_bf16 v[20:23], v[10:13], v[140:143], v[166:169]
	v_mfma_f32_16x16x32_bf16 v[44:47], v[24:27], v[154:157], v[20:23]
	v_mfma_f32_16x16x32_bf16 v[20:23], v[212:215], v[140:143], v[170:173]
	v_mfma_f32_16x16x32_bf16 v[36:39], v[216:219], v[154:157], v[20:23]
	v_mfma_f32_16x16x32_bf16 v[20:23], v[10:13], v[232:235], v[176:179]
	v_mfma_f32_16x16x32_bf16 v[2:5], v[10:13], v[240:243], v[2:5]
	v_mfma_f32_16x16x32_bf16 v[28:31], v[24:27], v[236:239], v[20:23]
	v_mfma_f32_16x16x32_bf16 v[20:23], v[212:215], v[232:235], v[180:183]
	v_mfma_f32_16x16x32_bf16 v[12:15], v[24:27], v[244:247], v[2:5]
	v_mfma_f32_16x16x32_bf16 v[2:5], v[212:215], v[240:243], v[6:9]
	v_mfma_f32_16x16x32_bf16 v[20:23], v[216:219], v[236:239], v[20:23]
	v_mfma_f32_16x16x32_bf16 v[4:7], v[216:219], v[244:247], v[2:5]
	v_mfma_f32_16x16x32_bf16 v[8:11], v[220:223], v[32:35], v[184:187]
	v_mfma_f32_16x16x32_bf16 v[72:75], v[224:227], v[40:43], v[8:11]
	v_mfma_f32_16x16x32_bf16 v[8:11], v[228:231], v[32:35], v[188:191]
	v_mfma_f32_16x16x32_bf16 v[56:59], v[150:153], v[40:43], v[8:11]
	v_mfma_f32_16x16x32_bf16 v[8:11], v[220:223], v[140:143], v[192:195]
	v_mfma_f32_16x16x32_bf16 v[48:51], v[224:227], v[154:157], v[8:11]
	v_mfma_f32_16x16x32_bf16 v[8:11], v[228:231], v[140:143], v[196:199]
	v_mfma_f32_16x16x32_bf16 v[40:43], v[150:153], v[154:157], v[8:11]
	v_mfma_f32_16x16x32_bf16 v[8:11], v[220:223], v[232:235], v[200:203]
	v_mfma_f32_16x16x32_bf16 v[32:35], v[224:227], v[236:239], v[8:11]
	v_mfma_f32_16x16x32_bf16 v[8:11], v[228:231], v[232:235], v[204:207]
	v_mfma_f32_16x16x32_bf16 v[24:27], v[150:153], v[236:239], v[8:11]
	v_mfma_f32_16x16x32_bf16 v[8:11], v[220:223], v[240:243], v[16:19]
	v_mfma_f32_16x16x32_bf16 v[16:19], v[224:227], v[244:247], v[8:11]
	v_mfma_f32_16x16x32_bf16 v[8:11], v[228:231], v[240:243], v[208:211]
	v_mfma_f32_16x16x32_bf16 v[8:11], v[150:153], v[244:247], v[8:11]
	s_barrier
	s_mov_b64 s[8:9], 0

; template <class Epi, class Sched, bool ALIGN_EPI = false, bool SP2 = false>
; __device__ __forceinline__ void gemm_phase(PG8_LAS unsigned char* lds, const Gemm g, const Sched& S, const Epi& E, int wave_s) {
;     ...
;         for (int t = peeled ? 2 : 0; t < nt; t += 2) {
;             const bool last = (t == nt - 2);
;             const char* a1 = cA + (size_t)(t + 1) * kstep;
;             const char* a2 = last ? nA : cA + (size_t)(t + 2) * kstep; const char* b2 = last ? nB : cB + (size_t)(t + 2) * kstep;
;             const char* a3 = a2 + kstep; const char* b3 = b2 + kstep;
;             if (last && has_next) S.a_ready(nxt);
.LBB0_912:
	v_add_u32_e32 v151, s82, v146
	v_add_u32_e32 v150, s87, v146
	ds_read_b128 v[152:155], v151
	ds_read_b128 v[156:159], v151 offset:1024
	ds_read_b128 v[160:163], v151 offset:2048
	ds_read_b128 v[164:167], v151 offset:3072
	ds_read_b128 v[168:171], v150
	ds_read_b128 v[176:179], v150 offset:1024
	ds_read_b128 v[180:183], v150 offset:2048
	ds_read_b128 v[184:187], v150 offset:3072
	s_add_u32 s30, s40, 0x100
	s_addc_u32 s31, s41, 0
	s_cmp_eq_u32 s95, 12
	s_cselect_b32 s38, s92, s30
	s_cselect_b32 s39, s91, s31
	s_cselect_b32 s36, s94, s96
	s_cselect_b32 s37, s93, s6
	s_add_u32 s34, s38, 0x80
	s_addc_u32 s35, s39, 0
	s_add_u32 s40, s40, 0x40080
	s_addc_u32 s41, s41, 0
	s_add_i32 s90, s72, 0xc000
	ds_read_b128 v[188:191], v149
	ds_read_b128 v[192:195], v149 offset:1024
	ds_read_b128 v[196:199], v149 offset:2048
	ds_read_b128 v[200:203], v149 offset:3072
	ds_read_b128 v[204:207], v149 offset:4096
	ds_read_b128 v[208:211], v149 offset:5120
	ds_read_b128 v[212:215], v149 offset:6144
	ds_read_b128 v[216:219], v149 offset:7168
	s_mov_b32 m0, s90
	s_add_i32 s10, s72, 0xe000
	global_load_lds_dwordx4 v138, s[40:41]
	s_mov_b32 m0, s10
	s_nop 0
	global_load_lds_dwordx4 v134, s[40:41]
	s_waitcnt vmcnt(8)
	s_waitcnt lgkmcnt(0)
	s_barrier
	s_waitcnt lgkmcnt(0)
	v_mfma_f32_16x16x32_bf16 v[124:127], v[152:155], v[188:191], v[124:127]
	v_mfma_f32_16x16x32_bf16 v[116:119], v[160:163], v[188:191], v[116:119]
	v_mfma_f32_16x16x32_bf16 v[108:111], v[152:155], v[196:199], v[108:111]
	v_mfma_f32_16x16x32_bf16 v[100:103], v[160:163], v[196:199], v[100:103]
	v_mfma_f32_16x16x32_bf16 v[92:95], v[152:155], v[204:207], v[92:95]
	v_mfma_f32_16x16x32_bf16 v[84:87], v[160:163], v[204:207], v[84:87]
	v_mfma_f32_16x16x32_bf16 v[76:79], v[152:155], v[212:215], v[76:79]
	v_mfma_f32_16x16x32_bf16 v[60:63], v[160:163], v[212:215], v[60:63]
	v_mfma_f32_16x16x32_bf16 v[124:127], v[156:159], v[192:195], v[124:127]
	v_mfma_f32_16x16x32_bf16 v[116:119], v[164:167], v[192:195], v[116:119]
	v_mfma_f32_16x16x32_bf16 v[108:111], v[156:159], v[200:203], v[108:111]
	v_mfma_f32_16x16x32_bf16 v[100:103], v[164:167], v[200:203], v[100:103]
	v_mfma_f32_16x16x32_bf16 v[92:95], v[156:159], v[208:211], v[92:95]
	v_mfma_f32_16x16x32_bf16 v[84:87], v[164:167], v[208:211], v[84:87]
	v_mfma_f32_16x16x32_bf16 v[76:79], v[156:159], v[216:219], v[76:79]
	v_mfma_f32_16x16x32_bf16 v[60:63], v[164:167], v[216:219], v[60:63]
	v_mfma_f32_16x16x32_bf16 v[128:131], v[168:171], v[188:191], v[128:131]
	v_mfma_f32_16x16x32_bf16 v[120:123], v[180:183], v[188:191], v[120:123]
	v_mfma_f32_16x16x32_bf16 v[112:115], v[168:171], v[196:199], v[112:115]
	v_mfma_f32_16x16x32_bf16 v[104:107], v[180:183], v[196:199], v[104:107]
	v_mfma_f32_16x16x32_bf16 v[96:99], v[168:171], v[204:207], v[96:99]
	v_mfma_f32_16x16x32_bf16 v[88:91], v[180:183], v[204:207], v[88:91]
	v_mfma_f32_16x16x32_bf16 v[80:83], v[168:171], v[212:215], v[80:83]
	v_mfma_f32_16x16x32_bf16 v[68:71], v[180:183], v[212:215], v[68:71]
	v_mfma_f32_16x16x32_bf16 v[128:131], v[176:179], v[192:195], v[128:131]
	v_mfma_f32_16x16x32_bf16 v[120:123], v[184:187], v[192:195], v[120:123]
	v_mfma_f32_16x16x32_bf16 v[112:115], v[176:179], v[200:203], v[112:115]
	v_mfma_f32_16x16x32_bf16 v[104:107], v[184:187], v[200:203], v[104:107]
	v_mfma_f32_16x16x32_bf16 v[96:99], v[176:179], v[208:211], v[96:99]
	v_mfma_f32_16x16x32_bf16 v[88:91], v[184:187], v[208:211], v[88:91]
	v_mfma_f32_16x16x32_bf16 v[80:83], v[176:179], v[216:219], v[80:83]
	v_mfma_f32_16x16x32_bf16 v[68:71], v[184:187], v[216:219], v[68:71]
	s_barrier
	s_setprio 1
	s_mov_b64 s[40:41], s[36:37]
	s_add_i32 s61, s82, s42
	ds_read_b128 v[188:191], v149 offset:16384
	ds_read_b128 v[192:195], v149 offset:17408
	ds_read_b128 v[196:199], v149 offset:18432
	ds_read_b128 v[200:203], v149 offset:19456
	ds_read_b128 v[204:207], v149 offset:20480
	ds_read_b128 v[208:211], v149 offset:21504
	ds_read_b128 v[212:215], v149 offset:22528
	ds_read_b128 v[216:219], v149 offset:23552
	s_mov_b32 m0, s61
	s_add_i32 s21, s61, 0x2000
	global_load_lds_dwordx4 v136, s[40:41]
	s_mov_b64 s[98:99], s[40:41]
	s_add_u32 s40, s36, 0x40000
	s_mov_b32 m0, s21
	s_addc_u32 s41, s37, 0
	s_add_i32 s23, s87, s42
	global_load_lds_dwordx4 v132, s[98:99]
	s_mov_b32 m0, s23
	s_add_i32 s60, s23, 0x2000
	global_load_lds_dwordx4 v136, s[40:41]
	s_mov_b64 s[98:99], s[40:41]
	s_mov_b32 m0, s60
	s_mov_b64 s[40:41], s[38:39]
	global_load_lds_dwordx4 v132, s[98:99]
	s_mov_b32 m0, s72
	s_nop 0
	global_load_lds_dwordx4 v138, s[40:41]
	s_mov_b32 m0, s73
	s_nop 0
	global_load_lds_dwordx4 v134, s[40:41]
	s_setprio 0
	s_waitcnt vmcnt(8)
	s_waitcnt lgkmcnt(0)
	s_barrier
	s_waitcnt lgkmcnt(0)
	v_mfma_f32_16x16x32_bf16 v[64:67], v[152:155], v[188:191], v[64:67]
	v_mfma_f32_16x16x32_bf16 v[52:55], v[160:163], v[188:191], v[52:55]
	v_mfma_f32_16x16x32_bf16 v[44:47], v[152:155], v[196:199], v[44:47]
	v_mfma_f32_16x16x32_bf16 v[36:39], v[160:163], v[196:199], v[36:39]
	v_mfma_f32_16x16x32_bf16 v[28:31], v[152:155], v[204:207], v[28:31]
	v_mfma_f32_16x16x32_bf16 v[20:23], v[160:163], v[204:207], v[20:23]
	v_mfma_f32_16x16x32_bf16 v[12:15], v[152:155], v[212:215], v[12:15]
	v_mfma_f32_16x16x32_bf16 v[2:5], v[160:163], v[212:215], v[4:7]
	v_mfma_f32_16x16x32_bf16 v[64:67], v[156:159], v[192:195], v[64:67]
	v_mfma_f32_16x16x32_bf16 v[52:55], v[164:167], v[192:195], v[52:55]
	v_mfma_f32_16x16x32_bf16 v[44:47], v[156:159], v[200:203], v[44:47]
	v_mfma_f32_16x16x32_bf16 v[36:39], v[164:167], v[200:203], v[36:39]
	v_mfma_f32_16x16x32_bf16 v[28:31], v[156:159], v[208:211], v[28:31]
	v_mfma_f32_16x16x32_bf16 v[20:23], v[164:167], v[208:211], v[20:23]
	v_mfma_f32_16x16x32_bf16 v[12:15], v[156:159], v[216:219], v[12:15]
	v_mfma_f32_16x16x32_bf16 v[2:5], v[164:167], v[216:219], v[2:5]
	v_mfma_f32_16x16x32_bf16 v[72:75], v[168:171], v[188:191], v[72:75]
	v_mfma_f32_16x16x32_bf16 v[56:59], v[180:183], v[188:191], v[56:59]
	v_mfma_f32_16x16x32_bf16 v[48:51], v[168:171], v[196:199], v[48:51]
	v_mfma_f32_16x16x32_bf16 v[40:43], v[180:183], v[196:199], v[40:43]
	v_mfma_f32_16x16x32_bf16 v[32:35], v[168:171], v[204:207], v[32:35]
	v_mfma_f32_16x16x32_bf16 v[24:27], v[180:183], v[204:207], v[24:27]
	v_mfma_f32_16x16x32_bf16 v[16:19], v[168:171], v[212:215], v[16:19]
	v_mfma_f32_16x16x32_bf16 v[6:9], v[180:183], v[212:215], v[8:11]
	v_mfma_f32_16x16x32_bf16 v[72:75], v[176:179], v[192:195], v[72:75]
	v_mfma_f32_16x16x32_bf16 v[56:59], v[184:187], v[192:195], v[56:59]
	v_mfma_f32_16x16x32_bf16 v[48:51], v[176:179], v[200:203], v[48:51]
	v_mfma_f32_16x16x32_bf16 v[40:43], v[184:187], v[200:203], v[40:43]
	v_mfma_f32_16x16x32_bf16 v[32:35], v[176:179], v[208:211], v[32:35]
	v_mfma_f32_16x16x32_bf16 v[24:27], v[184:187], v[208:211], v[24:27]
	v_mfma_f32_16x16x32_bf16 v[16:19], v[176:179], v[216:219], v[16:19]
	v_mfma_f32_16x16x32_bf16 v[8:11], v[184:187], v[216:219], v[6:9]
	s_barrier
	s_add_i32 s7, 0, 0x18000
	s_add_i32 s86, 0, 0x1c000
	v_add_u32_e32 v152, s7, v146
	v_add_u32_e32 v153, s86, v146
	ds_read_b128 v[154:157], v152
	ds_read_b128 v[158:161], v152 offset:1024
	ds_read_b128 v[162:165], v152 offset:2048
	ds_read_b128 v[166:169], v152 offset:3072
	ds_read_b128 v[170:173], v153
	ds_read_b128 v[176:179], v153 offset:1024
	ds_read_b128 v[180:183], v153 offset:2048
	ds_read_b128 v[184:187], v153 offset:3072
	s_add_u32 s38, s38, 0x40000
	s_addc_u32 s39, s39, 0
	s_mov_b32 m0, s74
	ds_read_b128 v[188:191], v149 offset:32768
	ds_read_b128 v[192:195], v149 offset:33792
	ds_read_b128 v[196:199], v149 offset:34816
	ds_read_b128 v[200:203], v149 offset:35840
	ds_read_b128 v[204:207], v149 offset:36864
	ds_read_b128 v[208:211], v149 offset:37888
	ds_read_b128 v[212:215], v149 offset:38912
	ds_read_b128 v[216:219], v149 offset:39936
	s_nop 0
	global_load_lds_dwordx4 v138, s[38:39]
	s_mov_b32 m0, s75
	s_nop 0
	global_load_lds_dwordx4 v134, s[38:39]
	s_waitcnt vmcnt(8)
	s_waitcnt lgkmcnt(0)
	s_barrier
	s_waitcnt lgkmcnt(0)
	v_mfma_f32_16x16x32_bf16 v[124:127], v[154:157], v[188:191], v[124:127]
	v_mfma_f32_16x16x32_bf16 v[116:119], v[162:165], v[188:191], v[116:119]
	v_mfma_f32_16x16x32_bf16 v[108:111], v[154:157], v[196:199], v[108:111]
	v_mfma_f32_16x16x32_bf16 v[100:103], v[162:165], v[196:199], v[100:103]
	v_mfma_f32_16x16x32_bf16 v[92:95], v[154:157], v[204:207], v[92:95]
	v_mfma_f32_16x16x32_bf16 v[84:87], v[162:165], v[204:207], v[84:87]
	v_mfma_f32_16x16x32_bf16 v[76:79], v[154:157], v[212:215], v[76:79]
	v_mfma_f32_16x16x32_bf16 v[60:63], v[162:165], v[212:215], v[60:63]
	v_mfma_f32_16x16x32_bf16 v[124:127], v[158:161], v[192:195], v[124:127]
	v_mfma_f32_16x16x32_bf16 v[116:119], v[166:169], v[192:195], v[116:119]
	v_mfma_f32_16x16x32_bf16 v[108:111], v[158:161], v[200:203], v[108:111]
	v_mfma_f32_16x16x32_bf16 v[100:103], v[166:169], v[200:203], v[100:103]
	v_mfma_f32_16x16x32_bf16 v[92:95], v[158:161], v[208:211], v[92:95]
	v_mfma_f32_16x16x32_bf16 v[84:87], v[166:169], v[208:211], v[84:87]
	v_mfma_f32_16x16x32_bf16 v[76:79], v[158:161], v[216:219], v[76:79]
	v_mfma_f32_16x16x32_bf16 v[60:63], v[166:169], v[216:219], v[60:63]
	v_mfma_f32_16x16x32_bf16 v[128:131], v[170:173], v[188:191], v[128:131]
	v_mfma_f32_16x16x32_bf16 v[120:123], v[180:183], v[188:191], v[120:123]
	v_mfma_f32_16x16x32_bf16 v[112:115], v[170:173], v[196:199], v[112:115]
	v_mfma_f32_16x16x32_bf16 v[104:107], v[180:183], v[196:199], v[104:107]
	v_mfma_f32_16x16x32_bf16 v[96:99], v[170:173], v[204:207], v[96:99]
	v_mfma_f32_16x16x32_bf16 v[88:91], v[180:183], v[204:207], v[88:91]
	v_mfma_f32_16x16x32_bf16 v[80:83], v[170:173], v[212:215], v[80:83]
	v_mfma_f32_16x16x32_bf16 v[68:71], v[180:183], v[212:215], v[68:71]
	v_mfma_f32_16x16x32_bf16 v[128:131], v[176:179], v[192:195], v[128:131]
	v_mfma_f32_16x16x32_bf16 v[120:123], v[184:187], v[192:195], v[120:123]
	v_mfma_f32_16x16x32_bf16 v[112:115], v[176:179], v[200:203], v[112:115]
	v_mfma_f32_16x16x32_bf16 v[104:107], v[184:187], v[200:203], v[104:107]
	v_mfma_f32_16x16x32_bf16 v[96:99], v[176:179], v[208:211], v[96:99]
	v_mfma_f32_16x16x32_bf16 v[88:91], v[184:187], v[208:211], v[88:91]
	v_mfma_f32_16x16x32_bf16 v[80:83], v[176:179], v[216:219], v[80:83]
	v_mfma_f32_16x16x32_bf16 v[68:71], v[184:187], v[216:219], v[68:71]
	s_barrier
; #define PG8_BAR __builtin_amdgcn_s_barrier()
; template <class Epi, class Sched, bool ALIGN_EPI = false, bool SP2 = false>
; __device__ __forceinline__ void gemm_phase(PG8_LAS unsigned char* lds, const Gemm g, const Sched& S, const Epi& E, int wave_s) {
;     ...
;         }
;         if constexpr (ALIGN_EPI) { if (wr == 0) PG8_BAR; }
	s_setprio 1
	s_add_u32 s40, s36, 0x80
	s_addc_u32 s41, s37, 0
	s_add_i32 s39, s7, s42
	ds_read_b128 v[188:191], v149 offset:49152
	ds_read_b128 v[192:195], v149 offset:50176
	ds_read_b128 v[196:199], v149 offset:51200
	ds_read_b128 v[200:203], v149 offset:52224
	ds_read_b128 v[204:207], v149 offset:53248
	ds_read_b128 v[208:211], v149 offset:54272
	ds_read_b128 v[212:215], v149 offset:55296
	ds_read_b128 v[216:219], v149 offset:56320
	s_mov_b32 m0, s39
	s_add_i32 s38, s39, 0x2000
	global_load_lds_dwordx4 v136, s[40:41]
	s_mov_b64 s[98:99], s[40:41]
	s_add_u32 s40, s36, 0x40080
	s_mov_b32 m0, s38
	s_addc_u32 s41, s37, 0
	s_add_i32 s36, s86, s42
	global_load_lds_dwordx4 v132, s[98:99]
	s_mov_b32 m0, s36
	s_add_i32 s37, s36, 0x2000
	global_load_lds_dwordx4 v136, s[40:41]
	s_mov_b32 m0, s37
	s_nop 0
	global_load_lds_dwordx4 v132, s[40:41]
	s_mov_b32 m0, s76
	s_nop 0
	global_load_lds_dwordx4 v138, s[34:35]
	s_mov_b32 m0, s77
	s_nop 0
	global_load_lds_dwordx4 v134, s[34:35]
	s_setprio 0
	s_waitcnt vmcnt(8)
	s_waitcnt lgkmcnt(0)
	s_barrier
	s_waitcnt lgkmcnt(0)
	v_mfma_f32_16x16x32_bf16 v[64:67], v[154:157], v[188:191], v[64:67]
	v_mfma_f32_16x16x32_bf16 v[52:55], v[162:165], v[188:191], v[52:55]
	v_mfma_f32_16x16x32_bf16 v[44:47], v[154:157], v[196:199], v[44:47]
	v_mfma_f32_16x16x32_bf16 v[36:39], v[162:165], v[196:199], v[36:39]
	v_mfma_f32_16x16x32_bf16 v[28:31], v[154:157], v[204:207], v[28:31]
	v_mfma_f32_16x16x32_bf16 v[20:23], v[162:165], v[204:207], v[20:23]
	v_mfma_f32_16x16x32_bf16 v[12:15], v[154:157], v[212:215], v[12:15]
	v_mfma_f32_16x16x32_bf16 v[2:5], v[162:165], v[212:215], v[2:5]
	v_mfma_f32_16x16x32_bf16 v[64:67], v[158:161], v[192:195], v[64:67]
	v_mfma_f32_16x16x32_bf16 v[52:55], v[166:169], v[192:195], v[52:55]
	v_mfma_f32_16x16x32_bf16 v[44:47], v[158:161], v[200:203], v[44:47]
	v_mfma_f32_16x16x32_bf16 v[36:39], v[166:169], v[200:203], v[36:39]
	v_mfma_f32_16x16x32_bf16 v[28:31], v[158:161], v[208:211], v[28:31]
	v_mfma_f32_16x16x32_bf16 v[20:23], v[166:169], v[208:211], v[20:23]
	v_mfma_f32_16x16x32_bf16 v[12:15], v[158:161], v[216:219], v[12:15]
	v_mfma_f32_16x16x32_bf16 v[4:7], v[166:169], v[216:219], v[2:5]
	v_mfma_f32_16x16x32_bf16 v[72:75], v[170:173], v[188:191], v[72:75]
	v_mfma_f32_16x16x32_bf16 v[56:59], v[180:183], v[188:191], v[56:59]
	v_mfma_f32_16x16x32_bf16 v[48:51], v[170:173], v[196:199], v[48:51]
	v_mfma_f32_16x16x32_bf16 v[40:43], v[180:183], v[196:199], v[40:43]
	v_mfma_f32_16x16x32_bf16 v[32:35], v[170:173], v[204:207], v[32:35]
	v_mfma_f32_16x16x32_bf16 v[24:27], v[180:183], v[204:207], v[24:27]
	v_mfma_f32_16x16x32_bf16 v[16:19], v[170:173], v[212:215], v[16:19]
	v_mfma_f32_16x16x32_bf16 v[8:11], v[180:183], v[212:215], v[8:11]
	v_mfma_f32_16x16x32_bf16 v[72:75], v[176:179], v[192:195], v[72:75]
	v_mfma_f32_16x16x32_bf16 v[56:59], v[184:187], v[192:195], v[56:59]
	v_mfma_f32_16x16x32_bf16 v[48:51], v[176:179], v[200:203], v[48:51]
	v_mfma_f32_16x16x32_bf16 v[40:43], v[184:187], v[200:203], v[40:43]
	v_mfma_f32_16x16x32_bf16 v[32:35], v[176:179], v[208:211], v[32:35]
	v_mfma_f32_16x16x32_bf16 v[24:27], v[184:187], v[208:211], v[24:27]
	v_mfma_f32_16x16x32_bf16 v[16:19], v[176:179], v[216:219], v[16:19]
	v_mfma_f32_16x16x32_bf16 v[8:11], v[184:187], v[216:219], v[8:11]
	s_barrier
	s_add_i32 s95, s95, 2
	s_add_u32 s96, s96, 0x100
	s_addc_u32 s6, s6, 0
	s_cmp_gt_u32 s95, 13
	s_mov_b64 s[40:41], s[30:31]
	s_cbranch_scc0 .LBB0_912
	s_and_b64 vcc, exec, s[18:19]
	s_cbranch_vccz .LBB0_915
	s_barrier

; template <class Epi, class Sched, bool ALIGN_EPI = false, bool SP2 = false>
; __device__ __forceinline__ void gemm_phase(PG8_LAS unsigned char* lds, const Gemm g, const Sched& S, const Epi& E, int wave_s) {
;     ...
;         for (int t = peeled ? 2 : 0; t < nt; t += 2) {
;             const bool last = (t == nt - 2);
;             const char* a1 = cA + (size_t)(t + 1) * kstep;
;             const char* a2 = last ? nA : cA + (size_t)(t + 2) * kstep; const char* b2 = last ? nB : cB + (size_t)(t + 2) * kstep;
;             const char* a3 = a2 + kstep; const char* b3 = b2 + kstep;
;             if (last && has_next) S.a_ready(nxt);
.LBB0_1188:
	ds_read_b128 v[140:143], v147
	ds_read_b128 v[160:163], v147 offset:1024
	ds_read_b128 v[164:167], v147 offset:2048
	ds_read_b128 v[168:171], v147 offset:3072
	ds_read_b128 v[172:175], v148
	ds_read_b128 v[176:179], v148 offset:1024
	ds_read_b128 v[180:183], v148 offset:2048
	ds_read_b128 v[184:187], v148 offset:3072
	s_add_u32 s40, s38, 0x100
	s_addc_u32 s41, s39, 0
	s_cmp_eq_u32 vcc_lo, 40
	s_cselect_b32 s72, s12, s40
	s_cselect_b32 s73, s13, s41
	s_cselect_b32 s70, s36, s60
	s_cselect_b32 s71, s37, s61
	s_add_u32 s42, s72, 0x80
	s_addc_u32 s43, s73, 0
	s_add_u32 s6, s38, 0xb0080
	s_addc_u32 s7, s39, 0
	ds_read_b128 v[188:191], v149
	ds_read_b128 v[192:195], v149 offset:1024
	ds_read_b128 v[196:199], v149 offset:2048
	ds_read_b128 v[200:203], v149 offset:3072
	ds_read_b128 v[204:207], v149 offset:4096
	ds_read_b128 v[208:211], v149 offset:5120
	ds_read_b128 v[212:215], v149 offset:6144
	ds_read_b128 v[216:219], v149 offset:7168
	s_add_i32 m0, s76, 0xc000
	s_nop 0
	global_load_lds_dwordx4 v128, s[6:7]
	s_add_i32 m0, s76, 0xe000
	s_nop 0
	global_load_lds_dwordx4 v132, s[6:7]
	s_waitcnt vmcnt(8)
	s_waitcnt lgkmcnt(0)
	s_barrier
	s_waitcnt lgkmcnt(0)
	v_mfma_f32_16x16x32_bf16 v[124:127], v[140:143], v[188:191], v[124:127]
	v_mfma_f32_16x16x32_bf16 v[120:123], v[164:167], v[188:191], v[120:123]
	v_mfma_f32_16x16x32_bf16 v[108:111], v[140:143], v[196:199], v[108:111]
	v_mfma_f32_16x16x32_bf16 v[104:107], v[164:167], v[196:199], v[104:107]
	v_mfma_f32_16x16x32_bf16 v[92:95], v[140:143], v[204:207], v[92:95]
	v_mfma_f32_16x16x32_bf16 v[88:91], v[164:167], v[204:207], v[88:91]
	v_mfma_f32_16x16x32_bf16 v[76:79], v[140:143], v[212:215], v[76:79]
	v_mfma_f32_16x16x32_bf16 v[72:75], v[164:167], v[212:215], v[72:75]
	v_mfma_f32_16x16x32_bf16 v[124:127], v[160:163], v[192:195], v[124:127]
	v_mfma_f32_16x16x32_bf16 v[120:123], v[168:171], v[192:195], v[120:123]
	v_mfma_f32_16x16x32_bf16 v[108:111], v[160:163], v[200:203], v[108:111]
	v_mfma_f32_16x16x32_bf16 v[104:107], v[168:171], v[200:203], v[104:107]
	v_mfma_f32_16x16x32_bf16 v[92:95], v[160:163], v[208:211], v[92:95]
	v_mfma_f32_16x16x32_bf16 v[88:91], v[168:171], v[208:211], v[88:91]
	v_mfma_f32_16x16x32_bf16 v[76:79], v[160:163], v[216:219], v[76:79]
	v_mfma_f32_16x16x32_bf16 v[72:75], v[168:171], v[216:219], v[72:75]
	v_mfma_f32_16x16x32_bf16 v[116:119], v[172:175], v[188:191], v[116:119]
	v_mfma_f32_16x16x32_bf16 v[112:115], v[180:183], v[188:191], v[112:115]
	v_mfma_f32_16x16x32_bf16 v[100:103], v[172:175], v[196:199], v[100:103]
	v_mfma_f32_16x16x32_bf16 v[96:99], v[180:183], v[196:199], v[96:99]
	v_mfma_f32_16x16x32_bf16 v[84:87], v[172:175], v[204:207], v[84:87]
	v_mfma_f32_16x16x32_bf16 v[80:83], v[180:183], v[204:207], v[80:83]
	v_mfma_f32_16x16x32_bf16 v[68:71], v[172:175], v[212:215], v[68:71]
	v_mfma_f32_16x16x32_bf16 v[64:67], v[180:183], v[212:215], v[64:67]
	v_mfma_f32_16x16x32_bf16 v[116:119], v[176:179], v[192:195], v[116:119]
	v_mfma_f32_16x16x32_bf16 v[112:115], v[184:187], v[192:195], v[112:115]
	v_mfma_f32_16x16x32_bf16 v[100:103], v[176:179], v[200:203], v[100:103]
	v_mfma_f32_16x16x32_bf16 v[96:99], v[184:187], v[200:203], v[96:99]
	v_mfma_f32_16x16x32_bf16 v[84:87], v[176:179], v[208:211], v[84:87]
	v_mfma_f32_16x16x32_bf16 v[80:83], v[184:187], v[208:211], v[80:83]
	v_mfma_f32_16x16x32_bf16 v[68:71], v[176:179], v[216:219], v[68:71]
	v_mfma_f32_16x16x32_bf16 v[64:67], v[184:187], v[216:219], v[64:67]
	s_barrier
	s_setprio 1
	s_mov_b64 s[6:7], s[70:71]
	s_add_i32 s38, s93, s75
	ds_read_b128 v[188:191], v149 offset:16384
	ds_read_b128 v[192:195], v149 offset:17408
	ds_read_b128 v[196:199], v149 offset:18432
	ds_read_b128 v[200:203], v149 offset:19456
	ds_read_b128 v[204:207], v149 offset:20480
	ds_read_b128 v[208:211], v149 offset:21504
	ds_read_b128 v[212:215], v149 offset:22528
	ds_read_b128 v[216:219], v149 offset:23552
	s_mov_b32 m0, s38
	s_nop 0
	global_load_lds_dwordx4 v130, s[6:7]
	s_add_i32 m0, s38, 0x2000
	s_nop 0
	global_load_lds_dwordx4 v134, s[6:7]
	s_add_u32 s6, s70, 0xb0000
	s_addc_u32 s7, s71, 0
	s_add_i32 s38, s94, s75
	s_mov_b32 m0, s38
	s_nop 0
	global_load_lds_dwordx4 v130, s[6:7]
	s_mov_b64 s[98:99], s[6:7]
	s_add_i32 m0, s38, 0x2000
	s_mov_b64 s[6:7], s[72:73]
	global_load_lds_dwordx4 v134, s[98:99]
	s_mov_b32 m0, s76
	s_nop 0
	global_load_lds_dwordx4 v128, s[6:7]
	s_mov_b32 m0, s77
	s_nop 0
	global_load_lds_dwordx4 v132, s[6:7]
	s_setprio 0
	s_waitcnt vmcnt(8)
	s_waitcnt lgkmcnt(0)
	s_barrier
	s_waitcnt lgkmcnt(0)
	v_mfma_f32_16x16x32_bf16 v[60:63], v[140:143], v[188:191], v[60:63]
	v_mfma_f32_16x16x32_bf16 v[56:59], v[164:167], v[188:191], v[56:59]
	v_mfma_f32_16x16x32_bf16 v[44:47], v[140:143], v[196:199], v[44:47]
	v_mfma_f32_16x16x32_bf16 v[40:43], v[164:167], v[196:199], v[40:43]
	v_mfma_f32_16x16x32_bf16 v[28:31], v[140:143], v[204:207], v[28:31]
	v_mfma_f32_16x16x32_bf16 v[24:27], v[164:167], v[204:207], v[24:27]
	v_mfma_f32_16x16x32_bf16 v[12:15], v[140:143], v[212:215], v[12:15]
	v_mfma_f32_16x16x32_bf16 v[8:11], v[164:167], v[212:215], v[8:11]
	v_mfma_f32_16x16x32_bf16 v[60:63], v[160:163], v[192:195], v[60:63]
	v_mfma_f32_16x16x32_bf16 v[56:59], v[168:171], v[192:195], v[56:59]
	v_mfma_f32_16x16x32_bf16 v[44:47], v[160:163], v[200:203], v[44:47]
	v_mfma_f32_16x16x32_bf16 v[40:43], v[168:171], v[200:203], v[40:43]
	v_mfma_f32_16x16x32_bf16 v[28:31], v[160:163], v[208:211], v[28:31]
	v_mfma_f32_16x16x32_bf16 v[24:27], v[168:171], v[208:211], v[24:27]
	v_mfma_f32_16x16x32_bf16 v[12:15], v[160:163], v[216:219], v[12:15]
	v_mfma_f32_16x16x32_bf16 v[8:11], v[168:171], v[216:219], v[8:11]
	v_mfma_f32_16x16x32_bf16 v[52:55], v[172:175], v[188:191], v[52:55]
	v_mfma_f32_16x16x32_bf16 v[48:51], v[180:183], v[188:191], v[48:51]
	v_mfma_f32_16x16x32_bf16 v[36:39], v[172:175], v[196:199], v[36:39]
	v_mfma_f32_16x16x32_bf16 v[32:35], v[180:183], v[196:199], v[32:35]
	v_mfma_f32_16x16x32_bf16 v[20:23], v[172:175], v[204:207], v[20:23]
	v_mfma_f32_16x16x32_bf16 v[16:19], v[180:183], v[204:207], v[16:19]
	v_mfma_f32_16x16x32_bf16 v[4:7], v[172:175], v[212:215], v[4:7]
	v_mfma_f32_16x16x32_bf16 v[0:3], v[180:183], v[212:215], v[0:3]
	v_mfma_f32_16x16x32_bf16 v[52:55], v[176:179], v[192:195], v[52:55]
	v_mfma_f32_16x16x32_bf16 v[48:51], v[184:187], v[192:195], v[48:51]
	v_mfma_f32_16x16x32_bf16 v[36:39], v[176:179], v[200:203], v[36:39]
	v_mfma_f32_16x16x32_bf16 v[32:35], v[184:187], v[200:203], v[32:35]
	v_mfma_f32_16x16x32_bf16 v[20:23], v[176:179], v[208:211], v[20:23]
	v_mfma_f32_16x16x32_bf16 v[16:19], v[184:187], v[208:211], v[16:19]
	v_mfma_f32_16x16x32_bf16 v[4:7], v[176:179], v[216:219], v[4:7]
	v_mfma_f32_16x16x32_bf16 v[0:3], v[184:187], v[216:219], v[0:3]
	s_barrier
; #define PG8_BAR __builtin_amdgcn_s_barrier()
; template <class Epi, class Sched, bool ALIGN_EPI = false, bool SP2 = false>
; __device__ __forceinline__ void gemm_phase(PG8_LAS unsigned char* lds, const Gemm g, const Sched& S, const Epi& E, int wave_s) {
;     ...
;         }
;         if constexpr (ALIGN_EPI) { if (wr == 0) PG8_BAR; }
	s_add_i32 s38, 0, 0x18000
	v_add_u32_e32 v159, s38, v145
	s_add_i32 s39, 0, 0x1c000
	ds_read_b128 v[140:143], v159
	ds_read_b128 v[160:163], v159 offset:1024
	ds_read_b128 v[164:167], v159 offset:2048
	ds_read_b128 v[168:171], v159 offset:3072
	v_add_u32_e32 v159, s39, v145
	ds_read_b128 v[172:175], v159
	ds_read_b128 v[176:179], v159 offset:1024
	ds_read_b128 v[180:183], v159 offset:2048
	ds_read_b128 v[184:187], v159 offset:3072
	s_add_u32 s6, s72, 0xb0000
	s_addc_u32 s7, s73, 0
	s_mov_b32 m0, s78
	ds_read_b128 v[188:191], v149 offset:32768
	ds_read_b128 v[192:195], v149 offset:33792
	ds_read_b128 v[196:199], v149 offset:34816
	ds_read_b128 v[200:203], v149 offset:35840
	ds_read_b128 v[204:207], v149 offset:36864
	ds_read_b128 v[208:211], v149 offset:37888
	ds_read_b128 v[212:215], v149 offset:38912
	ds_read_b128 v[216:219], v149 offset:39936
	s_nop 0
	global_load_lds_dwordx4 v128, s[6:7]
	s_mov_b32 m0, s79
	s_nop 0
	global_load_lds_dwordx4 v132, s[6:7]
	s_waitcnt vmcnt(8)
	s_waitcnt lgkmcnt(0)
	s_barrier
	s_waitcnt lgkmcnt(0)
	v_mfma_f32_16x16x32_bf16 v[124:127], v[140:143], v[188:191], v[124:127]
	v_mfma_f32_16x16x32_bf16 v[120:123], v[164:167], v[188:191], v[120:123]
	v_mfma_f32_16x16x32_bf16 v[108:111], v[140:143], v[196:199], v[108:111]
	v_mfma_f32_16x16x32_bf16 v[104:107], v[164:167], v[196:199], v[104:107]
	v_mfma_f32_16x16x32_bf16 v[92:95], v[140:143], v[204:207], v[92:95]
	v_mfma_f32_16x16x32_bf16 v[88:91], v[164:167], v[204:207], v[88:91]
	v_mfma_f32_16x16x32_bf16 v[76:79], v[140:143], v[212:215], v[76:79]
	v_mfma_f32_16x16x32_bf16 v[72:75], v[164:167], v[212:215], v[72:75]
	v_mfma_f32_16x16x32_bf16 v[124:127], v[160:163], v[192:195], v[124:127]
	v_mfma_f32_16x16x32_bf16 v[120:123], v[168:171], v[192:195], v[120:123]
	v_mfma_f32_16x16x32_bf16 v[108:111], v[160:163], v[200:203], v[108:111]
	v_mfma_f32_16x16x32_bf16 v[104:107], v[168:171], v[200:203], v[104:107]
	v_mfma_f32_16x16x32_bf16 v[92:95], v[160:163], v[208:211], v[92:95]
	v_mfma_f32_16x16x32_bf16 v[88:91], v[168:171], v[208:211], v[88:91]
	v_mfma_f32_16x16x32_bf16 v[76:79], v[160:163], v[216:219], v[76:79]
	v_mfma_f32_16x16x32_bf16 v[72:75], v[168:171], v[216:219], v[72:75]
	v_mfma_f32_16x16x32_bf16 v[116:119], v[172:175], v[188:191], v[116:119]
	v_mfma_f32_16x16x32_bf16 v[112:115], v[180:183], v[188:191], v[112:115]
	v_mfma_f32_16x16x32_bf16 v[100:103], v[172:175], v[196:199], v[100:103]
	v_mfma_f32_16x16x32_bf16 v[96:99], v[180:183], v[196:199], v[96:99]
	v_mfma_f32_16x16x32_bf16 v[84:87], v[172:175], v[204:207], v[84:87]
	v_mfma_f32_16x16x32_bf16 v[80:83], v[180:183], v[204:207], v[80:83]
	v_mfma_f32_16x16x32_bf16 v[68:71], v[172:175], v[212:215], v[68:71]
	v_mfma_f32_16x16x32_bf16 v[64:67], v[180:183], v[212:215], v[64:67]
	v_mfma_f32_16x16x32_bf16 v[116:119], v[176:179], v[192:195], v[116:119]
	v_mfma_f32_16x16x32_bf16 v[112:115], v[184:187], v[192:195], v[112:115]
	v_mfma_f32_16x16x32_bf16 v[100:103], v[176:179], v[200:203], v[100:103]
	v_mfma_f32_16x16x32_bf16 v[96:99], v[184:187], v[200:203], v[96:99]
	v_mfma_f32_16x16x32_bf16 v[84:87], v[176:179], v[208:211], v[84:87]
	v_mfma_f32_16x16x32_bf16 v[80:83], v[184:187], v[208:211], v[80:83]
	v_mfma_f32_16x16x32_bf16 v[68:71], v[176:179], v[216:219], v[68:71]
	v_mfma_f32_16x16x32_bf16 v[64:67], v[184:187], v[216:219], v[64:67]
	s_barrier
	s_setprio 1
	s_add_u32 s6, s70, 0x80
	s_addc_u32 s7, s71, 0
	s_add_i32 s38, s38, s75
	ds_read_b128 v[188:191], v149 offset:49152
	ds_read_b128 v[192:195], v149 offset:50176
	ds_read_b128 v[196:199], v149 offset:51200
	ds_read_b128 v[200:203], v149 offset:52224
	ds_read_b128 v[204:207], v149 offset:53248
	ds_read_b128 v[208:211], v149 offset:54272
	ds_read_b128 v[212:215], v149 offset:55296
	ds_read_b128 v[216:219], v149 offset:56320
	s_mov_b32 m0, s38
	s_nop 0
	global_load_lds_dwordx4 v130, s[6:7]
	s_add_i32 m0, s38, 0x2000
	s_nop 0
	global_load_lds_dwordx4 v134, s[6:7]
	s_add_u32 s6, s70, 0xb0080
	s_addc_u32 s7, s71, 0
	s_add_i32 s38, s39, s75
	s_mov_b32 m0, s38
	s_nop 0
	global_load_lds_dwordx4 v130, s[6:7]
	s_add_i32 m0, s38, 0x2000
	s_nop 0
	global_load_lds_dwordx4 v134, s[6:7]
	s_mov_b32 m0, s88
	s_nop 0
	global_load_lds_dwordx4 v128, s[42:43]
	s_mov_b32 m0, s89
	s_nop 0
	global_load_lds_dwordx4 v132, s[42:43]
	s_setprio 0
	s_waitcnt vmcnt(8)
	s_waitcnt lgkmcnt(0)
	s_barrier
	s_waitcnt lgkmcnt(0)
	v_mfma_f32_16x16x32_bf16 v[60:63], v[140:143], v[188:191], v[60:63]
	v_mfma_f32_16x16x32_bf16 v[56:59], v[164:167], v[188:191], v[56:59]
	v_mfma_f32_16x16x32_bf16 v[44:47], v[140:143], v[196:199], v[44:47]
	v_mfma_f32_16x16x32_bf16 v[40:43], v[164:167], v[196:199], v[40:43]
	v_mfma_f32_16x16x32_bf16 v[28:31], v[140:143], v[204:207], v[28:31]
	v_mfma_f32_16x16x32_bf16 v[24:27], v[164:167], v[204:207], v[24:27]
	v_mfma_f32_16x16x32_bf16 v[12:15], v[140:143], v[212:215], v[12:15]
	v_mfma_f32_16x16x32_bf16 v[8:11], v[164:167], v[212:215], v[8:11]
	v_mfma_f32_16x16x32_bf16 v[60:63], v[160:163], v[192:195], v[60:63]
	v_mfma_f32_16x16x32_bf16 v[56:59], v[168:171], v[192:195], v[56:59]
	v_mfma_f32_16x16x32_bf16 v[44:47], v[160:163], v[200:203], v[44:47]
	v_mfma_f32_16x16x32_bf16 v[40:43], v[168:171], v[200:203], v[40:43]
	v_mfma_f32_16x16x32_bf16 v[28:31], v[160:163], v[208:211], v[28:31]
	v_mfma_f32_16x16x32_bf16 v[24:27], v[168:171], v[208:211], v[24:27]
	v_mfma_f32_16x16x32_bf16 v[12:15], v[160:163], v[216:219], v[12:15]
	v_mfma_f32_16x16x32_bf16 v[8:11], v[168:171], v[216:219], v[8:11]
	v_mfma_f32_16x16x32_bf16 v[52:55], v[172:175], v[188:191], v[52:55]
	v_mfma_f32_16x16x32_bf16 v[48:51], v[180:183], v[188:191], v[48:51]
	v_mfma_f32_16x16x32_bf16 v[36:39], v[172:175], v[196:199], v[36:39]
	v_mfma_f32_16x16x32_bf16 v[32:35], v[180:183], v[196:199], v[32:35]
	v_mfma_f32_16x16x32_bf16 v[20:23], v[172:175], v[204:207], v[20:23]
	v_mfma_f32_16x16x32_bf16 v[16:19], v[180:183], v[204:207], v[16:19]
	v_mfma_f32_16x16x32_bf16 v[4:7], v[172:175], v[212:215], v[4:7]
	v_mfma_f32_16x16x32_bf16 v[0:3], v[180:183], v[212:215], v[0:3]
	v_mfma_f32_16x16x32_bf16 v[52:55], v[176:179], v[192:195], v[52:55]
	v_mfma_f32_16x16x32_bf16 v[48:51], v[184:187], v[192:195], v[48:51]
	v_mfma_f32_16x16x32_bf16 v[36:39], v[176:179], v[200:203], v[36:39]
	v_mfma_f32_16x16x32_bf16 v[32:35], v[184:187], v[200:203], v[32:35]
	v_mfma_f32_16x16x32_bf16 v[20:23], v[176:179], v[208:211], v[20:23]
	v_mfma_f32_16x16x32_bf16 v[16:19], v[184:187], v[208:211], v[16:19]
	v_mfma_f32_16x16x32_bf16 v[4:7], v[176:179], v[216:219], v[4:7]
	v_mfma_f32_16x16x32_bf16 v[0:3], v[184:187], v[216:219], v[0:3]
	s_barrier
	s_add_i32 vcc_lo, vcc_lo, 2
	s_add_u32 s60, s60, 0x100
	s_addc_u32 s61, s61, 0
	s_cmp_gt_u32 vcc_lo, 41
	s_mov_b64 s[38:39], s[40:41]
	s_cbranch_scc0 .LBB0_1188
	s_and_b64 vcc, exec, s[22:23]
	s_cbranch_vccz .LBB0_1191
	s_barrier

; __device__ __forceinline__ int lane_id_() { int l; asm volatile("v_mbcnt_lo_u32_b32 %0, -1, 0\n\tv_mbcnt_hi_u32_b32 %0, -1, %0" : "=v"(l)); return l; }
; #define PG8_LAS __attribute__((address_space(3)))
;     __device__ __forceinline__ void prefetch(PG8_LAS unsigned char* lds, int wid, const Unit& u, int wr, int fr, int fq) const {
;         { const int l_ = lane_id_(); fr = l_ & 15; fq = l_ >> 4; }
; #pragma unroll
;         for (int j = 0; j < 2; ++j) { const int i = 2 * fq + j;
;             __builtin_amdgcn_global_load_lds((const unsigned*)(ssq + u.pm * BM + wr * 64 + fr + (i >> 2) * HALF + (i & 3) * 16), (PG8_LAS unsigned*)(lds + PRE_SLOT + wid * 512 + j * 256), 4, 0, 0); }
;     }
.LBB0_1273:
	s_lshl_b32 s6, s26, 8
	s_ashr_i32 s7, s6, 31
	s_lshl_b64 s[6:7], s[6:7], 2
	v_mbcnt_lo_u32_b32 v6, -1, 0
	v_mbcnt_hi_u32_b32 v6, -1, v6
	s_add_u32 s6, s63, s6
	v_and_b32_e32 v0, 15, v6
	v_lshlrev_b32_e32 v2, 2, v6
	v_and_b32_e32 v2, 0xffffff80, v2
	s_addc_u32 s7, s74, s7
	v_lshlrev_b32_e32 v0, 2, v0
	v_ashrrev_i32_e32 v3, 31, v2
	v_lshl_add_u64 v[4:5], s[6:7], 0, v[0:1]
	v_lshlrev_b32_e32 v0, 3, v6
	v_lshl_add_u64 v[2:3], v[2:3], 2, v[4:5]
	v_and_b32_e32 v0, 0x80, v0
	s_mov_b32 m0, s76
	v_lshl_add_u64 v[2:3], v[2:3], 0, v[0:1]
	global_load_lds_dword v[2:3], off
	v_lshl_add_u64 v[2:3], v[2:3], 0, 64
	s_add_i32 m0, s76, 0x100
	s_add_u32 s34, s28, 0x100
	global_load_lds_dword v[2:3], off
	ds_read_b128 v[2:5], v151
	ds_read_b128 v[6:9], v151 offset:1024
	ds_read_b128 v[10:13], v151 offset:2048
	ds_read_b128 v[14:17], v151 offset:3072
	ds_read_b128 v[18:21], v150
	ds_read_b128 v[22:25], v150 offset:1024
	ds_read_b128 v[26:29], v150 offset:2048
	ds_read_b128 v[30:33], v150 offset:3072
	s_addc_u32 s35, s29, 0
	s_add_u32 s8, s28, 0x180
	s_addc_u32 s9, s29, 0
	s_add_u32 s6, s30, 0x100
	s_addc_u32 s7, s31, 0
	s_add_u32 s36, s28, 0x40080
	s_addc_u32 s37, s29, 0
	s_mov_b32 m0, s94
	ds_read_b128 v[34:37], v149
	ds_read_b128 v[38:41], v149 offset:1024
	ds_read_b128 v[42:45], v149 offset:2048
	ds_read_b128 v[46:49], v149 offset:3072
	ds_read_b128 v[50:53], v149 offset:4096
	ds_read_b128 v[54:57], v149 offset:5120
	ds_read_b128 v[58:61], v149 offset:6144
	ds_read_b128 v[62:65], v149 offset:7168
	s_nop 0
	global_load_lds_dwordx4 v138, s[36:37]
	s_mov_b32 m0, s12
	s_nop 0
	global_load_lds_dwordx4 v134, s[36:37]
	s_waitcnt vmcnt(18)
	s_waitcnt lgkmcnt(0)
	s_barrier
	s_waitcnt lgkmcnt(0)
	v_mfma_f32_16x16x32_bf16 v[90:93], v[2:5], v[58:61], 0
	v_mfma_f32_16x16x32_bf16 v[66:69], v[2:5], v[34:37], 0
	v_mfma_f32_16x16x32_bf16 v[70:73], v[10:13], v[34:37], 0
	v_mfma_f32_16x16x32_bf16 v[74:77], v[2:5], v[42:45], 0
	v_mfma_f32_16x16x32_bf16 v[78:81], v[10:13], v[42:45], 0
	v_mfma_f32_16x16x32_bf16 v[82:85], v[2:5], v[50:53], 0
	v_mfma_f32_16x16x32_bf16 v[86:89], v[10:13], v[50:53], 0
	v_mfma_f32_16x16x32_bf16 v[96:99], v[6:9], v[62:65], v[90:93]
	v_mfma_f32_16x16x32_bf16 v[90:93], v[10:13], v[58:61], 0
	v_mfma_f32_16x16x32_bf16 v[66:69], v[6:9], v[38:41], v[66:69]
	v_mfma_f32_16x16x32_bf16 v[70:73], v[14:17], v[38:41], v[70:73]
	v_mfma_f32_16x16x32_bf16 v[74:77], v[6:9], v[46:49], v[74:77]
	v_mfma_f32_16x16x32_bf16 v[78:81], v[14:17], v[46:49], v[78:81]
	v_mfma_f32_16x16x32_bf16 v[82:85], v[6:9], v[54:57], v[82:85]
	v_mfma_f32_16x16x32_bf16 v[86:89], v[14:17], v[54:57], v[86:89]
	v_mfma_f32_16x16x32_bf16 v[104:107], v[14:17], v[62:65], v[90:93]
	v_mfma_f32_16x16x32_bf16 v[90:93], v[18:21], v[34:37], 0
	v_mfma_f32_16x16x32_bf16 v[34:37], v[26:29], v[34:37], 0
	v_mfma_f32_16x16x32_bf16 v[112:115], v[22:25], v[38:41], v[90:93]
	v_mfma_f32_16x16x32_bf16 v[34:37], v[30:33], v[38:41], v[34:37]
	v_mfma_f32_16x16x32_bf16 v[38:41], v[18:21], v[42:45], 0
	v_mfma_f32_16x16x32_bf16 v[42:45], v[26:29], v[42:45], 0
	v_mfma_f32_16x16x32_bf16 v[38:41], v[22:25], v[46:49], v[38:41]
	v_mfma_f32_16x16x32_bf16 v[42:45], v[30:33], v[46:49], v[42:45]
	v_mfma_f32_16x16x32_bf16 v[46:49], v[18:21], v[50:53], 0
	v_mfma_f32_16x16x32_bf16 v[50:53], v[26:29], v[50:53], 0
	v_mfma_f32_16x16x32_bf16 v[46:49], v[22:25], v[54:57], v[46:49]
	v_mfma_f32_16x16x32_bf16 v[50:53], v[30:33], v[54:57], v[50:53]
	v_mfma_f32_16x16x32_bf16 v[54:57], v[18:21], v[58:61], 0
	v_mfma_f32_16x16x32_bf16 v[54:57], v[22:25], v[62:65], v[54:57]
	v_mfma_f32_16x16x32_bf16 v[58:61], v[26:29], v[58:61], 0
	v_mfma_f32_16x16x32_bf16 v[154:157], v[30:33], v[62:65], v[58:61]
	s_barrier
	s_setprio 1
	s_mov_b32 m0, s61
	s_nop 3
	ds_read_b128 v[58:61], v149 offset:16384
	ds_read_b128 v[62:65], v149 offset:17408
	ds_read_b128 v[90:93], v149 offset:18432
	ds_read_b128 v[100:103], v149 offset:19456
	ds_read_b128 v[108:111], v149 offset:20480
	ds_read_b128 v[116:119], v149 offset:21504
	ds_read_b128 v[120:123], v149 offset:22528
	ds_read_b128 v[124:127], v149 offset:23552
	s_nop 0
	global_load_lds_dwordx4 v136, s[6:7]
	s_mov_b64 s[98:99], s[6:7]
	s_add_u32 s6, s30, 0x40100
	s_mov_b32 m0, s25
	s_addc_u32 s7, s31, 0
	global_load_lds_dwordx4 v132, s[98:99]
	s_mov_b32 m0, s27
	s_nop 0
	global_load_lds_dwordx4 v136, s[6:7]
	s_mov_b32 m0, s60
	s_nop 0
	global_load_lds_dwordx4 v132, s[6:7]
	s_mov_b32 m0, s77
	s_nop 0
	global_load_lds_dwordx4 v138, s[34:35]
	s_mov_b32 m0, s78
	s_nop 0
	global_load_lds_dwordx4 v134, s[34:35]
	s_setprio 0
	s_waitcnt vmcnt(18)
	s_waitcnt lgkmcnt(0)
	s_barrier
	s_waitcnt lgkmcnt(0)
	v_mfma_f32_16x16x32_bf16 v[128:131], v[2:5], v[58:61], 0
	v_mfma_f32_16x16x32_bf16 v[158:161], v[6:9], v[62:65], v[128:131]
	v_mfma_f32_16x16x32_bf16 v[128:131], v[10:13], v[58:61], 0
	v_mfma_f32_16x16x32_bf16 v[162:165], v[14:17], v[62:65], v[128:131]
	v_mfma_f32_16x16x32_bf16 v[128:131], v[2:5], v[90:93], 0
	v_mfma_f32_16x16x32_bf16 v[166:169], v[6:9], v[100:103], v[128:131]
	v_mfma_f32_16x16x32_bf16 v[128:131], v[10:13], v[90:93], 0
	v_mfma_f32_16x16x32_bf16 v[170:173], v[14:17], v[100:103], v[128:131]
	v_mfma_f32_16x16x32_bf16 v[128:131], v[2:5], v[108:111], 0
	v_mfma_f32_16x16x32_bf16 v[2:5], v[2:5], v[120:123], 0
	v_mfma_f32_16x16x32_bf16 v[174:177], v[6:9], v[116:119], v[128:131]
	v_mfma_f32_16x16x32_bf16 v[2:5], v[6:9], v[124:127], v[2:5]
	v_mfma_f32_16x16x32_bf16 v[6:9], v[10:13], v[120:123], 0
	v_mfma_f32_16x16x32_bf16 v[128:131], v[10:13], v[108:111], 0
	v_mfma_f32_16x16x32_bf16 v[6:9], v[14:17], v[124:127], v[6:9]
	v_mfma_f32_16x16x32_bf16 v[178:181], v[14:17], v[116:119], v[128:131]
	v_mfma_f32_16x16x32_bf16 v[10:13], v[18:21], v[58:61], 0
	v_mfma_f32_16x16x32_bf16 v[182:185], v[22:25], v[62:65], v[10:13]
	v_mfma_f32_16x16x32_bf16 v[10:13], v[26:29], v[58:61], 0
	v_mfma_f32_16x16x32_bf16 v[186:189], v[30:33], v[62:65], v[10:13]
	v_mfma_f32_16x16x32_bf16 v[10:13], v[18:21], v[90:93], 0
	v_mfma_f32_16x16x32_bf16 v[190:193], v[22:25], v[100:103], v[10:13]
	v_mfma_f32_16x16x32_bf16 v[10:13], v[26:29], v[90:93], 0
	v_mfma_f32_16x16x32_bf16 v[194:197], v[30:33], v[100:103], v[10:13]
	v_mfma_f32_16x16x32_bf16 v[10:13], v[18:21], v[108:111], 0
	v_mfma_f32_16x16x32_bf16 v[198:201], v[22:25], v[116:119], v[10:13]
	v_mfma_f32_16x16x32_bf16 v[10:13], v[26:29], v[108:111], 0
	v_mfma_f32_16x16x32_bf16 v[202:205], v[30:33], v[116:119], v[10:13]
	v_mfma_f32_16x16x32_bf16 v[10:13], v[18:21], v[120:123], 0
	v_mfma_f32_16x16x32_bf16 v[16:19], v[22:25], v[124:127], v[10:13]
	v_mfma_f32_16x16x32_bf16 v[10:13], v[26:29], v[120:123], 0
	v_mfma_f32_16x16x32_bf16 v[206:209], v[30:33], v[124:127], v[10:13]
	s_barrier
; #define PG8_WAIT_V8_RELAX() do { if constexpr (Epi::NSTORES + Epi::NPRE == 10) asm volatile("s_waitcnt vmcnt(18)" ::: "memory"); else if constexpr (Epi::NSTORES + Epi::NPRE == 18) asm volatile("s_waitcnt vmcnt(26)" ::: "memory"); else asm volatile("s_waitcnt vmcnt(8)" ::: "memory"); } while (0)
; template <class Epi, class Sched, bool ALIGN_EPI = false, bool SP2 = false>
; __device__ __forceinline__ void gemm_phase(PG8_LAS unsigned char* lds, const Gemm g, const Sched& S, const Epi& E, int wave_s) {
;     ...
;         if constexpr (SP2 && Epi::NSTORES > 0 && !Epi::AFTER_DRAIN) {
;             const char* a1 = cA + kstep; const char* a2 = cA + 2 * kstep; const char* b2 = cB + 2 * kstep; const char* a3 = a2 + kstep; const char* b3 = b2 + kstep;
;             PG8_SP2_PAIR(PG8_WAIT_V8_RELAX);
;             peeled = true;
	s_nop 4
	ds_read_b128 v[10:13], v152
	ds_read_b128 v[24:27], v152 offset:1024
	ds_read_b128 v[210:213], v152 offset:2048
	ds_read_b128 v[214:217], v152 offset:3072
	ds_read_b128 v[218:221], v153
	ds_read_b128 v[222:225], v153 offset:1024
	ds_read_b128 v[226:229], v153 offset:2048
	ds_read_b128 v[150:153], v153 offset:3072
	s_add_u32 s6, s28, 0x40100
	s_addc_u32 s7, s29, 0
	s_mov_b32 m0, s79
	ds_read_b128 v[20:23], v149 offset:32768
	ds_read_b128 v[28:31], v149 offset:33792
	ds_read_b128 v[230:233], v149 offset:34816
	ds_read_b128 v[234:237], v149 offset:35840
	ds_read_b128 v[238:241], v149 offset:36864
	ds_read_b128 v[242:245], v149 offset:37888
	ds_read_b128 v[246:249], v149 offset:38912
	ds_read_b128 v[250:253], v149 offset:39936
	s_nop 0
	global_load_lds_dwordx4 v138, s[6:7]
	s_mov_b32 m0, s82
	s_nop 0
	global_load_lds_dwordx4 v134, s[6:7]
	s_waitcnt vmcnt(18)
	s_waitcnt lgkmcnt(0)
	s_barrier
	s_waitcnt lgkmcnt(0)
	v_mfma_f32_16x16x32_bf16 v[58:61], v[10:13], v[20:23], v[66:69]
	v_mfma_f32_16x16x32_bf16 v[124:127], v[24:27], v[28:31], v[58:61]
	v_mfma_f32_16x16x32_bf16 v[58:61], v[210:213], v[20:23], v[70:73]
	v_mfma_f32_16x16x32_bf16 v[116:119], v[214:217], v[28:31], v[58:61]
	v_mfma_f32_16x16x32_bf16 v[58:61], v[10:13], v[230:233], v[74:77]
	v_mfma_f32_16x16x32_bf16 v[108:111], v[24:27], v[234:237], v[58:61]
	v_mfma_f32_16x16x32_bf16 v[58:61], v[210:213], v[230:233], v[78:81]
	v_mfma_f32_16x16x32_bf16 v[100:103], v[214:217], v[234:237], v[58:61]
	v_mfma_f32_16x16x32_bf16 v[58:61], v[10:13], v[238:241], v[82:85]
	v_mfma_f32_16x16x32_bf16 v[92:95], v[24:27], v[242:245], v[58:61]
	v_mfma_f32_16x16x32_bf16 v[58:61], v[210:213], v[238:241], v[86:89]
	v_mfma_f32_16x16x32_bf16 v[84:87], v[214:217], v[242:245], v[58:61]
	v_mfma_f32_16x16x32_bf16 v[58:61], v[10:13], v[246:249], v[96:99]
	v_mfma_f32_16x16x32_bf16 v[76:79], v[24:27], v[250:253], v[58:61]
	v_mfma_f32_16x16x32_bf16 v[58:61], v[210:213], v[246:249], v[104:107]
	v_mfma_f32_16x16x32_bf16 v[60:63], v[214:217], v[250:253], v[58:61]
	v_mfma_f32_16x16x32_bf16 v[64:67], v[218:221], v[20:23], v[112:115]
	v_mfma_f32_16x16x32_bf16 v[20:23], v[226:229], v[20:23], v[34:37]
	v_mfma_f32_16x16x32_bf16 v[120:123], v[150:153], v[28:31], v[20:23]
	v_mfma_f32_16x16x32_bf16 v[20:23], v[218:221], v[230:233], v[38:41]
	v_mfma_f32_16x16x32_bf16 v[112:115], v[222:225], v[234:237], v[20:23]
	v_mfma_f32_16x16x32_bf16 v[20:23], v[226:229], v[230:233], v[42:45]
	v_mfma_f32_16x16x32_bf16 v[104:107], v[150:153], v[234:237], v[20:23]
	v_mfma_f32_16x16x32_bf16 v[20:23], v[218:221], v[238:241], v[46:49]
	v_mfma_f32_16x16x32_bf16 v[96:99], v[222:225], v[242:245], v[20:23]
	v_mfma_f32_16x16x32_bf16 v[20:23], v[226:229], v[238:241], v[50:53]
	v_mfma_f32_16x16x32_bf16 v[88:91], v[150:153], v[242:245], v[20:23]
	v_mfma_f32_16x16x32_bf16 v[20:23], v[218:221], v[246:249], v[54:57]
	v_mfma_f32_16x16x32_bf16 v[80:83], v[222:225], v[250:253], v[20:23]
	v_mfma_f32_16x16x32_bf16 v[20:23], v[226:229], v[246:249], v[154:157]
	v_mfma_f32_16x16x32_bf16 v[128:131], v[222:225], v[28:31], v[64:67]
	v_mfma_f32_16x16x32_bf16 v[68:71], v[150:153], v[250:253], v[20:23]
	s_barrier
	s_setprio 1
	s_add_u32 s6, s30, 0x180
	s_addc_u32 s7, s31, 0
	s_mov_b32 m0, s43
	ds_read_b128 v[32:35], v149 offset:49152
	ds_read_b128 v[40:43], v149 offset:50176
	ds_read_b128 v[154:157], v149 offset:51200
	ds_read_b128 v[230:233], v149 offset:52224
	ds_read_b128 v[234:237], v149 offset:53248
	ds_read_b128 v[238:241], v149 offset:54272
	ds_read_b128 v[242:245], v149 offset:55296
	ds_read_b128 v[246:249], v149 offset:56320
	s_nop 0
	global_load_lds_dwordx4 v136, s[6:7]
	s_mov_b64 s[98:99], s[6:7]
	s_add_u32 s6, s30, 0x40180
	s_mov_b32 m0, s42
	s_addc_u32 s7, s31, 0
	global_load_lds_dwordx4 v132, s[98:99]
	s_mov_b32 m0, s40
	s_nop 0
	global_load_lds_dwordx4 v136, s[6:7]
	s_mov_b32 m0, s41
	s_nop 0
	global_load_lds_dwordx4 v132, s[6:7]
	s_mov_b32 m0, s87
	s_nop 0
	global_load_lds_dwordx4 v138, s[8:9]
	s_mov_b32 m0, s88
	s_nop 0
	global_load_lds_dwordx4 v134, s[8:9]
	s_setprio 0
	s_waitcnt vmcnt(18)
	s_waitcnt lgkmcnt(0)
	s_barrier
	s_waitcnt lgkmcnt(0)
	v_mfma_f32_16x16x32_bf16 v[20:23], v[10:13], v[32:35], v[158:161]
	v_mfma_f32_16x16x32_bf16 v[64:67], v[24:27], v[40:43], v[20:23]
	v_mfma_f32_16x16x32_bf16 v[20:23], v[210:213], v[32:35], v[162:165]
	v_mfma_f32_16x16x32_bf16 v[52:55], v[214:217], v[40:43], v[20:23]
	v_mfma_f32_16x16x32_bf16 v[20:23], v[10:13], v[154:157], v[166:169]
	v_mfma_f32_16x16x32_bf16 v[44:47], v[24:27], v[230:233], v[20:23]
	v_mfma_f32_16x16x32_bf16 v[20:23], v[210:213], v[154:157], v[170:173]
	v_mfma_f32_16x16x32_bf16 v[36:39], v[214:217], v[230:233], v[20:23]
	v_mfma_f32_16x16x32_bf16 v[20:23], v[10:13], v[234:237], v[174:177]
	v_mfma_f32_16x16x32_bf16 v[2:5], v[10:13], v[242:245], v[2:5]
	v_mfma_f32_16x16x32_bf16 v[28:31], v[24:27], v[238:241], v[20:23]
	v_mfma_f32_16x16x32_bf16 v[20:23], v[210:213], v[234:237], v[178:181]
	v_mfma_f32_16x16x32_bf16 v[12:15], v[24:27], v[246:249], v[2:5]
	v_mfma_f32_16x16x32_bf16 v[2:5], v[210:213], v[242:245], v[6:9]
	v_mfma_f32_16x16x32_bf16 v[20:23], v[214:217], v[238:241], v[20:23]
	v_mfma_f32_16x16x32_bf16 v[4:7], v[214:217], v[246:249], v[2:5]
	v_mfma_f32_16x16x32_bf16 v[8:11], v[218:221], v[32:35], v[182:185]
	v_mfma_f32_16x16x32_bf16 v[72:75], v[222:225], v[40:43], v[8:11]
	v_mfma_f32_16x16x32_bf16 v[8:11], v[226:229], v[32:35], v[186:189]
	v_mfma_f32_16x16x32_bf16 v[56:59], v[150:153], v[40:43], v[8:11]
	v_mfma_f32_16x16x32_bf16 v[8:11], v[218:221], v[154:157], v[190:193]
	v_mfma_f32_16x16x32_bf16 v[48:51], v[222:225], v[230:233], v[8:11]
	v_mfma_f32_16x16x32_bf16 v[8:11], v[226:229], v[154:157], v[194:197]
	v_mfma_f32_16x16x32_bf16 v[40:43], v[150:153], v[230:233], v[8:11]
	v_mfma_f32_16x16x32_bf16 v[8:11], v[218:221], v[234:237], v[198:201]
	v_mfma_f32_16x16x32_bf16 v[32:35], v[222:225], v[238:241], v[8:11]
	v_mfma_f32_16x16x32_bf16 v[8:11], v[226:229], v[234:237], v[202:205]
	v_mfma_f32_16x16x32_bf16 v[24:27], v[150:153], v[238:241], v[8:11]
	v_mfma_f32_16x16x32_bf16 v[8:11], v[218:221], v[242:245], v[16:19]
	v_mfma_f32_16x16x32_bf16 v[16:19], v[222:225], v[246:249], v[8:11]
	v_mfma_f32_16x16x32_bf16 v[8:11], v[226:229], v[242:245], v[206:209]
	v_mfma_f32_16x16x32_bf16 v[8:11], v[150:153], v[246:249], v[8:11]
	s_barrier
	s_mov_b64 s[8:9], 0

; template <class Epi, class Sched, bool ALIGN_EPI = false, bool SP2 = false>
; __device__ __forceinline__ void gemm_phase(PG8_LAS unsigned char* lds, const Gemm g, const Sched& S, const Epi& E, int wave_s) {
;     ...
;         for (int t = peeled ? 2 : 0; t < nt; t += 2) {
;             const bool last = (t == nt - 2);
;             const char* a1 = cA + (size_t)(t + 1) * kstep;
;             const char* a2 = last ? nA : cA + (size_t)(t + 2) * kstep; const char* b2 = last ? nB : cB + (size_t)(t + 2) * kstep;
;             const char* a3 = a2 + kstep; const char* b3 = b2 + kstep;
;             if (last && has_next) S.a_ready(nxt);
.LBB0_1278:
	v_add_u32_e32 v151, s90, v146
	v_add_u32_e32 v150, s91, v146
	ds_read_b128 v[152:155], v151
	ds_read_b128 v[156:159], v151 offset:1024
	ds_read_b128 v[160:163], v151 offset:2048
	ds_read_b128 v[164:167], v151 offset:3072
	ds_read_b128 v[168:171], v150
	ds_read_b128 v[172:175], v150 offset:1024
	ds_read_b128 v[176:179], v150 offset:2048
	ds_read_b128 v[180:183], v150 offset:3072
	s_add_u32 s36, s70, 0x100
	s_addc_u32 s37, s71, 0
	s_cmp_eq_u32 vcc_hi, 12
	s_cselect_b32 s42, s96, s36
	s_cselect_b32 s43, s95, s37
	s_cselect_b32 s40, vcc_lo, s6
	s_cselect_b32 s41, s97, s7
	s_add_u32 s38, s42, 0x80
	s_addc_u32 s39, s43, 0
	s_add_u32 s60, s70, 0x40080
	s_addc_u32 s61, s71, 0
	s_add_i32 s94, s77, 0xc000
	ds_read_b128 v[184:187], v149
	ds_read_b128 v[188:191], v149 offset:1024
	ds_read_b128 v[192:195], v149 offset:2048
	ds_read_b128 v[196:199], v149 offset:3072
	ds_read_b128 v[200:203], v149 offset:4096
	ds_read_b128 v[204:207], v149 offset:5120
	ds_read_b128 v[208:211], v149 offset:6144
	ds_read_b128 v[212:215], v149 offset:7168
	s_mov_b32 m0, s94
	s_add_i32 s12, s77, 0xe000
	global_load_lds_dwordx4 v138, s[60:61]
	s_mov_b32 m0, s12
	s_nop 0
	global_load_lds_dwordx4 v134, s[60:61]
	s_waitcnt vmcnt(8)
	s_waitcnt lgkmcnt(0)
	s_barrier
	s_waitcnt lgkmcnt(0)
	v_mfma_f32_16x16x32_bf16 v[124:127], v[152:155], v[184:187], v[124:127]
	v_mfma_f32_16x16x32_bf16 v[116:119], v[160:163], v[184:187], v[116:119]
	v_mfma_f32_16x16x32_bf16 v[108:111], v[152:155], v[192:195], v[108:111]
	v_mfma_f32_16x16x32_bf16 v[100:103], v[160:163], v[192:195], v[100:103]
	v_mfma_f32_16x16x32_bf16 v[92:95], v[152:155], v[200:203], v[92:95]
	v_mfma_f32_16x16x32_bf16 v[84:87], v[160:163], v[200:203], v[84:87]
	v_mfma_f32_16x16x32_bf16 v[76:79], v[152:155], v[208:211], v[76:79]
	v_mfma_f32_16x16x32_bf16 v[60:63], v[160:163], v[208:211], v[60:63]
	v_mfma_f32_16x16x32_bf16 v[124:127], v[156:159], v[188:191], v[124:127]
	v_mfma_f32_16x16x32_bf16 v[116:119], v[164:167], v[188:191], v[116:119]
	v_mfma_f32_16x16x32_bf16 v[108:111], v[156:159], v[196:199], v[108:111]
	v_mfma_f32_16x16x32_bf16 v[100:103], v[164:167], v[196:199], v[100:103]
	v_mfma_f32_16x16x32_bf16 v[92:95], v[156:159], v[204:207], v[92:95]
	v_mfma_f32_16x16x32_bf16 v[84:87], v[164:167], v[204:207], v[84:87]
	v_mfma_f32_16x16x32_bf16 v[76:79], v[156:159], v[212:215], v[76:79]
	v_mfma_f32_16x16x32_bf16 v[60:63], v[164:167], v[212:215], v[60:63]
	v_mfma_f32_16x16x32_bf16 v[128:131], v[168:171], v[184:187], v[128:131]
	v_mfma_f32_16x16x32_bf16 v[120:123], v[176:179], v[184:187], v[120:123]
	v_mfma_f32_16x16x32_bf16 v[112:115], v[168:171], v[192:195], v[112:115]
	v_mfma_f32_16x16x32_bf16 v[104:107], v[176:179], v[192:195], v[104:107]
	v_mfma_f32_16x16x32_bf16 v[96:99], v[168:171], v[200:203], v[96:99]
	v_mfma_f32_16x16x32_bf16 v[88:91], v[176:179], v[200:203], v[88:91]
	v_mfma_f32_16x16x32_bf16 v[80:83], v[168:171], v[208:211], v[80:83]
	v_mfma_f32_16x16x32_bf16 v[68:71], v[176:179], v[208:211], v[68:71]
	v_mfma_f32_16x16x32_bf16 v[128:131], v[172:175], v[188:191], v[128:131]
	v_mfma_f32_16x16x32_bf16 v[120:123], v[180:183], v[188:191], v[120:123]
	v_mfma_f32_16x16x32_bf16 v[112:115], v[172:175], v[196:199], v[112:115]
	v_mfma_f32_16x16x32_bf16 v[104:107], v[180:183], v[196:199], v[104:107]
	v_mfma_f32_16x16x32_bf16 v[96:99], v[172:175], v[204:207], v[96:99]
	v_mfma_f32_16x16x32_bf16 v[88:91], v[180:183], v[204:207], v[88:91]
	v_mfma_f32_16x16x32_bf16 v[80:83], v[172:175], v[212:215], v[80:83]
	v_mfma_f32_16x16x32_bf16 v[68:71], v[180:183], v[212:215], v[68:71]
	s_barrier
	s_setprio 1
	s_mov_b64 s[70:71], s[40:41]
	s_add_i32 s61, s90, s72
	ds_read_b128 v[184:187], v149 offset:16384
	ds_read_b128 v[188:191], v149 offset:17408
	ds_read_b128 v[192:195], v149 offset:18432
	ds_read_b128 v[196:199], v149 offset:19456
	ds_read_b128 v[200:203], v149 offset:20480
	ds_read_b128 v[204:207], v149 offset:21504
	ds_read_b128 v[208:211], v149 offset:22528
	ds_read_b128 v[212:215], v149 offset:23552
	s_mov_b32 m0, s61
	s_add_i32 s25, s61, 0x2000
	global_load_lds_dwordx4 v136, s[70:71]
	s_mov_b64 s[98:99], s[70:71]
	s_add_u32 s70, s40, 0x40000
	s_mov_b32 m0, s25
	s_addc_u32 s71, s41, 0
	s_add_i32 s27, s91, s72
	global_load_lds_dwordx4 v132, s[98:99]
	s_mov_b32 m0, s27
	s_add_i32 s60, s27, 0x2000
	global_load_lds_dwordx4 v136, s[70:71]
	s_mov_b64 s[98:99], s[70:71]
	s_mov_b32 m0, s60
	s_mov_b64 s[70:71], s[42:43]
	global_load_lds_dwordx4 v132, s[98:99]
	s_mov_b32 m0, s77
	s_nop 0
	global_load_lds_dwordx4 v138, s[70:71]
	s_mov_b32 m0, s78
	s_nop 0
	global_load_lds_dwordx4 v134, s[70:71]
	s_setprio 0
	s_waitcnt vmcnt(8)
	s_waitcnt lgkmcnt(0)
	s_barrier
	s_waitcnt lgkmcnt(0)
	v_mfma_f32_16x16x32_bf16 v[64:67], v[152:155], v[184:187], v[64:67]
	v_mfma_f32_16x16x32_bf16 v[52:55], v[160:163], v[184:187], v[52:55]
	v_mfma_f32_16x16x32_bf16 v[44:47], v[152:155], v[192:195], v[44:47]
	v_mfma_f32_16x16x32_bf16 v[36:39], v[160:163], v[192:195], v[36:39]
	v_mfma_f32_16x16x32_bf16 v[28:31], v[152:155], v[200:203], v[28:31]
	v_mfma_f32_16x16x32_bf16 v[20:23], v[160:163], v[200:203], v[20:23]
	v_mfma_f32_16x16x32_bf16 v[12:15], v[152:155], v[208:211], v[12:15]
	v_mfma_f32_16x16x32_bf16 v[2:5], v[160:163], v[208:211], v[4:7]
	v_mfma_f32_16x16x32_bf16 v[64:67], v[156:159], v[188:191], v[64:67]
	v_mfma_f32_16x16x32_bf16 v[52:55], v[164:167], v[188:191], v[52:55]
	v_mfma_f32_16x16x32_bf16 v[44:47], v[156:159], v[196:199], v[44:47]
	v_mfma_f32_16x16x32_bf16 v[36:39], v[164:167], v[196:199], v[36:39]
	v_mfma_f32_16x16x32_bf16 v[28:31], v[156:159], v[204:207], v[28:31]
	v_mfma_f32_16x16x32_bf16 v[20:23], v[164:167], v[204:207], v[20:23]
	v_mfma_f32_16x16x32_bf16 v[12:15], v[156:159], v[212:215], v[12:15]
	v_mfma_f32_16x16x32_bf16 v[2:5], v[164:167], v[212:215], v[2:5]
	v_mfma_f32_16x16x32_bf16 v[72:75], v[168:171], v[184:187], v[72:75]
	v_mfma_f32_16x16x32_bf16 v[56:59], v[176:179], v[184:187], v[56:59]
	v_mfma_f32_16x16x32_bf16 v[48:51], v[168:171], v[192:195], v[48:51]
	v_mfma_f32_16x16x32_bf16 v[40:43], v[176:179], v[192:195], v[40:43]
	v_mfma_f32_16x16x32_bf16 v[32:35], v[168:171], v[200:203], v[32:35]
	v_mfma_f32_16x16x32_bf16 v[24:27], v[176:179], v[200:203], v[24:27]
	v_mfma_f32_16x16x32_bf16 v[16:19], v[168:171], v[208:211], v[16:19]
	v_mfma_f32_16x16x32_bf16 v[6:9], v[176:179], v[208:211], v[8:11]
	v_mfma_f32_16x16x32_bf16 v[72:75], v[172:175], v[188:191], v[72:75]
	v_mfma_f32_16x16x32_bf16 v[56:59], v[180:183], v[188:191], v[56:59]
	v_mfma_f32_16x16x32_bf16 v[48:51], v[172:175], v[196:199], v[48:51]
	v_mfma_f32_16x16x32_bf16 v[40:43], v[180:183], v[196:199], v[40:43]
	v_mfma_f32_16x16x32_bf16 v[32:35], v[172:175], v[204:207], v[32:35]
	v_mfma_f32_16x16x32_bf16 v[24:27], v[180:183], v[204:207], v[24:27]
	v_mfma_f32_16x16x32_bf16 v[16:19], v[172:175], v[212:215], v[16:19]
	v_mfma_f32_16x16x32_bf16 v[8:11], v[180:183], v[212:215], v[6:9]
	s_barrier
	s_add_i32 s86, 0, 0x18000
	s_add_i32 s85, 0, 0x1c000
	v_add_u32_e32 v152, s86, v146
	v_add_u32_e32 v153, s85, v146
	ds_read_b128 v[154:157], v152
	ds_read_b128 v[158:161], v152 offset:1024
	ds_read_b128 v[162:165], v152 offset:2048
	ds_read_b128 v[166:169], v152 offset:3072
	ds_read_b128 v[170:173], v153
	ds_read_b128 v[174:177], v153 offset:1024
	ds_read_b128 v[178:181], v153 offset:2048
	ds_read_b128 v[182:185], v153 offset:3072
	s_add_u32 s42, s42, 0x40000
	s_addc_u32 s43, s43, 0
	s_mov_b32 m0, s79
	ds_read_b128 v[186:189], v149 offset:32768
	ds_read_b128 v[190:193], v149 offset:33792
	ds_read_b128 v[194:197], v149 offset:34816
	ds_read_b128 v[198:201], v149 offset:35840
	ds_read_b128 v[202:205], v149 offset:36864
	ds_read_b128 v[206:209], v149 offset:37888
	ds_read_b128 v[210:213], v149 offset:38912
	ds_read_b128 v[214:217], v149 offset:39936
	s_nop 0
	global_load_lds_dwordx4 v138, s[42:43]
	s_mov_b32 m0, s82
	s_nop 0
	global_load_lds_dwordx4 v134, s[42:43]
	s_waitcnt vmcnt(8)
	s_waitcnt lgkmcnt(0)
	s_barrier
	s_waitcnt lgkmcnt(0)
	v_mfma_f32_16x16x32_bf16 v[124:127], v[154:157], v[186:189], v[124:127]
	v_mfma_f32_16x16x32_bf16 v[116:119], v[162:165], v[186:189], v[116:119]
	v_mfma_f32_16x16x32_bf16 v[108:111], v[154:157], v[194:197], v[108:111]
	v_mfma_f32_16x16x32_bf16 v[100:103], v[162:165], v[194:197], v[100:103]
	v_mfma_f32_16x16x32_bf16 v[92:95], v[154:157], v[202:205], v[92:95]
	v_mfma_f32_16x16x32_bf16 v[84:87], v[162:165], v[202:205], v[84:87]
	v_mfma_f32_16x16x32_bf16 v[76:79], v[154:157], v[210:213], v[76:79]
	v_mfma_f32_16x16x32_bf16 v[60:63], v[162:165], v[210:213], v[60:63]
	v_mfma_f32_16x16x32_bf16 v[124:127], v[158:161], v[190:193], v[124:127]
	v_mfma_f32_16x16x32_bf16 v[116:119], v[166:169], v[190:193], v[116:119]
	v_mfma_f32_16x16x32_bf16 v[108:111], v[158:161], v[198:201], v[108:111]
	v_mfma_f32_16x16x32_bf16 v[100:103], v[166:169], v[198:201], v[100:103]
	v_mfma_f32_16x16x32_bf16 v[92:95], v[158:161], v[206:209], v[92:95]
	v_mfma_f32_16x16x32_bf16 v[84:87], v[166:169], v[206:209], v[84:87]
	v_mfma_f32_16x16x32_bf16 v[76:79], v[158:161], v[214:217], v[76:79]
	v_mfma_f32_16x16x32_bf16 v[60:63], v[166:169], v[214:217], v[60:63]
	v_mfma_f32_16x16x32_bf16 v[128:131], v[170:173], v[186:189], v[128:131]
	v_mfma_f32_16x16x32_bf16 v[120:123], v[178:181], v[186:189], v[120:123]
	v_mfma_f32_16x16x32_bf16 v[112:115], v[170:173], v[194:197], v[112:115]
	v_mfma_f32_16x16x32_bf16 v[104:107], v[178:181], v[194:197], v[104:107]
	v_mfma_f32_16x16x32_bf16 v[96:99], v[170:173], v[202:205], v[96:99]
	v_mfma_f32_16x16x32_bf16 v[88:91], v[178:181], v[202:205], v[88:91]
	v_mfma_f32_16x16x32_bf16 v[80:83], v[170:173], v[210:213], v[80:83]
	v_mfma_f32_16x16x32_bf16 v[68:71], v[178:181], v[210:213], v[68:71]
	v_mfma_f32_16x16x32_bf16 v[128:131], v[174:177], v[190:193], v[128:131]
	v_mfma_f32_16x16x32_bf16 v[120:123], v[182:185], v[190:193], v[120:123]
	v_mfma_f32_16x16x32_bf16 v[112:115], v[174:177], v[198:201], v[112:115]
	v_mfma_f32_16x16x32_bf16 v[104:107], v[182:185], v[198:201], v[104:107]
	v_mfma_f32_16x16x32_bf16 v[96:99], v[174:177], v[206:209], v[96:99]
	v_mfma_f32_16x16x32_bf16 v[88:91], v[182:185], v[206:209], v[88:91]
	v_mfma_f32_16x16x32_bf16 v[80:83], v[174:177], v[214:217], v[80:83]
	v_mfma_f32_16x16x32_bf16 v[68:71], v[182:185], v[214:217], v[68:71]
	s_barrier
	s_setprio 1
	s_add_u32 s70, s40, 0x80
	s_addc_u32 s71, s41, 0
	s_add_i32 s43, s86, s72
	ds_read_b128 v[186:189], v149 offset:49152
	ds_read_b128 v[190:193], v149 offset:50176
	ds_read_b128 v[194:197], v149 offset:51200
	ds_read_b128 v[198:201], v149 offset:52224
	ds_read_b128 v[202:205], v149 offset:53248
	ds_read_b128 v[206:209], v149 offset:54272
	ds_read_b128 v[210:213], v149 offset:55296
	ds_read_b128 v[214:217], v149 offset:56320
	s_mov_b32 m0, s43
	s_add_i32 s42, s43, 0x2000
	global_load_lds_dwordx4 v136, s[70:71]
	s_mov_b64 s[98:99], s[70:71]
	s_add_u32 s70, s40, 0x40080
	s_mov_b32 m0, s42
	s_addc_u32 s71, s41, 0
	s_add_i32 s40, s85, s72
	global_load_lds_dwordx4 v132, s[98:99]
	s_mov_b32 m0, s40
	s_add_i32 s41, s40, 0x2000
	global_load_lds_dwordx4 v136, s[70:71]
	s_mov_b32 m0, s41
	s_nop 0
	global_load_lds_dwordx4 v132, s[70:71]
	s_mov_b32 m0, s87
	s_nop 0
	global_load_lds_dwordx4 v138, s[38:39]
	s_mov_b32 m0, s88
	s_nop 0
	global_load_lds_dwordx4 v134, s[38:39]
	s_setprio 0
	s_waitcnt vmcnt(8)
	s_waitcnt lgkmcnt(0)
	s_barrier
	s_waitcnt lgkmcnt(0)
	v_mfma_f32_16x16x32_bf16 v[64:67], v[154:157], v[186:189], v[64:67]
	v_mfma_f32_16x16x32_bf16 v[52:55], v[162:165], v[186:189], v[52:55]
	v_mfma_f32_16x16x32_bf16 v[44:47], v[154:157], v[194:197], v[44:47]
	v_mfma_f32_16x16x32_bf16 v[36:39], v[162:165], v[194:197], v[36:39]
	v_mfma_f32_16x16x32_bf16 v[28:31], v[154:157], v[202:205], v[28:31]
	v_mfma_f32_16x16x32_bf16 v[20:23], v[162:165], v[202:205], v[20:23]
	v_mfma_f32_16x16x32_bf16 v[12:15], v[154:157], v[210:213], v[12:15]
	v_mfma_f32_16x16x32_bf16 v[2:5], v[162:165], v[210:213], v[2:5]
	v_mfma_f32_16x16x32_bf16 v[64:67], v[158:161], v[190:193], v[64:67]
	v_mfma_f32_16x16x32_bf16 v[52:55], v[166:169], v[190:193], v[52:55]
	v_mfma_f32_16x16x32_bf16 v[44:47], v[158:161], v[198:201], v[44:47]
	v_mfma_f32_16x16x32_bf16 v[36:39], v[166:169], v[198:201], v[36:39]
	v_mfma_f32_16x16x32_bf16 v[28:31], v[158:161], v[206:209], v[28:31]
	v_mfma_f32_16x16x32_bf16 v[20:23], v[166:169], v[206:209], v[20:23]
	v_mfma_f32_16x16x32_bf16 v[12:15], v[158:161], v[214:217], v[12:15]
	v_mfma_f32_16x16x32_bf16 v[4:7], v[166:169], v[214:217], v[2:5]
	v_mfma_f32_16x16x32_bf16 v[72:75], v[170:173], v[186:189], v[72:75]
	v_mfma_f32_16x16x32_bf16 v[56:59], v[178:181], v[186:189], v[56:59]
	v_mfma_f32_16x16x32_bf16 v[48:51], v[170:173], v[194:197], v[48:51]
	v_mfma_f32_16x16x32_bf16 v[40:43], v[178:181], v[194:197], v[40:43]
	v_mfma_f32_16x16x32_bf16 v[32:35], v[170:173], v[202:205], v[32:35]
	v_mfma_f32_16x16x32_bf16 v[24:27], v[178:181], v[202:205], v[24:27]
	v_mfma_f32_16x16x32_bf16 v[16:19], v[170:173], v[210:213], v[16:19]
	v_mfma_f32_16x16x32_bf16 v[8:11], v[178:181], v[210:213], v[8:11]
	v_mfma_f32_16x16x32_bf16 v[72:75], v[174:177], v[190:193], v[72:75]
	v_mfma_f32_16x16x32_bf16 v[56:59], v[182:185], v[190:193], v[56:59]
	v_mfma_f32_16x16x32_bf16 v[48:51], v[174:177], v[198:201], v[48:51]
	v_mfma_f32_16x16x32_bf16 v[40:43], v[182:185], v[198:201], v[40:43]
	v_mfma_f32_16x16x32_bf16 v[32:35], v[174:177], v[206:209], v[32:35]
	v_mfma_f32_16x16x32_bf16 v[24:27], v[182:185], v[206:209], v[24:27]
	v_mfma_f32_16x16x32_bf16 v[16:19], v[174:177], v[214:217], v[16:19]
	v_mfma_f32_16x16x32_bf16 v[8:11], v[182:185], v[214:217], v[8:11]
	s_barrier
	s_add_i32 vcc_hi, vcc_hi, 2
	s_add_u32 s6, s6, 0x100
	s_addc_u32 s7, s7, 0
	s_cmp_gt_u32 vcc_hi, 13
	s_mov_b64 s[70:71], s[36:37]
	s_cbranch_scc0 .LBB0_1278
	s_and_b64 vcc, exec, s[22:23]
	s_cbranch_vccz .LBB0_1281
	s_barrier

; template <class Epi, class Sched, bool ALIGN_EPI = false, bool SP2 = false>
; __device__ __forceinline__ void gemm_phase(PG8_LAS unsigned char* lds, const Gemm g, const Sched& S, const Epi& E, int wave_s) {
;     ...
;             const bool last = (t == nt - 2);
;             const char* a1 = cA + (size_t)(t + 1) * kstep;
;             const char* a2 = last ? nA : cA + (size_t)(t + 2) * kstep; const char* b2 = last ? nB : cB + (size_t)(t + 2) * kstep;
;             const char* a3 = a2 + kstep; const char* b3 = b2 + kstep;
.LBB0_1666:
	ds_read_b128 v[140:143], v147
	ds_read_b128 v[160:163], v147 offset:1024
	ds_read_b128 v[164:167], v147 offset:2048
	ds_read_b128 v[168:171], v147 offset:3072
	ds_read_b128 v[172:175], v148
	ds_read_b128 v[176:179], v148 offset:1024
	ds_read_b128 v[180:183], v148 offset:2048
	ds_read_b128 v[184:187], v148 offset:3072
	s_add_u32 s34, s30, 0x100
	s_addc_u32 s35, s31, 0
	s_cmp_eq_u32 s77, 40
	s_cselect_b32 s40, s12, s34
	s_cselect_b32 s41, s13, s35
	s_cselect_b32 s38, s28, s60
	s_cselect_b32 s39, s29, s61
	s_add_u32 s36, s40, 0x80
	s_addc_u32 s37, s41, 0
	s_add_u32 s6, s30, 0xb0080
	s_addc_u32 s7, s31, 0
	ds_read_b128 v[188:191], v149
	ds_read_b128 v[192:195], v149 offset:1024
	ds_read_b128 v[196:199], v149 offset:2048
	ds_read_b128 v[200:203], v149 offset:3072
	ds_read_b128 v[204:207], v149 offset:4096
	ds_read_b128 v[208:211], v149 offset:5120
	ds_read_b128 v[212:215], v149 offset:6144
	ds_read_b128 v[216:219], v149 offset:7168
	s_add_i32 m0, s57, 0xc000
	s_nop 0
	global_load_lds_dwordx4 v128, s[6:7]
	s_add_i32 m0, s57, 0xe000
	s_nop 0
	global_load_lds_dwordx4 v132, s[6:7]
	s_waitcnt vmcnt(8)
	s_waitcnt lgkmcnt(0)
	s_barrier
	s_waitcnt lgkmcnt(0)
	v_mfma_f32_16x16x32_bf16 v[124:127], v[140:143], v[188:191], v[124:127]
	v_mfma_f32_16x16x32_bf16 v[120:123], v[164:167], v[188:191], v[120:123]
	v_mfma_f32_16x16x32_bf16 v[108:111], v[140:143], v[196:199], v[108:111]
	v_mfma_f32_16x16x32_bf16 v[104:107], v[164:167], v[196:199], v[104:107]
	v_mfma_f32_16x16x32_bf16 v[92:95], v[140:143], v[204:207], v[92:95]
	v_mfma_f32_16x16x32_bf16 v[88:91], v[164:167], v[204:207], v[88:91]
	v_mfma_f32_16x16x32_bf16 v[76:79], v[140:143], v[212:215], v[76:79]
	v_mfma_f32_16x16x32_bf16 v[72:75], v[164:167], v[212:215], v[72:75]
	v_mfma_f32_16x16x32_bf16 v[124:127], v[160:163], v[192:195], v[124:127]
	v_mfma_f32_16x16x32_bf16 v[120:123], v[168:171], v[192:195], v[120:123]
	v_mfma_f32_16x16x32_bf16 v[108:111], v[160:163], v[200:203], v[108:111]
	v_mfma_f32_16x16x32_bf16 v[104:107], v[168:171], v[200:203], v[104:107]
	v_mfma_f32_16x16x32_bf16 v[92:95], v[160:163], v[208:211], v[92:95]
	v_mfma_f32_16x16x32_bf16 v[88:91], v[168:171], v[208:211], v[88:91]
	v_mfma_f32_16x16x32_bf16 v[76:79], v[160:163], v[216:219], v[76:79]
	v_mfma_f32_16x16x32_bf16 v[72:75], v[168:171], v[216:219], v[72:75]
	v_mfma_f32_16x16x32_bf16 v[116:119], v[172:175], v[188:191], v[116:119]
	v_mfma_f32_16x16x32_bf16 v[112:115], v[180:183], v[188:191], v[112:115]
	v_mfma_f32_16x16x32_bf16 v[100:103], v[172:175], v[196:199], v[100:103]
	v_mfma_f32_16x16x32_bf16 v[96:99], v[180:183], v[196:199], v[96:99]
	v_mfma_f32_16x16x32_bf16 v[84:87], v[172:175], v[204:207], v[84:87]
	v_mfma_f32_16x16x32_bf16 v[80:83], v[180:183], v[204:207], v[80:83]
	v_mfma_f32_16x16x32_bf16 v[68:71], v[172:175], v[212:215], v[68:71]
	v_mfma_f32_16x16x32_bf16 v[64:67], v[180:183], v[212:215], v[64:67]
	v_mfma_f32_16x16x32_bf16 v[116:119], v[176:179], v[192:195], v[116:119]
	v_mfma_f32_16x16x32_bf16 v[112:115], v[184:187], v[192:195], v[112:115]
	v_mfma_f32_16x16x32_bf16 v[100:103], v[176:179], v[200:203], v[100:103]
	v_mfma_f32_16x16x32_bf16 v[96:99], v[184:187], v[200:203], v[96:99]
	v_mfma_f32_16x16x32_bf16 v[84:87], v[176:179], v[208:211], v[84:87]
	v_mfma_f32_16x16x32_bf16 v[80:83], v[184:187], v[208:211], v[80:83]
	v_mfma_f32_16x16x32_bf16 v[68:71], v[176:179], v[216:219], v[68:71]
	v_mfma_f32_16x16x32_bf16 v[64:67], v[184:187], v[216:219], v[64:67]
	s_barrier
	s_setprio 1
	s_mov_b64 s[6:7], s[38:39]
	s_add_i32 s30, s71, s56
	ds_read_b128 v[188:191], v149 offset:16384
	ds_read_b128 v[192:195], v149 offset:17408
	ds_read_b128 v[196:199], v149 offset:18432
	ds_read_b128 v[200:203], v149 offset:19456
	ds_read_b128 v[204:207], v149 offset:20480
	ds_read_b128 v[208:211], v149 offset:21504
	ds_read_b128 v[212:215], v149 offset:22528
	ds_read_b128 v[216:219], v149 offset:23552
	s_mov_b32 m0, s30
	s_nop 0
	global_load_lds_dwordx4 v130, s[6:7]
	s_add_i32 m0, s30, 0x2000
	s_nop 0
	global_load_lds_dwordx4 v134, s[6:7]
	s_add_u32 s6, s38, 0xb0000
	s_addc_u32 s7, s39, 0
	s_add_i32 s30, s72, s56
	s_mov_b32 m0, s30
	s_nop 0
	global_load_lds_dwordx4 v130, s[6:7]
	s_mov_b64 s[98:99], s[6:7]
	s_add_i32 m0, s30, 0x2000
	s_mov_b64 s[6:7], s[40:41]
	global_load_lds_dwordx4 v134, s[98:99]
	s_mov_b32 m0, s57
	s_nop 0
	global_load_lds_dwordx4 v128, s[6:7]
	s_mov_b32 m0, s62
	s_nop 0
	global_load_lds_dwordx4 v132, s[6:7]
	s_setprio 0
	s_waitcnt vmcnt(8)
	s_waitcnt lgkmcnt(0)
	s_barrier
	s_waitcnt lgkmcnt(0)
	v_mfma_f32_16x16x32_bf16 v[60:63], v[140:143], v[188:191], v[60:63]
	v_mfma_f32_16x16x32_bf16 v[56:59], v[164:167], v[188:191], v[56:59]
	v_mfma_f32_16x16x32_bf16 v[44:47], v[140:143], v[196:199], v[44:47]
	v_mfma_f32_16x16x32_bf16 v[40:43], v[164:167], v[196:199], v[40:43]
	v_mfma_f32_16x16x32_bf16 v[28:31], v[140:143], v[204:207], v[28:31]
	v_mfma_f32_16x16x32_bf16 v[24:27], v[164:167], v[204:207], v[24:27]
	v_mfma_f32_16x16x32_bf16 v[12:15], v[140:143], v[212:215], v[12:15]
	v_mfma_f32_16x16x32_bf16 v[8:11], v[164:167], v[212:215], v[8:11]
	v_mfma_f32_16x16x32_bf16 v[60:63], v[160:163], v[192:195], v[60:63]
	v_mfma_f32_16x16x32_bf16 v[56:59], v[168:171], v[192:195], v[56:59]
	v_mfma_f32_16x16x32_bf16 v[44:47], v[160:163], v[200:203], v[44:47]
	v_mfma_f32_16x16x32_bf16 v[40:43], v[168:171], v[200:203], v[40:43]
	v_mfma_f32_16x16x32_bf16 v[28:31], v[160:163], v[208:211], v[28:31]
	v_mfma_f32_16x16x32_bf16 v[24:27], v[168:171], v[208:211], v[24:27]
	v_mfma_f32_16x16x32_bf16 v[12:15], v[160:163], v[216:219], v[12:15]
	v_mfma_f32_16x16x32_bf16 v[8:11], v[168:171], v[216:219], v[8:11]
	v_mfma_f32_16x16x32_bf16 v[52:55], v[172:175], v[188:191], v[52:55]
	v_mfma_f32_16x16x32_bf16 v[48:51], v[180:183], v[188:191], v[48:51]
	v_mfma_f32_16x16x32_bf16 v[36:39], v[172:175], v[196:199], v[36:39]
	v_mfma_f32_16x16x32_bf16 v[32:35], v[180:183], v[196:199], v[32:35]
	v_mfma_f32_16x16x32_bf16 v[20:23], v[172:175], v[204:207], v[20:23]
	v_mfma_f32_16x16x32_bf16 v[16:19], v[180:183], v[204:207], v[16:19]
	v_mfma_f32_16x16x32_bf16 v[4:7], v[172:175], v[212:215], v[4:7]
	v_mfma_f32_16x16x32_bf16 v[0:3], v[180:183], v[212:215], v[0:3]
	v_mfma_f32_16x16x32_bf16 v[52:55], v[176:179], v[192:195], v[52:55]
	v_mfma_f32_16x16x32_bf16 v[48:51], v[184:187], v[192:195], v[48:51]
	v_mfma_f32_16x16x32_bf16 v[36:39], v[176:179], v[200:203], v[36:39]
	v_mfma_f32_16x16x32_bf16 v[32:35], v[184:187], v[200:203], v[32:35]
	v_mfma_f32_16x16x32_bf16 v[20:23], v[176:179], v[208:211], v[20:23]
	v_mfma_f32_16x16x32_bf16 v[16:19], v[184:187], v[208:211], v[16:19]
	v_mfma_f32_16x16x32_bf16 v[4:7], v[176:179], v[216:219], v[4:7]
	v_mfma_f32_16x16x32_bf16 v[0:3], v[184:187], v[216:219], v[0:3]
	s_barrier
	s_add_i32 s30, 0, 0x18000
	v_add_u32_e32 v159, s30, v145
	s_add_i32 s31, 0, 0x1c000
	ds_read_b128 v[140:143], v159
	ds_read_b128 v[160:163], v159 offset:1024
	ds_read_b128 v[164:167], v159 offset:2048
	ds_read_b128 v[168:171], v159 offset:3072
	v_add_u32_e32 v159, s31, v145
	ds_read_b128 v[172:175], v159
	ds_read_b128 v[176:179], v159 offset:1024
	ds_read_b128 v[180:183], v159 offset:2048
	ds_read_b128 v[184:187], v159 offset:3072
	s_add_u32 s6, s40, 0xb0000
	s_addc_u32 s7, s41, 0
	s_mov_b32 m0, s63
	ds_read_b128 v[188:191], v149 offset:32768
	ds_read_b128 v[192:195], v149 offset:33792
	ds_read_b128 v[196:199], v149 offset:34816
	ds_read_b128 v[200:203], v149 offset:35840
	ds_read_b128 v[204:207], v149 offset:36864
	ds_read_b128 v[208:211], v149 offset:37888
	ds_read_b128 v[212:215], v149 offset:38912
	ds_read_b128 v[216:219], v149 offset:39936
	s_nop 0
	global_load_lds_dwordx4 v128, s[6:7]
	s_mov_b32 m0, s64
	s_nop 0
	global_load_lds_dwordx4 v132, s[6:7]
	s_waitcnt vmcnt(8)
	s_waitcnt lgkmcnt(0)
	s_barrier
	s_waitcnt lgkmcnt(0)
	v_mfma_f32_16x16x32_bf16 v[124:127], v[140:143], v[188:191], v[124:127]
	v_mfma_f32_16x16x32_bf16 v[120:123], v[164:167], v[188:191], v[120:123]
	v_mfma_f32_16x16x32_bf16 v[108:111], v[140:143], v[196:199], v[108:111]
	v_mfma_f32_16x16x32_bf16 v[104:107], v[164:167], v[196:199], v[104:107]
	v_mfma_f32_16x16x32_bf16 v[92:95], v[140:143], v[204:207], v[92:95]
	v_mfma_f32_16x16x32_bf16 v[88:91], v[164:167], v[204:207], v[88:91]
	v_mfma_f32_16x16x32_bf16 v[76:79], v[140:143], v[212:215], v[76:79]
	v_mfma_f32_16x16x32_bf16 v[72:75], v[164:167], v[212:215], v[72:75]
	v_mfma_f32_16x16x32_bf16 v[124:127], v[160:163], v[192:195], v[124:127]
	v_mfma_f32_16x16x32_bf16 v[120:123], v[168:171], v[192:195], v[120:123]
	v_mfma_f32_16x16x32_bf16 v[108:111], v[160:163], v[200:203], v[108:111]
	v_mfma_f32_16x16x32_bf16 v[104:107], v[168:171], v[200:203], v[104:107]
	v_mfma_f32_16x16x32_bf16 v[92:95], v[160:163], v[208:211], v[92:95]
	v_mfma_f32_16x16x32_bf16 v[88:91], v[168:171], v[208:211], v[88:91]
	v_mfma_f32_16x16x32_bf16 v[76:79], v[160:163], v[216:219], v[76:79]
	v_mfma_f32_16x16x32_bf16 v[72:75], v[168:171], v[216:219], v[72:75]
	v_mfma_f32_16x16x32_bf16 v[116:119], v[172:175], v[188:191], v[116:119]
	v_mfma_f32_16x16x32_bf16 v[112:115], v[180:183], v[188:191], v[112:115]
	v_mfma_f32_16x16x32_bf16 v[100:103], v[172:175], v[196:199], v[100:103]
	v_mfma_f32_16x16x32_bf16 v[96:99], v[180:183], v[196:199], v[96:99]
	v_mfma_f32_16x16x32_bf16 v[84:87], v[172:175], v[204:207], v[84:87]
	v_mfma_f32_16x16x32_bf16 v[80:83], v[180:183], v[204:207], v[80:83]
	v_mfma_f32_16x16x32_bf16 v[68:71], v[172:175], v[212:215], v[68:71]
	v_mfma_f32_16x16x32_bf16 v[64:67], v[180:183], v[212:215], v[64:67]
	v_mfma_f32_16x16x32_bf16 v[116:119], v[176:179], v[192:195], v[116:119]
	v_mfma_f32_16x16x32_bf16 v[112:115], v[184:187], v[192:195], v[112:115]
	v_mfma_f32_16x16x32_bf16 v[100:103], v[176:179], v[200:203], v[100:103]
	v_mfma_f32_16x16x32_bf16 v[96:99], v[184:187], v[200:203], v[96:99]
	v_mfma_f32_16x16x32_bf16 v[84:87], v[176:179], v[208:211], v[84:87]
	v_mfma_f32_16x16x32_bf16 v[80:83], v[184:187], v[208:211], v[80:83]
	v_mfma_f32_16x16x32_bf16 v[68:71], v[176:179], v[216:219], v[68:71]
	v_mfma_f32_16x16x32_bf16 v[64:67], v[184:187], v[216:219], v[64:67]
	s_barrier
	s_setprio 1
	s_add_u32 s6, s38, 0x80
	s_addc_u32 s7, s39, 0
	s_add_i32 s30, s30, s56
	ds_read_b128 v[188:191], v149 offset:49152
	ds_read_b128 v[192:195], v149 offset:50176
	ds_read_b128 v[196:199], v149 offset:51200
	ds_read_b128 v[200:203], v149 offset:52224
	ds_read_b128 v[204:207], v149 offset:53248
	ds_read_b128 v[208:211], v149 offset:54272
	ds_read_b128 v[212:215], v149 offset:55296
	ds_read_b128 v[216:219], v149 offset:56320
	s_mov_b32 m0, s30
	s_nop 0
	global_load_lds_dwordx4 v130, s[6:7]
	s_add_i32 m0, s30, 0x2000
	s_nop 0
	global_load_lds_dwordx4 v134, s[6:7]
	s_add_u32 s6, s38, 0xb0080
	s_addc_u32 s7, s39, 0
	s_add_i32 s30, s31, s56
	s_mov_b32 m0, s30
	s_nop 0
	global_load_lds_dwordx4 v130, s[6:7]
	s_add_i32 m0, s30, 0x2000
	s_nop 0
	global_load_lds_dwordx4 v134, s[6:7]
	s_mov_b32 m0, s66
	s_nop 0
	global_load_lds_dwordx4 v128, s[36:37]
	s_mov_b32 m0, s67
	s_nop 0
	global_load_lds_dwordx4 v132, s[36:37]
	s_setprio 0
	s_waitcnt vmcnt(8)
	s_waitcnt lgkmcnt(0)
	s_barrier
	s_waitcnt lgkmcnt(0)
	v_mfma_f32_16x16x32_bf16 v[60:63], v[140:143], v[188:191], v[60:63]
	v_mfma_f32_16x16x32_bf16 v[56:59], v[164:167], v[188:191], v[56:59]
	v_mfma_f32_16x16x32_bf16 v[44:47], v[140:143], v[196:199], v[44:47]
	v_mfma_f32_16x16x32_bf16 v[40:43], v[164:167], v[196:199], v[40:43]
	v_mfma_f32_16x16x32_bf16 v[28:31], v[140:143], v[204:207], v[28:31]
	v_mfma_f32_16x16x32_bf16 v[24:27], v[164:167], v[204:207], v[24:27]
	v_mfma_f32_16x16x32_bf16 v[12:15], v[140:143], v[212:215], v[12:15]
	v_mfma_f32_16x16x32_bf16 v[8:11], v[164:167], v[212:215], v[8:11]
	v_mfma_f32_16x16x32_bf16 v[60:63], v[160:163], v[192:195], v[60:63]
	v_mfma_f32_16x16x32_bf16 v[56:59], v[168:171], v[192:195], v[56:59]
	v_mfma_f32_16x16x32_bf16 v[44:47], v[160:163], v[200:203], v[44:47]
	v_mfma_f32_16x16x32_bf16 v[40:43], v[168:171], v[200:203], v[40:43]
	v_mfma_f32_16x16x32_bf16 v[28:31], v[160:163], v[208:211], v[28:31]
	v_mfma_f32_16x16x32_bf16 v[24:27], v[168:171], v[208:211], v[24:27]
	v_mfma_f32_16x16x32_bf16 v[12:15], v[160:163], v[216:219], v[12:15]
	v_mfma_f32_16x16x32_bf16 v[8:11], v[168:171], v[216:219], v[8:11]
	v_mfma_f32_16x16x32_bf16 v[52:55], v[172:175], v[188:191], v[52:55]
	v_mfma_f32_16x16x32_bf16 v[48:51], v[180:183], v[188:191], v[48:51]
	v_mfma_f32_16x16x32_bf16 v[36:39], v[172:175], v[196:199], v[36:39]
	v_mfma_f32_16x16x32_bf16 v[32:35], v[180:183], v[196:199], v[32:35]
	v_mfma_f32_16x16x32_bf16 v[20:23], v[172:175], v[204:207], v[20:23]
	v_mfma_f32_16x16x32_bf16 v[16:19], v[180:183], v[204:207], v[16:19]
	v_mfma_f32_16x16x32_bf16 v[4:7], v[172:175], v[212:215], v[4:7]
	v_mfma_f32_16x16x32_bf16 v[0:3], v[180:183], v[212:215], v[0:3]
	v_mfma_f32_16x16x32_bf16 v[52:55], v[176:179], v[192:195], v[52:55]
	v_mfma_f32_16x16x32_bf16 v[48:51], v[184:187], v[192:195], v[48:51]
	v_mfma_f32_16x16x32_bf16 v[36:39], v[176:179], v[200:203], v[36:39]
	v_mfma_f32_16x16x32_bf16 v[32:35], v[184:187], v[200:203], v[32:35]
	v_mfma_f32_16x16x32_bf16 v[20:23], v[176:179], v[208:211], v[20:23]
	v_mfma_f32_16x16x32_bf16 v[16:19], v[184:187], v[208:211], v[16:19]
	v_mfma_f32_16x16x32_bf16 v[4:7], v[176:179], v[216:219], v[4:7]
	v_mfma_f32_16x16x32_bf16 v[0:3], v[184:187], v[216:219], v[0:3]
	s_barrier
	s_add_i32 s77, s77, 2
	s_add_u32 s60, s60, 0x100
	s_addc_u32 s61, s61, 0
	s_cmp_gt_u32 s77, 41
	s_mov_b64 s[30:31], s[34:35]
	s_cbranch_scc0 .LBB0_1666
	s_and_b64 vcc, exec, s[16:17]
	s_cbranch_vccz .LBB0_1669
	s_barrier

; __device__ __forceinline__ int lane_id_() { int l; asm volatile("v_mbcnt_lo_u32_b32 %0, -1, 0\n\tv_mbcnt_hi_u32_b32 %0, -1, %0" : "=v"(l)); return l; }
; #define PG8_LAS __attribute__((address_space(3)))
;     __device__ __forceinline__ void prefetch(PG8_LAS unsigned char* lds, int wid, const Unit& u, int wr, int fr, int fq) const {
;         { const int l_ = lane_id_(); fr = l_ & 15; fq = l_ >> 4; }
; #pragma unroll
;         for (int j = 0; j < 2; ++j) { const int i = 2 * fq + j;
;             __builtin_amdgcn_global_load_lds((const unsigned*)(ssq + u.pm * BM + wr * 64 + fr + (i >> 2) * HALF + (i & 3) * 16), (PG8_LAS unsigned*)(lds + PRE_SLOT + wid * 512 + j * 256), 4, 0, 0); }
.LBB0_1755:
	s_lshl_b32 s6, s28, 8
	s_ashr_i32 s7, s6, 31
	s_lshl_b64 s[6:7], s[6:7], 2
	v_mbcnt_lo_u32_b32 v6, -1, 0
	v_mbcnt_hi_u32_b32 v6, -1, v6
	s_add_u32 s6, s72, s6
	v_and_b32_e32 v0, 15, v6
	v_lshlrev_b32_e32 v2, 2, v6
	v_and_b32_e32 v2, 0xffffff80, v2
	s_addc_u32 s7, s73, s7
	v_lshlrev_b32_e32 v0, 2, v0
	v_ashrrev_i32_e32 v3, 31, v2
	v_lshl_add_u64 v[4:5], s[6:7], 0, v[0:1]
	v_lshlrev_b32_e32 v0, 3, v6
	v_lshl_add_u64 v[2:3], v[2:3], 2, v[4:5]
	v_and_b32_e32 v0, 0x80, v0
	s_mov_b32 m0, s65
	v_lshl_add_u64 v[2:3], v[2:3], 0, v[0:1]
	global_load_lds_dword v[2:3], off
	v_lshl_add_u64 v[2:3], v[2:3], 0, 64
	s_add_i32 m0, s65, 0x100
	s_add_u32 s10, s30, 0x100
	global_load_lds_dword v[2:3], off
	ds_read_b128 v[2:5], v151
	ds_read_b128 v[6:9], v151 offset:1024
	ds_read_b128 v[10:13], v151 offset:2048
	ds_read_b128 v[14:17], v151 offset:3072
	ds_read_b128 v[18:21], v150
	ds_read_b128 v[22:25], v150 offset:1024
	ds_read_b128 v[26:29], v150 offset:2048
	ds_read_b128 v[30:33], v150 offset:3072
	s_addc_u32 s11, s31, 0
	s_add_u32 s8, s30, 0x180
	s_addc_u32 s9, s31, 0
	s_add_u32 s6, s34, 0x100
	s_addc_u32 s7, s35, 0
	s_add_u32 s40, s30, 0x40080
	s_addc_u32 s41, s31, 0
	s_mov_b32 m0, s85
	ds_read_b128 v[34:37], v149
	ds_read_b128 v[38:41], v149 offset:1024
	ds_read_b128 v[42:45], v149 offset:2048
	ds_read_b128 v[46:49], v149 offset:3072
	ds_read_b128 v[50:53], v149 offset:4096
	ds_read_b128 v[54:57], v149 offset:5120
	ds_read_b128 v[58:61], v149 offset:6144
	ds_read_b128 v[62:65], v149 offset:7168
	s_nop 0
	global_load_lds_dwordx4 v132, s[40:41]
	s_mov_b32 m0, s12
	s_nop 0
	global_load_lds_dwordx4 v136, s[40:41]
	s_waitcnt vmcnt(26)
	s_waitcnt lgkmcnt(0)
	s_barrier
	s_waitcnt lgkmcnt(0)
	v_mfma_f32_16x16x32_bf16 v[90:93], v[2:5], v[58:61], 0
	v_mfma_f32_16x16x32_bf16 v[66:69], v[2:5], v[34:37], 0
	v_mfma_f32_16x16x32_bf16 v[70:73], v[10:13], v[34:37], 0
	v_mfma_f32_16x16x32_bf16 v[74:77], v[2:5], v[42:45], 0
	v_mfma_f32_16x16x32_bf16 v[78:81], v[10:13], v[42:45], 0
	v_mfma_f32_16x16x32_bf16 v[82:85], v[2:5], v[50:53], 0
	v_mfma_f32_16x16x32_bf16 v[86:89], v[10:13], v[50:53], 0
	v_mfma_f32_16x16x32_bf16 v[100:103], v[6:9], v[62:65], v[90:93]
	v_mfma_f32_16x16x32_bf16 v[90:93], v[10:13], v[58:61], 0
	v_mfma_f32_16x16x32_bf16 v[66:69], v[6:9], v[38:41], v[66:69]
	v_mfma_f32_16x16x32_bf16 v[70:73], v[14:17], v[38:41], v[70:73]
	v_mfma_f32_16x16x32_bf16 v[74:77], v[6:9], v[46:49], v[74:77]
	v_mfma_f32_16x16x32_bf16 v[78:81], v[14:17], v[46:49], v[78:81]
	v_mfma_f32_16x16x32_bf16 v[82:85], v[6:9], v[54:57], v[82:85]
	v_mfma_f32_16x16x32_bf16 v[86:89], v[14:17], v[54:57], v[86:89]
	v_mfma_f32_16x16x32_bf16 v[104:107], v[14:17], v[62:65], v[90:93]
	v_mfma_f32_16x16x32_bf16 v[90:93], v[18:21], v[34:37], 0
	v_mfma_f32_16x16x32_bf16 v[34:37], v[26:29], v[34:37], 0
	v_mfma_f32_16x16x32_bf16 v[116:119], v[22:25], v[38:41], v[90:93]
	v_mfma_f32_16x16x32_bf16 v[34:37], v[30:33], v[38:41], v[34:37]
	v_mfma_f32_16x16x32_bf16 v[38:41], v[18:21], v[42:45], 0
	v_mfma_f32_16x16x32_bf16 v[42:45], v[26:29], v[42:45], 0
	v_mfma_f32_16x16x32_bf16 v[38:41], v[22:25], v[46:49], v[38:41]
	v_mfma_f32_16x16x32_bf16 v[42:45], v[30:33], v[46:49], v[42:45]
	v_mfma_f32_16x16x32_bf16 v[46:49], v[18:21], v[50:53], 0
	v_mfma_f32_16x16x32_bf16 v[50:53], v[26:29], v[50:53], 0
	v_mfma_f32_16x16x32_bf16 v[46:49], v[22:25], v[54:57], v[46:49]
	v_mfma_f32_16x16x32_bf16 v[50:53], v[30:33], v[54:57], v[50:53]
	v_mfma_f32_16x16x32_bf16 v[54:57], v[18:21], v[58:61], 0
	v_mfma_f32_16x16x32_bf16 v[58:61], v[26:29], v[58:61], 0
	v_mfma_f32_16x16x32_bf16 v[54:57], v[22:25], v[62:65], v[54:57]
	v_mfma_f32_16x16x32_bf16 v[58:61], v[30:33], v[62:65], v[58:61]
	s_barrier
	s_setprio 1
	s_mov_b32 m0, s79
	ds_read_b128 v[62:65], v149 offset:16384
	ds_read_b128 v[90:93], v149 offset:17408
	ds_read_b128 v[94:97], v149 offset:18432
	ds_read_b128 v[108:111], v149 offset:19456
	ds_read_b128 v[112:115], v149 offset:20480
	ds_read_b128 v[120:123], v149 offset:21504
	ds_read_b128 v[124:127], v149 offset:22528
	ds_read_b128 v[128:131], v149 offset:23552
	s_nop 0
	global_load_lds_dwordx4 v134, s[6:7]
	s_mov_b64 s[98:99], s[6:7]
	s_add_u32 s6, s34, 0x40100
	s_mov_b32 m0, s27
	s_addc_u32 s7, s35, 0
	global_load_lds_dwordx4 v138, s[98:99]
	s_mov_b32 m0, s29
	s_nop 0
	global_load_lds_dwordx4 v134, s[6:7]
	s_mov_b32 m0, s77
	s_nop 0
	global_load_lds_dwordx4 v138, s[6:7]
	s_mov_b32 m0, s37
	s_nop 0
	global_load_lds_dwordx4 v132, s[10:11]
	s_mov_b32 m0, s39
	s_nop 0
	global_load_lds_dwordx4 v136, s[10:11]
	s_setprio 0
	s_waitcnt vmcnt(26)
	s_waitcnt lgkmcnt(0)
	s_barrier
	s_waitcnt lgkmcnt(0)
	v_mfma_f32_16x16x32_bf16 v[154:157], v[2:5], v[62:65], 0
	v_mfma_f32_16x16x32_bf16 v[162:165], v[2:5], v[94:97], 0
	v_mfma_f32_16x16x32_bf16 v[170:173], v[2:5], v[112:115], 0
	v_mfma_f32_16x16x32_bf16 v[2:5], v[2:5], v[124:127], 0
	v_mfma_f32_16x16x32_bf16 v[154:157], v[6:9], v[90:93], v[154:157]
	v_mfma_f32_16x16x32_bf16 v[162:165], v[6:9], v[108:111], v[162:165]
	v_mfma_f32_16x16x32_bf16 v[170:173], v[6:9], v[120:123], v[170:173]
	v_mfma_f32_16x16x32_bf16 v[2:5], v[6:9], v[128:131], v[2:5]
	v_mfma_f32_16x16x32_bf16 v[6:9], v[10:13], v[124:127], 0
	v_mfma_f32_16x16x32_bf16 v[158:161], v[10:13], v[62:65], 0
	v_mfma_f32_16x16x32_bf16 v[166:169], v[10:13], v[94:97], 0
	v_mfma_f32_16x16x32_bf16 v[174:177], v[10:13], v[112:115], 0
	v_mfma_f32_16x16x32_bf16 v[6:9], v[14:17], v[128:131], v[6:9]
	v_mfma_f32_16x16x32_bf16 v[158:161], v[14:17], v[90:93], v[158:161]
	v_mfma_f32_16x16x32_bf16 v[166:169], v[14:17], v[108:111], v[166:169]
	v_mfma_f32_16x16x32_bf16 v[174:177], v[14:17], v[120:123], v[174:177]
	v_mfma_f32_16x16x32_bf16 v[10:13], v[18:21], v[62:65], 0
	v_mfma_f32_16x16x32_bf16 v[178:181], v[22:25], v[90:93], v[10:13]
	v_mfma_f32_16x16x32_bf16 v[10:13], v[26:29], v[62:65], 0
	v_mfma_f32_16x16x32_bf16 v[182:185], v[30:33], v[90:93], v[10:13]
	v_mfma_f32_16x16x32_bf16 v[10:13], v[18:21], v[94:97], 0
	v_mfma_f32_16x16x32_bf16 v[186:189], v[22:25], v[108:111], v[10:13]
	v_mfma_f32_16x16x32_bf16 v[10:13], v[26:29], v[94:97], 0
	v_mfma_f32_16x16x32_bf16 v[190:193], v[30:33], v[108:111], v[10:13]
	v_mfma_f32_16x16x32_bf16 v[10:13], v[18:21], v[112:115], 0
	v_mfma_f32_16x16x32_bf16 v[194:197], v[22:25], v[120:123], v[10:13]
	v_mfma_f32_16x16x32_bf16 v[10:13], v[26:29], v[112:115], 0
	v_mfma_f32_16x16x32_bf16 v[198:201], v[30:33], v[120:123], v[10:13]
	v_mfma_f32_16x16x32_bf16 v[10:13], v[18:21], v[124:127], 0
	v_mfma_f32_16x16x32_bf16 v[202:205], v[22:25], v[128:131], v[10:13]
	v_mfma_f32_16x16x32_bf16 v[10:13], v[26:29], v[124:127], 0
	v_mfma_f32_16x16x32_bf16 v[206:209], v[30:33], v[128:131], v[10:13]
	s_barrier
	s_nop 4
	ds_read_b128 v[10:13], v152
	ds_read_b128 v[14:17], v152 offset:1024
	ds_read_b128 v[20:23], v152 offset:2048
	ds_read_b128 v[24:27], v152 offset:3072
	ds_read_b128 v[210:213], v153
	ds_read_b128 v[214:217], v153 offset:1024
	ds_read_b128 v[218:221], v153 offset:2048
	ds_read_b128 v[150:153], v153 offset:3072
	s_add_u32 s6, s30, 0x40100
	s_addc_u32 s7, s31, 0
	s_mov_b32 m0, s66
	ds_read_b128 v[28:31], v149 offset:32768
	ds_read_b128 v[62:65], v149 offset:33792
	ds_read_b128 v[222:225], v149 offset:34816
	ds_read_b128 v[226:229], v149 offset:35840
	ds_read_b128 v[230:233], v149 offset:36864
	ds_read_b128 v[234:237], v149 offset:37888
	ds_read_b128 v[238:241], v149 offset:38912
	ds_read_b128 v[242:245], v149 offset:39936
	s_nop 0
	global_load_lds_dwordx4 v132, s[6:7]
	s_mov_b32 m0, s67
	s_nop 0
	global_load_lds_dwordx4 v136, s[6:7]
	s_waitcnt vmcnt(26)
	s_waitcnt lgkmcnt(0)
	s_barrier
	s_waitcnt lgkmcnt(0)
	v_mfma_f32_16x16x32_bf16 v[66:69], v[10:13], v[28:31], v[66:69]
	v_mfma_f32_16x16x32_bf16 v[128:131], v[14:17], v[62:65], v[66:69]
	v_mfma_f32_16x16x32_bf16 v[66:69], v[20:23], v[28:31], v[70:73]
	v_mfma_f32_16x16x32_bf16 v[124:127], v[24:27], v[62:65], v[66:69]
	v_mfma_f32_16x16x32_bf16 v[66:69], v[10:13], v[222:225], v[74:77]
	v_mfma_f32_16x16x32_bf16 v[112:115], v[14:17], v[226:229], v[66:69]
	v_mfma_f32_16x16x32_bf16 v[66:69], v[20:23], v[222:225], v[78:81]
	v_mfma_f32_16x16x32_bf16 v[108:111], v[24:27], v[226:229], v[66:69]
	v_mfma_f32_16x16x32_bf16 v[66:69], v[10:13], v[230:233], v[82:85]
	v_mfma_f32_16x16x32_bf16 v[96:99], v[14:17], v[234:237], v[66:69]
	v_mfma_f32_16x16x32_bf16 v[66:69], v[20:23], v[230:233], v[86:89]
	v_mfma_f32_16x16x32_bf16 v[92:95], v[24:27], v[234:237], v[66:69]
	v_mfma_f32_16x16x32_bf16 v[66:69], v[10:13], v[238:241], v[100:103]
	v_mfma_f32_16x16x32_bf16 v[80:83], v[14:17], v[242:245], v[66:69]
	v_mfma_f32_16x16x32_bf16 v[66:69], v[20:23], v[238:241], v[104:107]
	v_mfma_f32_16x16x32_bf16 v[76:79], v[24:27], v[242:245], v[66:69]
	v_mfma_f32_16x16x32_bf16 v[66:69], v[210:213], v[28:31], v[116:119]
	v_mfma_f32_16x16x32_bf16 v[28:31], v[218:221], v[28:31], v[34:37]
	v_mfma_f32_16x16x32_bf16 v[116:119], v[150:153], v[62:65], v[28:31]
	v_mfma_f32_16x16x32_bf16 v[28:31], v[210:213], v[222:225], v[38:41]
	v_mfma_f32_16x16x32_bf16 v[104:107], v[214:217], v[226:229], v[28:31]
	v_mfma_f32_16x16x32_bf16 v[28:31], v[218:221], v[222:225], v[42:45]
	v_mfma_f32_16x16x32_bf16 v[100:103], v[150:153], v[226:229], v[28:31]
	v_mfma_f32_16x16x32_bf16 v[28:31], v[210:213], v[230:233], v[46:49]
	v_mfma_f32_16x16x32_bf16 v[88:91], v[214:217], v[234:237], v[28:31]
	v_mfma_f32_16x16x32_bf16 v[28:31], v[218:221], v[230:233], v[50:53]
	v_mfma_f32_16x16x32_bf16 v[84:87], v[150:153], v[234:237], v[28:31]
	v_mfma_f32_16x16x32_bf16 v[28:31], v[210:213], v[238:241], v[54:57]
	v_mfma_f32_16x16x32_bf16 v[72:75], v[214:217], v[242:245], v[28:31]
	v_mfma_f32_16x16x32_bf16 v[28:31], v[218:221], v[238:241], v[58:61]
	v_mfma_f32_16x16x32_bf16 v[120:123], v[214:217], v[62:65], v[66:69]
	v_mfma_f32_16x16x32_bf16 v[68:71], v[150:153], v[242:245], v[28:31]
	s_barrier
	s_setprio 1
	s_add_u32 s6, s34, 0x180
	s_addc_u32 s7, s35, 0
	s_mov_b32 m0, s86
	ds_read_b128 v[36:39], v149 offset:49152
	ds_read_b128 v[40:43], v149 offset:50176
	ds_read_b128 v[222:225], v149 offset:51200
	ds_read_b128 v[226:229], v149 offset:52224
	ds_read_b128 v[230:233], v149 offset:53248
	ds_read_b128 v[234:237], v149 offset:54272
	ds_read_b128 v[238:241], v149 offset:55296
	ds_read_b128 v[242:245], v149 offset:56320
	s_nop 0
	global_load_lds_dwordx4 v134, s[6:7]
	s_mov_b64 s[98:99], s[6:7]
	s_add_u32 s6, s34, 0x40180
	s_mov_b32 m0, s54
	s_addc_u32 s7, s35, 0
	global_load_lds_dwordx4 v138, s[98:99]
	s_mov_b32 m0, s55
	s_nop 0
	global_load_lds_dwordx4 v134, s[6:7]
	s_mov_b32 m0, s78
	s_nop 0
	global_load_lds_dwordx4 v138, s[6:7]
	s_mov_b32 m0, s68
	s_nop 0
	global_load_lds_dwordx4 v132, s[8:9]
	s_mov_b32 m0, s69
	s_nop 0
	global_load_lds_dwordx4 v136, s[8:9]
	s_setprio 0
	s_waitcnt vmcnt(26)
	s_waitcnt lgkmcnt(0)
	s_barrier
	s_waitcnt lgkmcnt(0)
	v_mfma_f32_16x16x32_bf16 v[28:31], v[10:13], v[36:39], v[154:157]
	v_mfma_f32_16x16x32_bf16 v[64:67], v[14:17], v[40:43], v[28:31]
	v_mfma_f32_16x16x32_bf16 v[28:31], v[20:23], v[36:39], v[158:161]
	v_mfma_f32_16x16x32_bf16 v[60:63], v[24:27], v[40:43], v[28:31]
	v_mfma_f32_16x16x32_bf16 v[28:31], v[10:13], v[222:225], v[162:165]
	v_mfma_f32_16x16x32_bf16 v[48:51], v[14:17], v[226:229], v[28:31]
	v_mfma_f32_16x16x32_bf16 v[28:31], v[20:23], v[222:225], v[166:169]
	v_mfma_f32_16x16x32_bf16 v[44:47], v[24:27], v[226:229], v[28:31]
	v_mfma_f32_16x16x32_bf16 v[28:31], v[10:13], v[230:233], v[170:173]
	v_mfma_f32_16x16x32_bf16 v[2:5], v[10:13], v[238:241], v[2:5]
	v_mfma_f32_16x16x32_bf16 v[32:35], v[14:17], v[234:237], v[28:31]
	v_mfma_f32_16x16x32_bf16 v[28:31], v[20:23], v[230:233], v[174:177]
	v_mfma_f32_16x16x32_bf16 v[16:19], v[14:17], v[242:245], v[2:5]
	v_mfma_f32_16x16x32_bf16 v[2:5], v[20:23], v[238:241], v[6:9]
	v_mfma_f32_16x16x32_bf16 v[28:31], v[24:27], v[234:237], v[28:31]
	v_mfma_f32_16x16x32_bf16 v[12:15], v[24:27], v[242:245], v[2:5]
	v_mfma_f32_16x16x32_bf16 v[2:5], v[210:213], v[36:39], v[178:181]
	v_mfma_f32_16x16x32_bf16 v[56:59], v[214:217], v[40:43], v[2:5]
	v_mfma_f32_16x16x32_bf16 v[2:5], v[218:221], v[36:39], v[182:185]
	v_mfma_f32_16x16x32_bf16 v[52:55], v[150:153], v[40:43], v[2:5]
	v_mfma_f32_16x16x32_bf16 v[2:5], v[210:213], v[222:225], v[186:189]
	v_mfma_f32_16x16x32_bf16 v[40:43], v[214:217], v[226:229], v[2:5]
	v_mfma_f32_16x16x32_bf16 v[2:5], v[218:221], v[222:225], v[190:193]
	v_mfma_f32_16x16x32_bf16 v[36:39], v[150:153], v[226:229], v[2:5]
	v_mfma_f32_16x16x32_bf16 v[2:5], v[210:213], v[230:233], v[194:197]
	v_mfma_f32_16x16x32_bf16 v[24:27], v[214:217], v[234:237], v[2:5]
	v_mfma_f32_16x16x32_bf16 v[2:5], v[218:221], v[230:233], v[198:201]
	v_mfma_f32_16x16x32_bf16 v[20:23], v[150:153], v[234:237], v[2:5]
	v_mfma_f32_16x16x32_bf16 v[2:5], v[210:213], v[238:241], v[202:205]
	v_mfma_f32_16x16x32_bf16 v[8:11], v[214:217], v[242:245], v[2:5]
	v_mfma_f32_16x16x32_bf16 v[2:5], v[218:221], v[238:241], v[206:209]
	v_mfma_f32_16x16x32_bf16 v[4:7], v[150:153], v[242:245], v[2:5]
	s_barrier
	s_mov_b64 s[8:9], 0

; template <class Epi, class Sched, bool ALIGN_EPI = false, bool SP2 = false>
; __device__ __forceinline__ void gemm_phase(PG8_LAS unsigned char* lds, const Gemm g, const Sched& S, const Epi& E, int wave_s) {
;     ...
;             const bool last = (t == nt - 2);
;             const char* a1 = cA + (size_t)(t + 1) * kstep;
;             const char* a2 = last ? nA : cA + (size_t)(t + 2) * kstep; const char* b2 = last ? nB : cB + (size_t)(t + 2) * kstep;
;             const char* a3 = a2 + kstep; const char* b3 = b2 + kstep;
.LBB0_1764:
	v_add_u32_e32 v151, s74, v146
	v_add_u32_e32 v150, s75, v146
	ds_read_b128 v[152:155], v151
	ds_read_b128 v[156:159], v151 offset:1024
	ds_read_b128 v[160:163], v151 offset:2048
	ds_read_b128 v[164:167], v151 offset:3072
	ds_read_b128 v[168:171], v150
	ds_read_b128 v[172:175], v150 offset:1024
	ds_read_b128 v[176:179], v150 offset:2048
	ds_read_b128 v[180:183], v150 offset:3072
	s_add_u32 s10, s56, 0x100
	s_addc_u32 s11, s57, 0
	s_cmp_eq_u32 s88, 12
	s_cselect_b32 s54, s61, s10
	s_cselect_b32 s55, s60, s11
	s_cselect_b32 s42, s87, s6
	s_cselect_b32 s43, s82, s7
	s_add_u32 s40, s54, 0x80
	s_addc_u32 s41, s55, 0
	s_add_u32 s56, s56, 0x40080
	s_addc_u32 s57, s57, 0
	s_add_i32 s85, s37, 0xc000
	ds_read_b128 v[184:187], v149
	ds_read_b128 v[188:191], v149 offset:1024
	ds_read_b128 v[192:195], v149 offset:2048
	ds_read_b128 v[196:199], v149 offset:3072
	ds_read_b128 v[200:203], v149 offset:4096
	ds_read_b128 v[204:207], v149 offset:5120
	ds_read_b128 v[208:211], v149 offset:6144
	ds_read_b128 v[212:215], v149 offset:7168
	s_mov_b32 m0, s85
	s_add_i32 s12, s37, 0xe000
	global_load_lds_dwordx4 v132, s[56:57]
	s_mov_b32 m0, s12
	s_nop 0
	global_load_lds_dwordx4 v136, s[56:57]
	s_waitcnt vmcnt(8)
	s_waitcnt lgkmcnt(0)
	s_barrier
	s_waitcnt lgkmcnt(0)
	v_mfma_f32_16x16x32_bf16 v[128:131], v[152:155], v[184:187], v[128:131]
	v_mfma_f32_16x16x32_bf16 v[124:127], v[160:163], v[184:187], v[124:127]
	v_mfma_f32_16x16x32_bf16 v[112:115], v[152:155], v[192:195], v[112:115]
	v_mfma_f32_16x16x32_bf16 v[108:111], v[160:163], v[192:195], v[108:111]
	v_mfma_f32_16x16x32_bf16 v[96:99], v[152:155], v[200:203], v[96:99]
	v_mfma_f32_16x16x32_bf16 v[92:95], v[160:163], v[200:203], v[92:95]
	v_mfma_f32_16x16x32_bf16 v[80:83], v[152:155], v[208:211], v[80:83]
	v_mfma_f32_16x16x32_bf16 v[76:79], v[160:163], v[208:211], v[76:79]
	v_mfma_f32_16x16x32_bf16 v[128:131], v[156:159], v[188:191], v[128:131]
	v_mfma_f32_16x16x32_bf16 v[124:127], v[164:167], v[188:191], v[124:127]
	v_mfma_f32_16x16x32_bf16 v[112:115], v[156:159], v[196:199], v[112:115]
	v_mfma_f32_16x16x32_bf16 v[108:111], v[164:167], v[196:199], v[108:111]
	v_mfma_f32_16x16x32_bf16 v[96:99], v[156:159], v[204:207], v[96:99]
	v_mfma_f32_16x16x32_bf16 v[92:95], v[164:167], v[204:207], v[92:95]
	v_mfma_f32_16x16x32_bf16 v[80:83], v[156:159], v[212:215], v[80:83]
	v_mfma_f32_16x16x32_bf16 v[76:79], v[164:167], v[212:215], v[76:79]
	v_mfma_f32_16x16x32_bf16 v[120:123], v[168:171], v[184:187], v[120:123]
	v_mfma_f32_16x16x32_bf16 v[116:119], v[176:179], v[184:187], v[116:119]
	v_mfma_f32_16x16x32_bf16 v[104:107], v[168:171], v[192:195], v[104:107]
	v_mfma_f32_16x16x32_bf16 v[100:103], v[176:179], v[192:195], v[100:103]
	v_mfma_f32_16x16x32_bf16 v[88:91], v[168:171], v[200:203], v[88:91]
	v_mfma_f32_16x16x32_bf16 v[84:87], v[176:179], v[200:203], v[84:87]
	v_mfma_f32_16x16x32_bf16 v[72:75], v[168:171], v[208:211], v[72:75]
	v_mfma_f32_16x16x32_bf16 v[68:71], v[176:179], v[208:211], v[68:71]
	v_mfma_f32_16x16x32_bf16 v[120:123], v[172:175], v[188:191], v[120:123]
	v_mfma_f32_16x16x32_bf16 v[116:119], v[180:183], v[188:191], v[116:119]
	v_mfma_f32_16x16x32_bf16 v[104:107], v[172:175], v[196:199], v[104:107]
	v_mfma_f32_16x16x32_bf16 v[100:103], v[180:183], v[196:199], v[100:103]
	v_mfma_f32_16x16x32_bf16 v[88:91], v[172:175], v[204:207], v[88:91]
	v_mfma_f32_16x16x32_bf16 v[84:87], v[180:183], v[204:207], v[84:87]
	v_mfma_f32_16x16x32_bf16 v[72:75], v[172:175], v[212:215], v[72:75]
	v_mfma_f32_16x16x32_bf16 v[68:71], v[180:183], v[212:215], v[68:71]
	s_barrier
	s_setprio 1
	s_mov_b64 s[56:57], s[42:43]
	s_add_i32 s79, s74, s64
	ds_read_b128 v[184:187], v149 offset:16384
	ds_read_b128 v[188:191], v149 offset:17408
	ds_read_b128 v[192:195], v149 offset:18432
	ds_read_b128 v[196:199], v149 offset:19456
	ds_read_b128 v[200:203], v149 offset:20480
	ds_read_b128 v[204:207], v149 offset:21504
	ds_read_b128 v[208:211], v149 offset:22528
	ds_read_b128 v[212:215], v149 offset:23552
	s_mov_b32 m0, s79
	s_add_i32 s27, s79, 0x2000
	global_load_lds_dwordx4 v134, s[56:57]
	s_mov_b64 s[98:99], s[56:57]
	s_add_u32 s56, s42, 0x40000
	s_mov_b32 m0, s27
	s_addc_u32 s57, s43, 0
	s_add_i32 s29, s75, s64
	global_load_lds_dwordx4 v138, s[98:99]
	s_mov_b32 m0, s29
	s_add_i32 s77, s29, 0x2000
	global_load_lds_dwordx4 v134, s[56:57]
	s_mov_b64 s[98:99], s[56:57]
	s_mov_b32 m0, s77
	s_mov_b64 s[56:57], s[54:55]
	global_load_lds_dwordx4 v138, s[98:99]
	s_mov_b32 m0, s37
	s_nop 0
	global_load_lds_dwordx4 v132, s[56:57]
	s_mov_b32 m0, s39
	s_nop 0
	global_load_lds_dwordx4 v136, s[56:57]
	s_setprio 0
	s_waitcnt vmcnt(8)
	s_waitcnt lgkmcnt(0)
	s_barrier
	s_waitcnt lgkmcnt(0)
	v_mfma_f32_16x16x32_bf16 v[64:67], v[152:155], v[184:187], v[64:67]
	v_mfma_f32_16x16x32_bf16 v[60:63], v[160:163], v[184:187], v[60:63]
	v_mfma_f32_16x16x32_bf16 v[48:51], v[152:155], v[192:195], v[48:51]
	v_mfma_f32_16x16x32_bf16 v[44:47], v[160:163], v[192:195], v[44:47]
	v_mfma_f32_16x16x32_bf16 v[32:35], v[152:155], v[200:203], v[32:35]
	v_mfma_f32_16x16x32_bf16 v[28:31], v[160:163], v[200:203], v[28:31]
	v_mfma_f32_16x16x32_bf16 v[16:19], v[152:155], v[208:211], v[16:19]
	v_mfma_f32_16x16x32_bf16 v[12:15], v[160:163], v[208:211], v[12:15]
	v_mfma_f32_16x16x32_bf16 v[64:67], v[156:159], v[188:191], v[64:67]
	v_mfma_f32_16x16x32_bf16 v[60:63], v[164:167], v[188:191], v[60:63]
	v_mfma_f32_16x16x32_bf16 v[48:51], v[156:159], v[196:199], v[48:51]
	v_mfma_f32_16x16x32_bf16 v[44:47], v[164:167], v[196:199], v[44:47]
	v_mfma_f32_16x16x32_bf16 v[32:35], v[156:159], v[204:207], v[32:35]
	v_mfma_f32_16x16x32_bf16 v[28:31], v[164:167], v[204:207], v[28:31]
	v_mfma_f32_16x16x32_bf16 v[16:19], v[156:159], v[212:215], v[16:19]
	v_mfma_f32_16x16x32_bf16 v[12:15], v[164:167], v[212:215], v[12:15]
	v_mfma_f32_16x16x32_bf16 v[56:59], v[168:171], v[184:187], v[56:59]
	v_mfma_f32_16x16x32_bf16 v[52:55], v[176:179], v[184:187], v[52:55]
	v_mfma_f32_16x16x32_bf16 v[40:43], v[168:171], v[192:195], v[40:43]
	v_mfma_f32_16x16x32_bf16 v[36:39], v[176:179], v[192:195], v[36:39]
	v_mfma_f32_16x16x32_bf16 v[24:27], v[168:171], v[200:203], v[24:27]
	v_mfma_f32_16x16x32_bf16 v[20:23], v[176:179], v[200:203], v[20:23]
	v_mfma_f32_16x16x32_bf16 v[8:11], v[168:171], v[208:211], v[8:11]
	v_mfma_f32_16x16x32_bf16 v[2:5], v[176:179], v[208:211], v[4:7]
	v_mfma_f32_16x16x32_bf16 v[56:59], v[172:175], v[188:191], v[56:59]
	v_mfma_f32_16x16x32_bf16 v[52:55], v[180:183], v[188:191], v[52:55]
	v_mfma_f32_16x16x32_bf16 v[40:43], v[172:175], v[196:199], v[40:43]
	v_mfma_f32_16x16x32_bf16 v[36:39], v[180:183], v[196:199], v[36:39]
	v_mfma_f32_16x16x32_bf16 v[24:27], v[172:175], v[204:207], v[24:27]
	v_mfma_f32_16x16x32_bf16 v[20:23], v[180:183], v[204:207], v[20:23]
	v_mfma_f32_16x16x32_bf16 v[8:11], v[172:175], v[212:215], v[8:11]
	v_mfma_f32_16x16x32_bf16 v[2:5], v[180:183], v[212:215], v[2:5]
	s_barrier
	s_add_i32 s86, 0, 0x18000
	s_add_i32 s56, 0, 0x1c000
	v_add_u32_e32 v152, s86, v146
	v_add_u32_e32 v153, s56, v146
	ds_read_b128 v[154:157], v152
	ds_read_b128 v[158:161], v152 offset:1024
	ds_read_b128 v[162:165], v152 offset:2048
	ds_read_b128 v[166:169], v152 offset:3072
	ds_read_b128 v[170:173], v153
	ds_read_b128 v[174:177], v153 offset:1024
	ds_read_b128 v[178:181], v153 offset:2048
	ds_read_b128 v[182:185], v153 offset:3072
	s_add_u32 s54, s54, 0x40000
	s_addc_u32 s55, s55, 0
	s_mov_b32 m0, s66
	ds_read_b128 v[186:189], v149 offset:32768
	ds_read_b128 v[190:193], v149 offset:33792
	ds_read_b128 v[194:197], v149 offset:34816
	ds_read_b128 v[198:201], v149 offset:35840
	ds_read_b128 v[202:205], v149 offset:36864
	ds_read_b128 v[206:209], v149 offset:37888
	ds_read_b128 v[210:213], v149 offset:38912
	ds_read_b128 v[214:217], v149 offset:39936
	s_nop 0
	global_load_lds_dwordx4 v132, s[54:55]
	s_mov_b32 m0, s67
	s_nop 0
	global_load_lds_dwordx4 v136, s[54:55]
	s_waitcnt vmcnt(8)
	s_waitcnt lgkmcnt(0)
	s_barrier
	s_waitcnt lgkmcnt(0)
	v_mfma_f32_16x16x32_bf16 v[128:131], v[154:157], v[186:189], v[128:131]
	v_mfma_f32_16x16x32_bf16 v[124:127], v[162:165], v[186:189], v[124:127]
	v_mfma_f32_16x16x32_bf16 v[112:115], v[154:157], v[194:197], v[112:115]
	v_mfma_f32_16x16x32_bf16 v[108:111], v[162:165], v[194:197], v[108:111]
	v_mfma_f32_16x16x32_bf16 v[96:99], v[154:157], v[202:205], v[96:99]
	v_mfma_f32_16x16x32_bf16 v[92:95], v[162:165], v[202:205], v[92:95]
	v_mfma_f32_16x16x32_bf16 v[80:83], v[154:157], v[210:213], v[80:83]
	v_mfma_f32_16x16x32_bf16 v[76:79], v[162:165], v[210:213], v[76:79]
	v_mfma_f32_16x16x32_bf16 v[128:131], v[158:161], v[190:193], v[128:131]
	v_mfma_f32_16x16x32_bf16 v[124:127], v[166:169], v[190:193], v[124:127]
	v_mfma_f32_16x16x32_bf16 v[112:115], v[158:161], v[198:201], v[112:115]
	v_mfma_f32_16x16x32_bf16 v[108:111], v[166:169], v[198:201], v[108:111]
	v_mfma_f32_16x16x32_bf16 v[96:99], v[158:161], v[206:209], v[96:99]
	v_mfma_f32_16x16x32_bf16 v[92:95], v[166:169], v[206:209], v[92:95]
	v_mfma_f32_16x16x32_bf16 v[80:83], v[158:161], v[214:217], v[80:83]
	v_mfma_f32_16x16x32_bf16 v[76:79], v[166:169], v[214:217], v[76:79]
	v_mfma_f32_16x16x32_bf16 v[120:123], v[170:173], v[186:189], v[120:123]
	v_mfma_f32_16x16x32_bf16 v[116:119], v[178:181], v[186:189], v[116:119]
	v_mfma_f32_16x16x32_bf16 v[104:107], v[170:173], v[194:197], v[104:107]
	v_mfma_f32_16x16x32_bf16 v[100:103], v[178:181], v[194:197], v[100:103]
	v_mfma_f32_16x16x32_bf16 v[88:91], v[170:173], v[202:205], v[88:91]
	v_mfma_f32_16x16x32_bf16 v[84:87], v[178:181], v[202:205], v[84:87]
	v_mfma_f32_16x16x32_bf16 v[72:75], v[170:173], v[210:213], v[72:75]
	v_mfma_f32_16x16x32_bf16 v[68:71], v[178:181], v[210:213], v[68:71]
	v_mfma_f32_16x16x32_bf16 v[120:123], v[174:177], v[190:193], v[120:123]
	v_mfma_f32_16x16x32_bf16 v[116:119], v[182:185], v[190:193], v[116:119]
	v_mfma_f32_16x16x32_bf16 v[104:107], v[174:177], v[198:201], v[104:107]
	v_mfma_f32_16x16x32_bf16 v[100:103], v[182:185], v[198:201], v[100:103]
	v_mfma_f32_16x16x32_bf16 v[88:91], v[174:177], v[206:209], v[88:91]
	v_mfma_f32_16x16x32_bf16 v[84:87], v[182:185], v[206:209], v[84:87]
	v_mfma_f32_16x16x32_bf16 v[72:75], v[174:177], v[214:217], v[72:75]
	v_mfma_f32_16x16x32_bf16 v[68:71], v[182:185], v[214:217], v[68:71]
	s_barrier
	s_setprio 1
	s_add_u32 s54, s42, 0x80
	s_addc_u32 s55, s43, 0
	s_add_i32 s86, s86, s64
	ds_read_b128 v[186:189], v149 offset:49152
	ds_read_b128 v[190:193], v149 offset:50176
	ds_read_b128 v[194:197], v149 offset:51200
	ds_read_b128 v[198:201], v149 offset:52224
	ds_read_b128 v[202:205], v149 offset:53248
	ds_read_b128 v[206:209], v149 offset:54272
	ds_read_b128 v[210:213], v149 offset:55296
	ds_read_b128 v[214:217], v149 offset:56320
	s_mov_b32 m0, s86
	s_nop 0
	global_load_lds_dwordx4 v134, s[54:55]
	s_mov_b64 s[98:99], s[54:55]
	s_add_i32 s54, s86, 0x2000
	s_add_u32 s42, s42, 0x40080
	s_mov_b32 m0, s54
	s_addc_u32 s43, s43, 0
	s_add_i32 s55, s56, s64
	global_load_lds_dwordx4 v138, s[98:99]
	s_mov_b32 m0, s55
	s_add_i32 s78, s55, 0x2000
	global_load_lds_dwordx4 v134, s[42:43]
	s_mov_b32 m0, s78
	s_nop 0
	global_load_lds_dwordx4 v138, s[42:43]
	s_mov_b32 m0, s68
	s_nop 0
	global_load_lds_dwordx4 v132, s[40:41]
	s_mov_b32 m0, s69
	s_nop 0
	global_load_lds_dwordx4 v136, s[40:41]
	s_setprio 0
	s_waitcnt vmcnt(8)
	s_waitcnt lgkmcnt(0)
	s_barrier
	s_waitcnt lgkmcnt(0)
	v_mfma_f32_16x16x32_bf16 v[64:67], v[154:157], v[186:189], v[64:67]
	v_mfma_f32_16x16x32_bf16 v[60:63], v[162:165], v[186:189], v[60:63]
	v_mfma_f32_16x16x32_bf16 v[48:51], v[154:157], v[194:197], v[48:51]
	v_mfma_f32_16x16x32_bf16 v[44:47], v[162:165], v[194:197], v[44:47]
	v_mfma_f32_16x16x32_bf16 v[32:35], v[154:157], v[202:205], v[32:35]
	v_mfma_f32_16x16x32_bf16 v[28:31], v[162:165], v[202:205], v[28:31]
	v_mfma_f32_16x16x32_bf16 v[16:19], v[154:157], v[210:213], v[16:19]
	v_mfma_f32_16x16x32_bf16 v[12:15], v[162:165], v[210:213], v[12:15]
	v_mfma_f32_16x16x32_bf16 v[64:67], v[158:161], v[190:193], v[64:67]
	v_mfma_f32_16x16x32_bf16 v[60:63], v[166:169], v[190:193], v[60:63]
	v_mfma_f32_16x16x32_bf16 v[48:51], v[158:161], v[198:201], v[48:51]
	v_mfma_f32_16x16x32_bf16 v[44:47], v[166:169], v[198:201], v[44:47]
	v_mfma_f32_16x16x32_bf16 v[32:35], v[158:161], v[206:209], v[32:35]
	v_mfma_f32_16x16x32_bf16 v[28:31], v[166:169], v[206:209], v[28:31]
	v_mfma_f32_16x16x32_bf16 v[16:19], v[158:161], v[214:217], v[16:19]
	v_mfma_f32_16x16x32_bf16 v[12:15], v[166:169], v[214:217], v[12:15]
	v_mfma_f32_16x16x32_bf16 v[56:59], v[170:173], v[186:189], v[56:59]
	v_mfma_f32_16x16x32_bf16 v[52:55], v[178:181], v[186:189], v[52:55]
	v_mfma_f32_16x16x32_bf16 v[40:43], v[170:173], v[194:197], v[40:43]
	v_mfma_f32_16x16x32_bf16 v[36:39], v[178:181], v[194:197], v[36:39]
	v_mfma_f32_16x16x32_bf16 v[24:27], v[170:173], v[202:205], v[24:27]
	v_mfma_f32_16x16x32_bf16 v[20:23], v[178:181], v[202:205], v[20:23]
	v_mfma_f32_16x16x32_bf16 v[6:9], v[170:173], v[210:213], v[8:11]
	v_mfma_f32_16x16x32_bf16 v[2:5], v[178:181], v[210:213], v[2:5]
	v_mfma_f32_16x16x32_bf16 v[56:59], v[174:177], v[190:193], v[56:59]
	v_mfma_f32_16x16x32_bf16 v[52:55], v[182:185], v[190:193], v[52:55]
	v_mfma_f32_16x16x32_bf16 v[40:43], v[174:177], v[198:201], v[40:43]
	v_mfma_f32_16x16x32_bf16 v[36:39], v[182:185], v[198:201], v[36:39]
	v_mfma_f32_16x16x32_bf16 v[24:27], v[174:177], v[206:209], v[24:27]
	v_mfma_f32_16x16x32_bf16 v[20:23], v[182:185], v[206:209], v[20:23]
	v_mfma_f32_16x16x32_bf16 v[8:11], v[174:177], v[214:217], v[6:9]
	v_mfma_f32_16x16x32_bf16 v[4:7], v[182:185], v[214:217], v[2:5]
	s_barrier
	s_add_i32 s88, s88, 2
	s_add_u32 s6, s6, 0x100
	s_addc_u32 s7, s7, 0
	s_cmp_gt_u32 s88, 13
	s_mov_b64 s[56:57], s[10:11]
	s_cbranch_scc0 .LBB0_1764
	s_and_b64 vcc, exec, s[18:19]
	s_cbranch_vccz .LBB0_1767
	s_barrier

; template <class Epi, class Sched, bool ALIGN_EPI = false, bool SP2 = false>
; __device__ __forceinline__ void gemm_phase(PG8_LAS unsigned char* lds, const Gemm g, const Sched& S, const Epi& E, int wave_s) {
;     ...
;             const bool last = (t == nt - 2);
;             const char* a1 = cA + (size_t)(t + 1) * kstep;
;             const char* a2 = last ? nA : cA + (size_t)(t + 2) * kstep; const char* b2 = last ? nB : cB + (size_t)(t + 2) * kstep;
;             const char* a3 = a2 + kstep; const char* b3 = b2 + kstep;
.LBB0_2302:
	ds_read_b128 v[140:143], v147
	ds_read_b128 v[160:163], v147 offset:1024
	ds_read_b128 v[164:167], v147 offset:2048
	ds_read_b128 v[168:171], v147 offset:3072
	ds_read_b128 v[172:175], v148
	ds_read_b128 v[176:179], v148 offset:1024
	ds_read_b128 v[180:183], v148 offset:2048
	ds_read_b128 v[184:187], v148 offset:3072
	s_add_u32 s42, s40, 0x100
	s_addc_u32 s43, s41, 0
	s_cmp_eq_u32 s79, 12
	s_cselect_b32 s58, s37, s42
	s_cselect_b32 s59, s29, s43
	s_cselect_b32 s56, s39, s77
	s_cselect_b32 s57, s27, s78
	s_add_u32 s54, s58, 0x80
	s_addc_u32 s55, s59, 0
	s_add_u32 s6, s40, 0x40080
	s_addc_u32 s7, s41, 0
	ds_read_b128 v[188:191], v149
	ds_read_b128 v[192:195], v149 offset:1024
	ds_read_b128 v[196:199], v149 offset:2048
	ds_read_b128 v[200:203], v149 offset:3072
	ds_read_b128 v[204:207], v149 offset:4096
	ds_read_b128 v[208:211], v149 offset:5120
	ds_read_b128 v[212:215], v149 offset:6144
	ds_read_b128 v[216:219], v149 offset:7168
	s_add_i32 m0, s65, 0xc000
	s_nop 0
	global_load_lds_dwordx4 v128, s[6:7]
	s_add_i32 m0, s65, 0xe000
	s_nop 0
	global_load_lds_dwordx4 v132, s[6:7]
	s_waitcnt vmcnt(8)
	s_waitcnt lgkmcnt(0)
	s_barrier
	s_waitcnt lgkmcnt(0)
	v_mfma_f32_16x16x32_bf16 v[124:127], v[140:143], v[188:191], v[124:127]
	v_mfma_f32_16x16x32_bf16 v[120:123], v[164:167], v[188:191], v[120:123]
	v_mfma_f32_16x16x32_bf16 v[108:111], v[140:143], v[196:199], v[108:111]
	v_mfma_f32_16x16x32_bf16 v[104:107], v[164:167], v[196:199], v[104:107]
	v_mfma_f32_16x16x32_bf16 v[92:95], v[140:143], v[204:207], v[92:95]
	v_mfma_f32_16x16x32_bf16 v[88:91], v[164:167], v[204:207], v[88:91]
	v_mfma_f32_16x16x32_bf16 v[76:79], v[140:143], v[212:215], v[76:79]
	v_mfma_f32_16x16x32_bf16 v[72:75], v[164:167], v[212:215], v[72:75]
	v_mfma_f32_16x16x32_bf16 v[124:127], v[160:163], v[192:195], v[124:127]
	v_mfma_f32_16x16x32_bf16 v[120:123], v[168:171], v[192:195], v[120:123]
	v_mfma_f32_16x16x32_bf16 v[108:111], v[160:163], v[200:203], v[108:111]
	v_mfma_f32_16x16x32_bf16 v[104:107], v[168:171], v[200:203], v[104:107]
	v_mfma_f32_16x16x32_bf16 v[92:95], v[160:163], v[208:211], v[92:95]
	v_mfma_f32_16x16x32_bf16 v[88:91], v[168:171], v[208:211], v[88:91]
	v_mfma_f32_16x16x32_bf16 v[76:79], v[160:163], v[216:219], v[76:79]
	v_mfma_f32_16x16x32_bf16 v[72:75], v[168:171], v[216:219], v[72:75]
	v_mfma_f32_16x16x32_bf16 v[116:119], v[172:175], v[188:191], v[116:119]
	v_mfma_f32_16x16x32_bf16 v[112:115], v[180:183], v[188:191], v[112:115]
	v_mfma_f32_16x16x32_bf16 v[100:103], v[172:175], v[196:199], v[100:103]
	v_mfma_f32_16x16x32_bf16 v[96:99], v[180:183], v[196:199], v[96:99]
	v_mfma_f32_16x16x32_bf16 v[84:87], v[172:175], v[204:207], v[84:87]
	v_mfma_f32_16x16x32_bf16 v[80:83], v[180:183], v[204:207], v[80:83]
	v_mfma_f32_16x16x32_bf16 v[68:71], v[172:175], v[212:215], v[68:71]
	v_mfma_f32_16x16x32_bf16 v[64:67], v[180:183], v[212:215], v[64:67]
	v_mfma_f32_16x16x32_bf16 v[116:119], v[176:179], v[192:195], v[116:119]
	v_mfma_f32_16x16x32_bf16 v[112:115], v[184:187], v[192:195], v[112:115]
	v_mfma_f32_16x16x32_bf16 v[100:103], v[176:179], v[200:203], v[100:103]
	v_mfma_f32_16x16x32_bf16 v[96:99], v[184:187], v[200:203], v[96:99]
	v_mfma_f32_16x16x32_bf16 v[84:87], v[176:179], v[208:211], v[84:87]
	v_mfma_f32_16x16x32_bf16 v[80:83], v[184:187], v[208:211], v[80:83]
	v_mfma_f32_16x16x32_bf16 v[68:71], v[176:179], v[216:219], v[68:71]
	v_mfma_f32_16x16x32_bf16 v[64:67], v[184:187], v[216:219], v[64:67]
	s_barrier
	s_setprio 1
	s_mov_b64 s[6:7], s[56:57]
	s_add_i32 s40, s75, s64
	ds_read_b128 v[188:191], v149 offset:16384
	ds_read_b128 v[192:195], v149 offset:17408
	ds_read_b128 v[196:199], v149 offset:18432
	ds_read_b128 v[200:203], v149 offset:19456
	ds_read_b128 v[204:207], v149 offset:20480
	ds_read_b128 v[208:211], v149 offset:21504
	ds_read_b128 v[212:215], v149 offset:22528
	ds_read_b128 v[216:219], v149 offset:23552
	s_mov_b32 m0, s40
	s_nop 0
	global_load_lds_dwordx4 v130, s[6:7]
	s_add_i32 m0, s40, 0x2000
	s_nop 0
	global_load_lds_dwordx4 v134, s[6:7]
	s_add_u32 s6, s56, 0x40000
	s_addc_u32 s7, s57, 0
	s_add_i32 s40, s76, s64
	s_mov_b32 m0, s40
	s_nop 0
	global_load_lds_dwordx4 v130, s[6:7]
	s_mov_b64 s[98:99], s[6:7]
	s_add_i32 m0, s40, 0x2000
	s_mov_b64 s[6:7], s[58:59]
	global_load_lds_dwordx4 v134, s[98:99]
	s_mov_b32 m0, s65
	s_nop 0
	global_load_lds_dwordx4 v128, s[6:7]
	s_mov_b32 m0, s66
	s_nop 0
	global_load_lds_dwordx4 v132, s[6:7]
	s_setprio 0
	s_waitcnt vmcnt(8)
	s_waitcnt lgkmcnt(0)
	s_barrier
	s_waitcnt lgkmcnt(0)
	v_mfma_f32_16x16x32_bf16 v[60:63], v[140:143], v[188:191], v[60:63]
	v_mfma_f32_16x16x32_bf16 v[56:59], v[164:167], v[188:191], v[56:59]
	v_mfma_f32_16x16x32_bf16 v[44:47], v[140:143], v[196:199], v[44:47]
	v_mfma_f32_16x16x32_bf16 v[40:43], v[164:167], v[196:199], v[40:43]
	v_mfma_f32_16x16x32_bf16 v[28:31], v[140:143], v[204:207], v[28:31]
	v_mfma_f32_16x16x32_bf16 v[24:27], v[164:167], v[204:207], v[24:27]
	v_mfma_f32_16x16x32_bf16 v[12:15], v[140:143], v[212:215], v[12:15]
	v_mfma_f32_16x16x32_bf16 v[8:11], v[164:167], v[212:215], v[8:11]
	v_mfma_f32_16x16x32_bf16 v[60:63], v[160:163], v[192:195], v[60:63]
	v_mfma_f32_16x16x32_bf16 v[56:59], v[168:171], v[192:195], v[56:59]
	v_mfma_f32_16x16x32_bf16 v[44:47], v[160:163], v[200:203], v[44:47]
	v_mfma_f32_16x16x32_bf16 v[40:43], v[168:171], v[200:203], v[40:43]
	v_mfma_f32_16x16x32_bf16 v[28:31], v[160:163], v[208:211], v[28:31]
	v_mfma_f32_16x16x32_bf16 v[24:27], v[168:171], v[208:211], v[24:27]
	v_mfma_f32_16x16x32_bf16 v[12:15], v[160:163], v[216:219], v[12:15]
	v_mfma_f32_16x16x32_bf16 v[8:11], v[168:171], v[216:219], v[8:11]
	v_mfma_f32_16x16x32_bf16 v[52:55], v[172:175], v[188:191], v[52:55]
	v_mfma_f32_16x16x32_bf16 v[48:51], v[180:183], v[188:191], v[48:51]
	v_mfma_f32_16x16x32_bf16 v[36:39], v[172:175], v[196:199], v[36:39]
	v_mfma_f32_16x16x32_bf16 v[32:35], v[180:183], v[196:199], v[32:35]
	v_mfma_f32_16x16x32_bf16 v[20:23], v[172:175], v[204:207], v[20:23]
	v_mfma_f32_16x16x32_bf16 v[16:19], v[180:183], v[204:207], v[16:19]
	v_mfma_f32_16x16x32_bf16 v[4:7], v[172:175], v[212:215], v[4:7]
	v_mfma_f32_16x16x32_bf16 v[0:3], v[180:183], v[212:215], v[0:3]
	v_mfma_f32_16x16x32_bf16 v[52:55], v[176:179], v[192:195], v[52:55]
	v_mfma_f32_16x16x32_bf16 v[48:51], v[184:187], v[192:195], v[48:51]
	v_mfma_f32_16x16x32_bf16 v[36:39], v[176:179], v[200:203], v[36:39]
	v_mfma_f32_16x16x32_bf16 v[32:35], v[184:187], v[200:203], v[32:35]
	v_mfma_f32_16x16x32_bf16 v[20:23], v[176:179], v[208:211], v[20:23]
	v_mfma_f32_16x16x32_bf16 v[16:19], v[184:187], v[208:211], v[16:19]
	v_mfma_f32_16x16x32_bf16 v[4:7], v[176:179], v[216:219], v[4:7]
	v_mfma_f32_16x16x32_bf16 v[0:3], v[184:187], v[216:219], v[0:3]
	s_barrier
	s_add_i32 s40, 0, 0x18000
	v_add_u32_e32 v159, s40, v145
	s_add_i32 s41, 0, 0x1c000
	ds_read_b128 v[140:143], v159
	ds_read_b128 v[160:163], v159 offset:1024
	ds_read_b128 v[164:167], v159 offset:2048
	ds_read_b128 v[168:171], v159 offset:3072
	v_add_u32_e32 v159, s41, v145
	ds_read_b128 v[172:175], v159
	ds_read_b128 v[176:179], v159 offset:1024
	ds_read_b128 v[180:183], v159 offset:2048
	ds_read_b128 v[184:187], v159 offset:3072
	s_add_u32 s6, s58, 0x40000
	s_addc_u32 s7, s59, 0
	s_mov_b32 m0, s67
	ds_read_b128 v[188:191], v149 offset:32768
	ds_read_b128 v[192:195], v149 offset:33792
	ds_read_b128 v[196:199], v149 offset:34816
	ds_read_b128 v[200:203], v149 offset:35840
	ds_read_b128 v[204:207], v149 offset:36864
	ds_read_b128 v[208:211], v149 offset:37888
	ds_read_b128 v[212:215], v149 offset:38912
	ds_read_b128 v[216:219], v149 offset:39936
	s_nop 0
	global_load_lds_dwordx4 v128, s[6:7]
	s_mov_b32 m0, s68
	s_nop 0
	global_load_lds_dwordx4 v132, s[6:7]
	s_waitcnt vmcnt(8)
	s_waitcnt lgkmcnt(0)
	s_barrier
	s_waitcnt lgkmcnt(0)
	v_mfma_f32_16x16x32_bf16 v[124:127], v[140:143], v[188:191], v[124:127]
	v_mfma_f32_16x16x32_bf16 v[120:123], v[164:167], v[188:191], v[120:123]
	v_mfma_f32_16x16x32_bf16 v[108:111], v[140:143], v[196:199], v[108:111]
	v_mfma_f32_16x16x32_bf16 v[104:107], v[164:167], v[196:199], v[104:107]
	v_mfma_f32_16x16x32_bf16 v[92:95], v[140:143], v[204:207], v[92:95]
	v_mfma_f32_16x16x32_bf16 v[88:91], v[164:167], v[204:207], v[88:91]
	v_mfma_f32_16x16x32_bf16 v[76:79], v[140:143], v[212:215], v[76:79]
	v_mfma_f32_16x16x32_bf16 v[72:75], v[164:167], v[212:215], v[72:75]
	v_mfma_f32_16x16x32_bf16 v[124:127], v[160:163], v[192:195], v[124:127]
	v_mfma_f32_16x16x32_bf16 v[120:123], v[168:171], v[192:195], v[120:123]
	v_mfma_f32_16x16x32_bf16 v[108:111], v[160:163], v[200:203], v[108:111]
	v_mfma_f32_16x16x32_bf16 v[104:107], v[168:171], v[200:203], v[104:107]
	v_mfma_f32_16x16x32_bf16 v[92:95], v[160:163], v[208:211], v[92:95]
	v_mfma_f32_16x16x32_bf16 v[88:91], v[168:171], v[208:211], v[88:91]
	v_mfma_f32_16x16x32_bf16 v[76:79], v[160:163], v[216:219], v[76:79]
	v_mfma_f32_16x16x32_bf16 v[72:75], v[168:171], v[216:219], v[72:75]
	v_mfma_f32_16x16x32_bf16 v[116:119], v[172:175], v[188:191], v[116:119]
	v_mfma_f32_16x16x32_bf16 v[112:115], v[180:183], v[188:191], v[112:115]
	v_mfma_f32_16x16x32_bf16 v[100:103], v[172:175], v[196:199], v[100:103]
	v_mfma_f32_16x16x32_bf16 v[96:99], v[180:183], v[196:199], v[96:99]
	v_mfma_f32_16x16x32_bf16 v[84:87], v[172:175], v[204:207], v[84:87]
	v_mfma_f32_16x16x32_bf16 v[80:83], v[180:183], v[204:207], v[80:83]
	v_mfma_f32_16x16x32_bf16 v[68:71], v[172:175], v[212:215], v[68:71]
	v_mfma_f32_16x16x32_bf16 v[64:67], v[180:183], v[212:215], v[64:67]
	v_mfma_f32_16x16x32_bf16 v[116:119], v[176:179], v[192:195], v[116:119]
	v_mfma_f32_16x16x32_bf16 v[112:115], v[184:187], v[192:195], v[112:115]
	v_mfma_f32_16x16x32_bf16 v[100:103], v[176:179], v[200:203], v[100:103]
	v_mfma_f32_16x16x32_bf16 v[96:99], v[184:187], v[200:203], v[96:99]
	v_mfma_f32_16x16x32_bf16 v[84:87], v[176:179], v[208:211], v[84:87]
	v_mfma_f32_16x16x32_bf16 v[80:83], v[184:187], v[208:211], v[80:83]
	v_mfma_f32_16x16x32_bf16 v[68:71], v[176:179], v[216:219], v[68:71]
	v_mfma_f32_16x16x32_bf16 v[64:67], v[184:187], v[216:219], v[64:67]
	s_barrier
	s_setprio 1
	s_add_u32 s6, s56, 0x80
	s_addc_u32 s7, s57, 0
	s_add_i32 s40, s40, s64
	ds_read_b128 v[188:191], v149 offset:49152
	ds_read_b128 v[192:195], v149 offset:50176
	ds_read_b128 v[196:199], v149 offset:51200
	ds_read_b128 v[200:203], v149 offset:52224
	ds_read_b128 v[204:207], v149 offset:53248
	ds_read_b128 v[208:211], v149 offset:54272
	ds_read_b128 v[212:215], v149 offset:55296
	ds_read_b128 v[216:219], v149 offset:56320
	s_mov_b32 m0, s40
	s_nop 0
	global_load_lds_dwordx4 v130, s[6:7]
	s_add_i32 m0, s40, 0x2000
	s_nop 0
	global_load_lds_dwordx4 v134, s[6:7]
	s_add_u32 s6, s56, 0x40080
	s_addc_u32 s7, s57, 0
	s_add_i32 s40, s41, s64
	s_mov_b32 m0, s40
	s_nop 0
	global_load_lds_dwordx4 v130, s[6:7]
	s_add_i32 m0, s40, 0x2000
	s_nop 0
	global_load_lds_dwordx4 v134, s[6:7]
	s_mov_b32 m0, s70
	s_nop 0
	global_load_lds_dwordx4 v128, s[54:55]
	s_mov_b32 m0, s71
	s_nop 0
	global_load_lds_dwordx4 v132, s[54:55]
	s_setprio 0
	s_waitcnt vmcnt(8)
	s_waitcnt lgkmcnt(0)
	s_barrier
	s_waitcnt lgkmcnt(0)
	v_mfma_f32_16x16x32_bf16 v[60:63], v[140:143], v[188:191], v[60:63]
	v_mfma_f32_16x16x32_bf16 v[56:59], v[164:167], v[188:191], v[56:59]
	v_mfma_f32_16x16x32_bf16 v[44:47], v[140:143], v[196:199], v[44:47]
	v_mfma_f32_16x16x32_bf16 v[40:43], v[164:167], v[196:199], v[40:43]
	v_mfma_f32_16x16x32_bf16 v[28:31], v[140:143], v[204:207], v[28:31]
	v_mfma_f32_16x16x32_bf16 v[24:27], v[164:167], v[204:207], v[24:27]
	v_mfma_f32_16x16x32_bf16 v[12:15], v[140:143], v[212:215], v[12:15]
	v_mfma_f32_16x16x32_bf16 v[8:11], v[164:167], v[212:215], v[8:11]
	v_mfma_f32_16x16x32_bf16 v[60:63], v[160:163], v[192:195], v[60:63]
	v_mfma_f32_16x16x32_bf16 v[56:59], v[168:171], v[192:195], v[56:59]
	v_mfma_f32_16x16x32_bf16 v[44:47], v[160:163], v[200:203], v[44:47]
	v_mfma_f32_16x16x32_bf16 v[40:43], v[168:171], v[200:203], v[40:43]
	v_mfma_f32_16x16x32_bf16 v[28:31], v[160:163], v[208:211], v[28:31]
	v_mfma_f32_16x16x32_bf16 v[24:27], v[168:171], v[208:211], v[24:27]
	v_mfma_f32_16x16x32_bf16 v[12:15], v[160:163], v[216:219], v[12:15]
	v_mfma_f32_16x16x32_bf16 v[8:11], v[168:171], v[216:219], v[8:11]
	v_mfma_f32_16x16x32_bf16 v[52:55], v[172:175], v[188:191], v[52:55]
	v_mfma_f32_16x16x32_bf16 v[48:51], v[180:183], v[188:191], v[48:51]
	v_mfma_f32_16x16x32_bf16 v[36:39], v[172:175], v[196:199], v[36:39]
	v_mfma_f32_16x16x32_bf16 v[32:35], v[180:183], v[196:199], v[32:35]
	v_mfma_f32_16x16x32_bf16 v[20:23], v[172:175], v[204:207], v[20:23]
	v_mfma_f32_16x16x32_bf16 v[16:19], v[180:183], v[204:207], v[16:19]
	v_mfma_f32_16x16x32_bf16 v[4:7], v[172:175], v[212:215], v[4:7]
	v_mfma_f32_16x16x32_bf16 v[0:3], v[180:183], v[212:215], v[0:3]
	v_mfma_f32_16x16x32_bf16 v[52:55], v[176:179], v[192:195], v[52:55]
	v_mfma_f32_16x16x32_bf16 v[48:51], v[184:187], v[192:195], v[48:51]
	v_mfma_f32_16x16x32_bf16 v[36:39], v[176:179], v[200:203], v[36:39]
	v_mfma_f32_16x16x32_bf16 v[32:35], v[184:187], v[200:203], v[32:35]
	v_mfma_f32_16x16x32_bf16 v[20:23], v[176:179], v[208:211], v[20:23]
	v_mfma_f32_16x16x32_bf16 v[16:19], v[184:187], v[208:211], v[16:19]
	v_mfma_f32_16x16x32_bf16 v[4:7], v[176:179], v[216:219], v[4:7]
	v_mfma_f32_16x16x32_bf16 v[0:3], v[184:187], v[216:219], v[0:3]
	s_barrier
	s_add_i32 s79, s79, 2
	s_add_u32 s77, s77, 0x100
	s_addc_u32 s78, s78, 0
	s_cmp_gt_u32 s79, 13
	s_mov_b64 s[40:41], s[42:43]
	s_cbranch_scc0 .LBB0_2302
	s_and_b64 vcc, exec, s[16:17]
	s_cbranch_vccz .LBB0_2305
	s_barrier

; __device__ __forceinline__ int lane_id_() { int l; asm volatile("v_mbcnt_lo_u32_b32 %0, -1, 0\n\tv_mbcnt_hi_u32_b32 %0, -1, %0" : "=v"(l)); return l; }
; #define PG8_LAS __attribute__((address_space(3)))
;     __device__ __forceinline__ void prefetch(PG8_LAS unsigned char* lds, int wid, const Unit& u, int wr, int fr, int fq) const {
;         { const int l_ = lane_id_(); fr = l_ & 15; fq = l_ >> 4; }
; #pragma unroll
;         for (int j = 0; j < 2; ++j) { const int i = 2 * fq + j;
;             __builtin_amdgcn_global_load_lds((const unsigned*)(ssq + u.pm * BM + wr * 64 + fr + (i >> 2) * HALF + (i & 3) * 16), (PG8_LAS unsigned*)(lds + PRE_SLOT + wid * 512 + j * 256), 4, 0, 0); }
.LBB0_2385:
	s_lshl_b32 s6, s16, 8
	s_ashr_i32 s7, s6, 31
	s_lshl_b64 s[6:7], s[6:7], 2
	v_mbcnt_lo_u32_b32 v6, -1, 0
	v_mbcnt_hi_u32_b32 v6, -1, v6
	s_add_u32 s6, s57, s6
	v_and_b32_e32 v0, 15, v6
	v_lshlrev_b32_e32 v2, 2, v6
	v_and_b32_e32 v2, 0xffffff80, v2
	s_addc_u32 s7, s58, s7
	v_lshlrev_b32_e32 v0, 2, v0
	v_ashrrev_i32_e32 v3, 31, v2
	v_lshl_add_u64 v[4:5], s[6:7], 0, v[0:1]
	v_lshlrev_b32_e32 v0, 3, v6
	v_lshl_add_u64 v[2:3], v[2:3], 2, v[4:5]
	v_and_b32_e32 v0, 0x80, v0
	s_mov_b32 m0, s41
	v_lshl_add_u64 v[2:3], v[2:3], 0, v[0:1]
	global_load_lds_dword v[2:3], off
	v_lshl_add_u64 v[2:3], v[2:3], 0, 64
	s_add_i32 m0, s41, 0x100
	s_add_u32 s22, s18, 0x100
	global_load_lds_dword v[2:3], off
	ds_read_b128 v[2:5], v151
	ds_read_b128 v[6:9], v151 offset:1024
	ds_read_b128 v[10:13], v151 offset:2048
	ds_read_b128 v[14:17], v151 offset:3072
	ds_read_b128 v[18:21], v150
	ds_read_b128 v[22:25], v150 offset:1024
	ds_read_b128 v[26:29], v150 offset:2048
	ds_read_b128 v[30:33], v150 offset:3072
	s_addc_u32 s23, s19, 0
	s_add_u32 s6, s18, 0x180
	s_addc_u32 s7, s19, 0
	s_add_u32 s24, s20, 0x100
	s_addc_u32 s25, s21, 0
	s_add_u32 s26, s18, 0x40080
	s_addc_u32 s27, s19, 0
	s_mov_b32 m0, s65
	ds_read_b128 v[34:37], v149
	ds_read_b128 v[38:41], v149 offset:1024
	ds_read_b128 v[42:45], v149 offset:2048
	ds_read_b128 v[46:49], v149 offset:3072
	ds_read_b128 v[50:53], v149 offset:4096
	ds_read_b128 v[54:57], v149 offset:5120
	ds_read_b128 v[58:61], v149 offset:6144
	ds_read_b128 v[62:65], v149 offset:7168
	s_nop 0
	global_load_lds_dwordx4 v138, s[26:27]
	s_mov_b32 m0, s8
	s_nop 0
	global_load_lds_dwordx4 v134, s[26:27]
	s_waitcnt vmcnt(18)
	s_waitcnt lgkmcnt(0)
	s_barrier
	s_waitcnt lgkmcnt(0)
	v_mfma_f32_16x16x32_bf16 v[90:93], v[2:5], v[58:61], 0
	v_mfma_f32_16x16x32_bf16 v[66:69], v[2:5], v[34:37], 0
	v_mfma_f32_16x16x32_bf16 v[70:73], v[10:13], v[34:37], 0
	v_mfma_f32_16x16x32_bf16 v[74:77], v[2:5], v[42:45], 0
	v_mfma_f32_16x16x32_bf16 v[78:81], v[10:13], v[42:45], 0
	v_mfma_f32_16x16x32_bf16 v[82:85], v[2:5], v[50:53], 0
	v_mfma_f32_16x16x32_bf16 v[86:89], v[10:13], v[50:53], 0
	v_mfma_f32_16x16x32_bf16 v[96:99], v[6:9], v[62:65], v[90:93]
	v_mfma_f32_16x16x32_bf16 v[90:93], v[10:13], v[58:61], 0
	v_mfma_f32_16x16x32_bf16 v[66:69], v[6:9], v[38:41], v[66:69]
	v_mfma_f32_16x16x32_bf16 v[70:73], v[14:17], v[38:41], v[70:73]
	v_mfma_f32_16x16x32_bf16 v[74:77], v[6:9], v[46:49], v[74:77]
	v_mfma_f32_16x16x32_bf16 v[78:81], v[14:17], v[46:49], v[78:81]
	v_mfma_f32_16x16x32_bf16 v[82:85], v[6:9], v[54:57], v[82:85]
	v_mfma_f32_16x16x32_bf16 v[86:89], v[14:17], v[54:57], v[86:89]
	v_mfma_f32_16x16x32_bf16 v[104:107], v[14:17], v[62:65], v[90:93]
	v_mfma_f32_16x16x32_bf16 v[90:93], v[18:21], v[34:37], 0
	v_mfma_f32_16x16x32_bf16 v[34:37], v[26:29], v[34:37], 0
	v_mfma_f32_16x16x32_bf16 v[112:115], v[22:25], v[38:41], v[90:93]
	v_mfma_f32_16x16x32_bf16 v[34:37], v[30:33], v[38:41], v[34:37]
	v_mfma_f32_16x16x32_bf16 v[38:41], v[18:21], v[42:45], 0
	v_mfma_f32_16x16x32_bf16 v[42:45], v[26:29], v[42:45], 0
	v_mfma_f32_16x16x32_bf16 v[38:41], v[22:25], v[46:49], v[38:41]
	v_mfma_f32_16x16x32_bf16 v[42:45], v[30:33], v[46:49], v[42:45]
	v_mfma_f32_16x16x32_bf16 v[46:49], v[18:21], v[50:53], 0
	v_mfma_f32_16x16x32_bf16 v[50:53], v[26:29], v[50:53], 0
	v_mfma_f32_16x16x32_bf16 v[46:49], v[22:25], v[54:57], v[46:49]
	v_mfma_f32_16x16x32_bf16 v[50:53], v[30:33], v[54:57], v[50:53]
	v_mfma_f32_16x16x32_bf16 v[54:57], v[18:21], v[58:61], 0
	v_mfma_f32_16x16x32_bf16 v[54:57], v[22:25], v[62:65], v[54:57]
	v_mfma_f32_16x16x32_bf16 v[58:61], v[26:29], v[58:61], 0
	v_mfma_f32_16x16x32_bf16 v[154:157], v[30:33], v[62:65], v[58:61]
	s_barrier
	s_setprio 1
	s_mov_b32 m0, s64
	s_nop 3
	ds_read_b128 v[58:61], v149 offset:16384
	ds_read_b128 v[62:65], v149 offset:17408
	ds_read_b128 v[90:93], v149 offset:18432
	ds_read_b128 v[100:103], v149 offset:19456
	ds_read_b128 v[108:111], v149 offset:20480
	ds_read_b128 v[116:119], v149 offset:21504
	ds_read_b128 v[120:123], v149 offset:22528
	ds_read_b128 v[124:127], v149 offset:23552
	s_nop 0
	global_load_lds_dwordx4 v136, s[24:25]
	s_mov_b64 s[98:99], s[24:25]
	s_add_u32 s24, s20, 0x40100
	s_mov_b32 m0, s15
	s_addc_u32 s25, s21, 0
	global_load_lds_dwordx4 v132, s[98:99]
	s_mov_b32 m0, s17
	s_nop 0
	global_load_lds_dwordx4 v136, s[24:25]
	s_mov_b32 m0, s63
	s_nop 0
	global_load_lds_dwordx4 v132, s[24:25]
	s_mov_b32 m0, s42
	s_nop 0
	global_load_lds_dwordx4 v138, s[22:23]
	s_mov_b32 m0, s43
	s_nop 0
	global_load_lds_dwordx4 v134, s[22:23]
	s_setprio 0
	s_waitcnt vmcnt(18)
	s_waitcnt lgkmcnt(0)
	s_barrier
	s_waitcnt lgkmcnt(0)
	v_mfma_f32_16x16x32_bf16 v[128:131], v[2:5], v[58:61], 0
	v_mfma_f32_16x16x32_bf16 v[158:161], v[6:9], v[62:65], v[128:131]
	v_mfma_f32_16x16x32_bf16 v[128:131], v[10:13], v[58:61], 0
	v_mfma_f32_16x16x32_bf16 v[162:165], v[14:17], v[62:65], v[128:131]
	v_mfma_f32_16x16x32_bf16 v[128:131], v[2:5], v[90:93], 0
	v_mfma_f32_16x16x32_bf16 v[166:169], v[6:9], v[100:103], v[128:131]
	v_mfma_f32_16x16x32_bf16 v[128:131], v[10:13], v[90:93], 0
	v_mfma_f32_16x16x32_bf16 v[170:173], v[14:17], v[100:103], v[128:131]
	v_mfma_f32_16x16x32_bf16 v[128:131], v[2:5], v[108:111], 0
	v_mfma_f32_16x16x32_bf16 v[2:5], v[2:5], v[120:123], 0
	v_mfma_f32_16x16x32_bf16 v[174:177], v[6:9], v[116:119], v[128:131]
	v_mfma_f32_16x16x32_bf16 v[2:5], v[6:9], v[124:127], v[2:5]
	v_mfma_f32_16x16x32_bf16 v[6:9], v[10:13], v[120:123], 0
	v_mfma_f32_16x16x32_bf16 v[128:131], v[10:13], v[108:111], 0
	v_mfma_f32_16x16x32_bf16 v[6:9], v[14:17], v[124:127], v[6:9]
	v_mfma_f32_16x16x32_bf16 v[178:181], v[14:17], v[116:119], v[128:131]
	v_mfma_f32_16x16x32_bf16 v[10:13], v[18:21], v[58:61], 0
	v_mfma_f32_16x16x32_bf16 v[182:185], v[22:25], v[62:65], v[10:13]
	v_mfma_f32_16x16x32_bf16 v[10:13], v[26:29], v[58:61], 0
	v_mfma_f32_16x16x32_bf16 v[186:189], v[30:33], v[62:65], v[10:13]
	v_mfma_f32_16x16x32_bf16 v[10:13], v[18:21], v[90:93], 0
	v_mfma_f32_16x16x32_bf16 v[190:193], v[22:25], v[100:103], v[10:13]
	v_mfma_f32_16x16x32_bf16 v[10:13], v[26:29], v[90:93], 0
	v_mfma_f32_16x16x32_bf16 v[194:197], v[30:33], v[100:103], v[10:13]
	v_mfma_f32_16x16x32_bf16 v[10:13], v[18:21], v[108:111], 0
	v_mfma_f32_16x16x32_bf16 v[198:201], v[22:25], v[116:119], v[10:13]
	v_mfma_f32_16x16x32_bf16 v[10:13], v[26:29], v[108:111], 0
	v_mfma_f32_16x16x32_bf16 v[202:205], v[30:33], v[116:119], v[10:13]
	v_mfma_f32_16x16x32_bf16 v[10:13], v[18:21], v[120:123], 0
	v_mfma_f32_16x16x32_bf16 v[16:19], v[22:25], v[124:127], v[10:13]
	v_mfma_f32_16x16x32_bf16 v[10:13], v[26:29], v[120:123], 0
	v_mfma_f32_16x16x32_bf16 v[206:209], v[30:33], v[124:127], v[10:13]
	s_barrier
	s_nop 4
	ds_read_b128 v[10:13], v152
	ds_read_b128 v[24:27], v152 offset:1024
	ds_read_b128 v[210:213], v152 offset:2048
	ds_read_b128 v[214:217], v152 offset:3072
	ds_read_b128 v[218:221], v153
	ds_read_b128 v[222:225], v153 offset:1024
	ds_read_b128 v[226:229], v153 offset:2048
	ds_read_b128 v[150:153], v153 offset:3072
	s_add_u32 s22, s18, 0x40100
	s_addc_u32 s23, s19, 0
	s_mov_b32 m0, s52
	ds_read_b128 v[20:23], v149 offset:32768
	ds_read_b128 v[28:31], v149 offset:33792
	ds_read_b128 v[230:233], v149 offset:34816
	ds_read_b128 v[234:237], v149 offset:35840
	ds_read_b128 v[238:241], v149 offset:36864
	ds_read_b128 v[242:245], v149 offset:37888
	ds_read_b128 v[246:249], v149 offset:38912
	ds_read_b128 v[250:253], v149 offset:39936
	s_nop 0
	global_load_lds_dwordx4 v138, s[22:23]
	s_mov_b32 m0, s53
	s_nop 0
	global_load_lds_dwordx4 v134, s[22:23]
	s_waitcnt vmcnt(18)
	s_waitcnt lgkmcnt(0)
	s_barrier
	s_waitcnt lgkmcnt(0)
	v_mfma_f32_16x16x32_bf16 v[58:61], v[10:13], v[20:23], v[66:69]
	v_mfma_f32_16x16x32_bf16 v[124:127], v[24:27], v[28:31], v[58:61]
	v_mfma_f32_16x16x32_bf16 v[58:61], v[210:213], v[20:23], v[70:73]
	v_mfma_f32_16x16x32_bf16 v[116:119], v[214:217], v[28:31], v[58:61]
	v_mfma_f32_16x16x32_bf16 v[58:61], v[10:13], v[230:233], v[74:77]
	v_mfma_f32_16x16x32_bf16 v[108:111], v[24:27], v[234:237], v[58:61]
	v_mfma_f32_16x16x32_bf16 v[58:61], v[210:213], v[230:233], v[78:81]
	v_mfma_f32_16x16x32_bf16 v[100:103], v[214:217], v[234:237], v[58:61]
	v_mfma_f32_16x16x32_bf16 v[58:61], v[10:13], v[238:241], v[82:85]
	v_mfma_f32_16x16x32_bf16 v[92:95], v[24:27], v[242:245], v[58:61]
	v_mfma_f32_16x16x32_bf16 v[58:61], v[210:213], v[238:241], v[86:89]
	v_mfma_f32_16x16x32_bf16 v[84:87], v[214:217], v[242:245], v[58:61]
	v_mfma_f32_16x16x32_bf16 v[58:61], v[10:13], v[246:249], v[96:99]
	v_mfma_f32_16x16x32_bf16 v[76:79], v[24:27], v[250:253], v[58:61]
	v_mfma_f32_16x16x32_bf16 v[58:61], v[210:213], v[246:249], v[104:107]
	v_mfma_f32_16x16x32_bf16 v[60:63], v[214:217], v[250:253], v[58:61]
	v_mfma_f32_16x16x32_bf16 v[64:67], v[218:221], v[20:23], v[112:115]
	v_mfma_f32_16x16x32_bf16 v[20:23], v[226:229], v[20:23], v[34:37]
	v_mfma_f32_16x16x32_bf16 v[120:123], v[150:153], v[28:31], v[20:23]
	v_mfma_f32_16x16x32_bf16 v[20:23], v[218:221], v[230:233], v[38:41]
	v_mfma_f32_16x16x32_bf16 v[112:115], v[222:225], v[234:237], v[20:23]
	v_mfma_f32_16x16x32_bf16 v[20:23], v[226:229], v[230:233], v[42:45]
	v_mfma_f32_16x16x32_bf16 v[104:107], v[150:153], v[234:237], v[20:23]
	v_mfma_f32_16x16x32_bf16 v[20:23], v[218:221], v[238:241], v[46:49]
	v_mfma_f32_16x16x32_bf16 v[96:99], v[222:225], v[242:245], v[20:23]
	v_mfma_f32_16x16x32_bf16 v[20:23], v[226:229], v[238:241], v[50:53]
	v_mfma_f32_16x16x32_bf16 v[88:91], v[150:153], v[242:245], v[20:23]
	v_mfma_f32_16x16x32_bf16 v[20:23], v[218:221], v[246:249], v[54:57]
	v_mfma_f32_16x16x32_bf16 v[80:83], v[222:225], v[250:253], v[20:23]
	v_mfma_f32_16x16x32_bf16 v[20:23], v[226:229], v[246:249], v[154:157]
	v_mfma_f32_16x16x32_bf16 v[128:131], v[222:225], v[28:31], v[64:67]
	v_mfma_f32_16x16x32_bf16 v[68:71], v[150:153], v[250:253], v[20:23]
	s_barrier
	s_setprio 1
	s_add_u32 s22, s20, 0x180
	s_addc_u32 s23, s21, 0
	s_mov_b32 m0, s31
	ds_read_b128 v[32:35], v149 offset:49152
	ds_read_b128 v[40:43], v149 offset:50176
	ds_read_b128 v[154:157], v149 offset:51200
	ds_read_b128 v[230:233], v149 offset:52224
	ds_read_b128 v[234:237], v149 offset:53248
	ds_read_b128 v[238:241], v149 offset:54272
	ds_read_b128 v[242:245], v149 offset:55296
	ds_read_b128 v[246:249], v149 offset:56320
	s_nop 0
	global_load_lds_dwordx4 v136, s[22:23]
	s_mov_b64 s[98:99], s[22:23]
	s_add_u32 s22, s20, 0x40180
	s_mov_b32 m0, s30
	s_addc_u32 s23, s21, 0
	global_load_lds_dwordx4 v132, s[98:99]
	s_mov_b32 m0, s28
	s_nop 0
	global_load_lds_dwordx4 v136, s[22:23]
	s_mov_b32 m0, s29
	s_nop 0
	global_load_lds_dwordx4 v132, s[22:23]
	s_mov_b32 m0, s54
	s_nop 0
	global_load_lds_dwordx4 v138, s[6:7]
	s_mov_b32 m0, s55
	s_nop 0
	global_load_lds_dwordx4 v134, s[6:7]
	s_setprio 0
	s_waitcnt vmcnt(18)
	s_waitcnt lgkmcnt(0)
	s_barrier
	s_waitcnt lgkmcnt(0)
	v_mfma_f32_16x16x32_bf16 v[20:23], v[10:13], v[32:35], v[158:161]
	v_mfma_f32_16x16x32_bf16 v[64:67], v[24:27], v[40:43], v[20:23]
	v_mfma_f32_16x16x32_bf16 v[20:23], v[210:213], v[32:35], v[162:165]
	v_mfma_f32_16x16x32_bf16 v[52:55], v[214:217], v[40:43], v[20:23]
	v_mfma_f32_16x16x32_bf16 v[20:23], v[10:13], v[154:157], v[166:169]
	v_mfma_f32_16x16x32_bf16 v[44:47], v[24:27], v[230:233], v[20:23]
	v_mfma_f32_16x16x32_bf16 v[20:23], v[210:213], v[154:157], v[170:173]
	v_mfma_f32_16x16x32_bf16 v[36:39], v[214:217], v[230:233], v[20:23]
	v_mfma_f32_16x16x32_bf16 v[20:23], v[10:13], v[234:237], v[174:177]
	v_mfma_f32_16x16x32_bf16 v[2:5], v[10:13], v[242:245], v[2:5]
	v_mfma_f32_16x16x32_bf16 v[28:31], v[24:27], v[238:241], v[20:23]
	v_mfma_f32_16x16x32_bf16 v[20:23], v[210:213], v[234:237], v[178:181]
	v_mfma_f32_16x16x32_bf16 v[12:15], v[24:27], v[246:249], v[2:5]
	v_mfma_f32_16x16x32_bf16 v[2:5], v[210:213], v[242:245], v[6:9]
	v_mfma_f32_16x16x32_bf16 v[20:23], v[214:217], v[238:241], v[20:23]
	v_mfma_f32_16x16x32_bf16 v[4:7], v[214:217], v[246:249], v[2:5]
	v_mfma_f32_16x16x32_bf16 v[8:11], v[218:221], v[32:35], v[182:185]
	v_mfma_f32_16x16x32_bf16 v[72:75], v[222:225], v[40:43], v[8:11]
	v_mfma_f32_16x16x32_bf16 v[8:11], v[226:229], v[32:35], v[186:189]
	v_mfma_f32_16x16x32_bf16 v[56:59], v[150:153], v[40:43], v[8:11]
	v_mfma_f32_16x16x32_bf16 v[8:11], v[218:221], v[154:157], v[190:193]
	v_mfma_f32_16x16x32_bf16 v[48:51], v[222:225], v[230:233], v[8:11]
	v_mfma_f32_16x16x32_bf16 v[8:11], v[226:229], v[154:157], v[194:197]
	v_mfma_f32_16x16x32_bf16 v[40:43], v[150:153], v[230:233], v[8:11]
	v_mfma_f32_16x16x32_bf16 v[8:11], v[218:221], v[234:237], v[198:201]
	v_mfma_f32_16x16x32_bf16 v[32:35], v[222:225], v[238:241], v[8:11]
	v_mfma_f32_16x16x32_bf16 v[8:11], v[226:229], v[234:237], v[202:205]
	v_mfma_f32_16x16x32_bf16 v[24:27], v[150:153], v[238:241], v[8:11]
	v_mfma_f32_16x16x32_bf16 v[8:11], v[218:221], v[242:245], v[16:19]
	v_mfma_f32_16x16x32_bf16 v[16:19], v[222:225], v[246:249], v[8:11]
	v_mfma_f32_16x16x32_bf16 v[8:11], v[226:229], v[242:245], v[206:209]
	v_mfma_f32_16x16x32_bf16 v[8:11], v[150:153], v[246:249], v[8:11]
	s_barrier
	s_mov_b64 s[6:7], 0

; template <class Epi, class Sched, bool ALIGN_EPI = false, bool SP2 = false>
; __device__ __forceinline__ void gemm_phase(PG8_LAS unsigned char* lds, const Gemm g, const Sched& S, const Epi& E, int wave_s) {
;     ...
;             const bool last = (t == nt - 2);
;             const char* a1 = cA + (size_t)(t + 1) * kstep;
;             const char* a2 = last ? nA : cA + (size_t)(t + 2) * kstep; const char* b2 = last ? nB : cB + (size_t)(t + 2) * kstep;
;             const char* a3 = a2 + kstep; const char* b3 = b2 + kstep;
.LBB0_2390:
	v_add_u32_e32 v151, s59, v146
	v_add_u32_e32 v150, s60, v146
	ds_read_b128 v[152:155], v151
	ds_read_b128 v[156:159], v151 offset:1024
	ds_read_b128 v[160:163], v151 offset:2048
	ds_read_b128 v[164:167], v151 offset:3072
	ds_read_b128 v[168:171], v150
	ds_read_b128 v[172:175], v150 offset:1024
	ds_read_b128 v[176:179], v150 offset:2048
	ds_read_b128 v[180:183], v150 offset:3072
	s_add_u32 s24, s34, 0x100
	s_addc_u32 s25, s35, 0
	s_cmp_eq_u32 s70, 12
	s_cselect_b32 s30, s67, s24
	s_cselect_b32 s31, s66, s25
	s_cselect_b32 s28, s69, s71
	s_cselect_b32 s29, s68, s72
	s_add_u32 s26, s30, 0x80
	s_addc_u32 s27, s31, 0
	s_add_u32 s34, s34, 0x40080
	s_addc_u32 s35, s35, 0
	s_add_i32 s65, s42, 0xc000
	ds_read_b128 v[184:187], v149
	ds_read_b128 v[188:191], v149 offset:1024
	ds_read_b128 v[192:195], v149 offset:2048
	ds_read_b128 v[196:199], v149 offset:3072
	ds_read_b128 v[200:203], v149 offset:4096
	ds_read_b128 v[204:207], v149 offset:5120
	ds_read_b128 v[208:211], v149 offset:6144
	ds_read_b128 v[212:215], v149 offset:7168
	s_mov_b32 m0, s65
	s_add_i32 s8, s42, 0xe000
	global_load_lds_dwordx4 v138, s[34:35]
	s_mov_b32 m0, s8
	s_nop 0
	global_load_lds_dwordx4 v134, s[34:35]
	s_waitcnt vmcnt(8)
	s_waitcnt lgkmcnt(0)
	s_barrier
	s_waitcnt lgkmcnt(0)
	v_mfma_f32_16x16x32_bf16 v[124:127], v[152:155], v[184:187], v[124:127]
	v_mfma_f32_16x16x32_bf16 v[116:119], v[160:163], v[184:187], v[116:119]
	v_mfma_f32_16x16x32_bf16 v[108:111], v[152:155], v[192:195], v[108:111]
	v_mfma_f32_16x16x32_bf16 v[100:103], v[160:163], v[192:195], v[100:103]
	v_mfma_f32_16x16x32_bf16 v[92:95], v[152:155], v[200:203], v[92:95]
	v_mfma_f32_16x16x32_bf16 v[84:87], v[160:163], v[200:203], v[84:87]
	v_mfma_f32_16x16x32_bf16 v[76:79], v[152:155], v[208:211], v[76:79]
	v_mfma_f32_16x16x32_bf16 v[60:63], v[160:163], v[208:211], v[60:63]
	v_mfma_f32_16x16x32_bf16 v[124:127], v[156:159], v[188:191], v[124:127]
	v_mfma_f32_16x16x32_bf16 v[116:119], v[164:167], v[188:191], v[116:119]
	v_mfma_f32_16x16x32_bf16 v[108:111], v[156:159], v[196:199], v[108:111]
	v_mfma_f32_16x16x32_bf16 v[100:103], v[164:167], v[196:199], v[100:103]
	v_mfma_f32_16x16x32_bf16 v[92:95], v[156:159], v[204:207], v[92:95]
	v_mfma_f32_16x16x32_bf16 v[84:87], v[164:167], v[204:207], v[84:87]
	v_mfma_f32_16x16x32_bf16 v[76:79], v[156:159], v[212:215], v[76:79]
	v_mfma_f32_16x16x32_bf16 v[60:63], v[164:167], v[212:215], v[60:63]
	v_mfma_f32_16x16x32_bf16 v[128:131], v[168:171], v[184:187], v[128:131]
	v_mfma_f32_16x16x32_bf16 v[120:123], v[176:179], v[184:187], v[120:123]
	v_mfma_f32_16x16x32_bf16 v[112:115], v[168:171], v[192:195], v[112:115]
	v_mfma_f32_16x16x32_bf16 v[104:107], v[176:179], v[192:195], v[104:107]
	v_mfma_f32_16x16x32_bf16 v[96:99], v[168:171], v[200:203], v[96:99]
	v_mfma_f32_16x16x32_bf16 v[88:91], v[176:179], v[200:203], v[88:91]
	v_mfma_f32_16x16x32_bf16 v[80:83], v[168:171], v[208:211], v[80:83]
	v_mfma_f32_16x16x32_bf16 v[68:71], v[176:179], v[208:211], v[68:71]
	v_mfma_f32_16x16x32_bf16 v[128:131], v[172:175], v[188:191], v[128:131]
	v_mfma_f32_16x16x32_bf16 v[120:123], v[180:183], v[188:191], v[120:123]
	v_mfma_f32_16x16x32_bf16 v[112:115], v[172:175], v[196:199], v[112:115]
	v_mfma_f32_16x16x32_bf16 v[104:107], v[180:183], v[196:199], v[104:107]
	v_mfma_f32_16x16x32_bf16 v[96:99], v[172:175], v[204:207], v[96:99]
	v_mfma_f32_16x16x32_bf16 v[88:91], v[180:183], v[204:207], v[88:91]
	v_mfma_f32_16x16x32_bf16 v[80:83], v[172:175], v[212:215], v[80:83]
	v_mfma_f32_16x16x32_bf16 v[68:71], v[180:183], v[212:215], v[68:71]
	s_barrier
	s_setprio 1
	s_mov_b64 s[34:35], s[28:29]
	s_add_i32 s64, s59, s38
	ds_read_b128 v[184:187], v149 offset:16384
	ds_read_b128 v[188:191], v149 offset:17408
	ds_read_b128 v[192:195], v149 offset:18432
	ds_read_b128 v[196:199], v149 offset:19456
	ds_read_b128 v[200:203], v149 offset:20480
	ds_read_b128 v[204:207], v149 offset:21504
	ds_read_b128 v[208:211], v149 offset:22528
	ds_read_b128 v[212:215], v149 offset:23552
	s_mov_b32 m0, s64
	s_add_i32 s15, s64, 0x2000
	global_load_lds_dwordx4 v136, s[34:35]
	s_mov_b64 s[98:99], s[34:35]
	s_add_u32 s34, s28, 0x40000
	s_mov_b32 m0, s15
	s_addc_u32 s35, s29, 0
	s_add_i32 s17, s60, s38
	global_load_lds_dwordx4 v132, s[98:99]
	s_mov_b32 m0, s17
	s_add_i32 s63, s17, 0x2000
	global_load_lds_dwordx4 v136, s[34:35]
	s_mov_b64 s[98:99], s[34:35]
	s_mov_b32 m0, s63
	s_mov_b64 s[34:35], s[30:31]
	global_load_lds_dwordx4 v132, s[98:99]
	s_mov_b32 m0, s42
	s_nop 0
	global_load_lds_dwordx4 v138, s[34:35]
	s_mov_b32 m0, s43
	s_nop 0
	global_load_lds_dwordx4 v134, s[34:35]
	s_setprio 0
	s_waitcnt vmcnt(8)
	s_waitcnt lgkmcnt(0)
	s_barrier
	s_waitcnt lgkmcnt(0)
	v_mfma_f32_16x16x32_bf16 v[64:67], v[152:155], v[184:187], v[64:67]
	v_mfma_f32_16x16x32_bf16 v[52:55], v[160:163], v[184:187], v[52:55]
	v_mfma_f32_16x16x32_bf16 v[44:47], v[152:155], v[192:195], v[44:47]
	v_mfma_f32_16x16x32_bf16 v[36:39], v[160:163], v[192:195], v[36:39]
	v_mfma_f32_16x16x32_bf16 v[28:31], v[152:155], v[200:203], v[28:31]
	v_mfma_f32_16x16x32_bf16 v[20:23], v[160:163], v[200:203], v[20:23]
	v_mfma_f32_16x16x32_bf16 v[12:15], v[152:155], v[208:211], v[12:15]
	v_mfma_f32_16x16x32_bf16 v[2:5], v[160:163], v[208:211], v[4:7]
	v_mfma_f32_16x16x32_bf16 v[64:67], v[156:159], v[188:191], v[64:67]
	v_mfma_f32_16x16x32_bf16 v[52:55], v[164:167], v[188:191], v[52:55]
	v_mfma_f32_16x16x32_bf16 v[44:47], v[156:159], v[196:199], v[44:47]
	v_mfma_f32_16x16x32_bf16 v[36:39], v[164:167], v[196:199], v[36:39]
	v_mfma_f32_16x16x32_bf16 v[28:31], v[156:159], v[204:207], v[28:31]
	v_mfma_f32_16x16x32_bf16 v[20:23], v[164:167], v[204:207], v[20:23]
	v_mfma_f32_16x16x32_bf16 v[12:15], v[156:159], v[212:215], v[12:15]
	v_mfma_f32_16x16x32_bf16 v[2:5], v[164:167], v[212:215], v[2:5]
	v_mfma_f32_16x16x32_bf16 v[72:75], v[168:171], v[184:187], v[72:75]
	v_mfma_f32_16x16x32_bf16 v[56:59], v[176:179], v[184:187], v[56:59]
	v_mfma_f32_16x16x32_bf16 v[48:51], v[168:171], v[192:195], v[48:51]
	v_mfma_f32_16x16x32_bf16 v[40:43], v[176:179], v[192:195], v[40:43]
	v_mfma_f32_16x16x32_bf16 v[32:35], v[168:171], v[200:203], v[32:35]
	v_mfma_f32_16x16x32_bf16 v[24:27], v[176:179], v[200:203], v[24:27]
	v_mfma_f32_16x16x32_bf16 v[16:19], v[168:171], v[208:211], v[16:19]
	v_mfma_f32_16x16x32_bf16 v[6:9], v[176:179], v[208:211], v[8:11]
	v_mfma_f32_16x16x32_bf16 v[72:75], v[172:175], v[188:191], v[72:75]
	v_mfma_f32_16x16x32_bf16 v[56:59], v[180:183], v[188:191], v[56:59]
	v_mfma_f32_16x16x32_bf16 v[48:51], v[172:175], v[196:199], v[48:51]
	v_mfma_f32_16x16x32_bf16 v[40:43], v[180:183], v[196:199], v[40:43]
	v_mfma_f32_16x16x32_bf16 v[32:35], v[172:175], v[204:207], v[32:35]
	v_mfma_f32_16x16x32_bf16 v[24:27], v[180:183], v[204:207], v[24:27]
	v_mfma_f32_16x16x32_bf16 v[16:19], v[172:175], v[212:215], v[16:19]
	v_mfma_f32_16x16x32_bf16 v[8:11], v[180:183], v[212:215], v[6:9]
	s_barrier
	s_add_i32 s73, 0, 0x18000
	s_add_i32 s74, 0, 0x1c000
	v_add_u32_e32 v152, s73, v146
	v_add_u32_e32 v153, s74, v146
	ds_read_b128 v[154:157], v152
	ds_read_b128 v[158:161], v152 offset:1024
	ds_read_b128 v[162:165], v152 offset:2048
	ds_read_b128 v[166:169], v152 offset:3072
	ds_read_b128 v[170:173], v153
	ds_read_b128 v[174:177], v153 offset:1024
	ds_read_b128 v[178:181], v153 offset:2048
	ds_read_b128 v[182:185], v153 offset:3072
	s_add_u32 s30, s30, 0x40000
	s_addc_u32 s31, s31, 0
	s_mov_b32 m0, s52
	ds_read_b128 v[186:189], v149 offset:32768
	ds_read_b128 v[190:193], v149 offset:33792
	ds_read_b128 v[194:197], v149 offset:34816
	ds_read_b128 v[198:201], v149 offset:35840
	ds_read_b128 v[202:205], v149 offset:36864
	ds_read_b128 v[206:209], v149 offset:37888
	ds_read_b128 v[210:213], v149 offset:38912
	ds_read_b128 v[214:217], v149 offset:39936
	s_nop 0
	global_load_lds_dwordx4 v138, s[30:31]
	s_mov_b32 m0, s53
	s_nop 0
	global_load_lds_dwordx4 v134, s[30:31]
	s_waitcnt vmcnt(8)
	s_waitcnt lgkmcnt(0)
	s_barrier
	s_waitcnt lgkmcnt(0)
	v_mfma_f32_16x16x32_bf16 v[124:127], v[154:157], v[186:189], v[124:127]
	v_mfma_f32_16x16x32_bf16 v[116:119], v[162:165], v[186:189], v[116:119]
	v_mfma_f32_16x16x32_bf16 v[108:111], v[154:157], v[194:197], v[108:111]
	v_mfma_f32_16x16x32_bf16 v[100:103], v[162:165], v[194:197], v[100:103]
	v_mfma_f32_16x16x32_bf16 v[92:95], v[154:157], v[202:205], v[92:95]
	v_mfma_f32_16x16x32_bf16 v[84:87], v[162:165], v[202:205], v[84:87]
	v_mfma_f32_16x16x32_bf16 v[76:79], v[154:157], v[210:213], v[76:79]
	v_mfma_f32_16x16x32_bf16 v[60:63], v[162:165], v[210:213], v[60:63]
	v_mfma_f32_16x16x32_bf16 v[124:127], v[158:161], v[190:193], v[124:127]
	v_mfma_f32_16x16x32_bf16 v[116:119], v[166:169], v[190:193], v[116:119]
	v_mfma_f32_16x16x32_bf16 v[108:111], v[158:161], v[198:201], v[108:111]
	v_mfma_f32_16x16x32_bf16 v[100:103], v[166:169], v[198:201], v[100:103]
	v_mfma_f32_16x16x32_bf16 v[92:95], v[158:161], v[206:209], v[92:95]
	v_mfma_f32_16x16x32_bf16 v[84:87], v[166:169], v[206:209], v[84:87]
	v_mfma_f32_16x16x32_bf16 v[76:79], v[158:161], v[214:217], v[76:79]
	v_mfma_f32_16x16x32_bf16 v[60:63], v[166:169], v[214:217], v[60:63]
	v_mfma_f32_16x16x32_bf16 v[128:131], v[170:173], v[186:189], v[128:131]
	v_mfma_f32_16x16x32_bf16 v[120:123], v[178:181], v[186:189], v[120:123]
	v_mfma_f32_16x16x32_bf16 v[112:115], v[170:173], v[194:197], v[112:115]
	v_mfma_f32_16x16x32_bf16 v[104:107], v[178:181], v[194:197], v[104:107]
	v_mfma_f32_16x16x32_bf16 v[96:99], v[170:173], v[202:205], v[96:99]
	v_mfma_f32_16x16x32_bf16 v[88:91], v[178:181], v[202:205], v[88:91]
	v_mfma_f32_16x16x32_bf16 v[80:83], v[170:173], v[210:213], v[80:83]
	v_mfma_f32_16x16x32_bf16 v[68:71], v[178:181], v[210:213], v[68:71]
	v_mfma_f32_16x16x32_bf16 v[128:131], v[174:177], v[190:193], v[128:131]
	v_mfma_f32_16x16x32_bf16 v[120:123], v[182:185], v[190:193], v[120:123]
	v_mfma_f32_16x16x32_bf16 v[112:115], v[174:177], v[198:201], v[112:115]
	v_mfma_f32_16x16x32_bf16 v[104:107], v[182:185], v[198:201], v[104:107]
	v_mfma_f32_16x16x32_bf16 v[96:99], v[174:177], v[206:209], v[96:99]
	v_mfma_f32_16x16x32_bf16 v[88:91], v[182:185], v[206:209], v[88:91]
	v_mfma_f32_16x16x32_bf16 v[80:83], v[174:177], v[214:217], v[80:83]
	v_mfma_f32_16x16x32_bf16 v[68:71], v[182:185], v[214:217], v[68:71]
	s_barrier
	s_setprio 1
	s_add_u32 s34, s28, 0x80
	s_addc_u32 s35, s29, 0
	s_add_i32 s31, s73, s38
	ds_read_b128 v[186:189], v149 offset:49152
	ds_read_b128 v[190:193], v149 offset:50176
	ds_read_b128 v[194:197], v149 offset:51200
	ds_read_b128 v[198:201], v149 offset:52224
	ds_read_b128 v[202:205], v149 offset:53248
	ds_read_b128 v[206:209], v149 offset:54272
	ds_read_b128 v[210:213], v149 offset:55296
	ds_read_b128 v[214:217], v149 offset:56320
	s_mov_b32 m0, s31
	s_add_i32 s30, s31, 0x2000
	global_load_lds_dwordx4 v136, s[34:35]
	s_mov_b64 s[98:99], s[34:35]
	s_add_u32 s34, s28, 0x40080
	s_mov_b32 m0, s30
	s_addc_u32 s35, s29, 0
	s_add_i32 s28, s74, s38
	global_load_lds_dwordx4 v132, s[98:99]
	s_mov_b32 m0, s28
	s_add_i32 s29, s28, 0x2000
	global_load_lds_dwordx4 v136, s[34:35]
	s_mov_b32 m0, s29
	s_nop 0
	global_load_lds_dwordx4 v132, s[34:35]
	s_mov_b32 m0, s54
	s_nop 0
	global_load_lds_dwordx4 v138, s[26:27]
	s_mov_b32 m0, s55
	s_nop 0
	global_load_lds_dwordx4 v134, s[26:27]
	s_setprio 0
	s_waitcnt vmcnt(8)
	s_waitcnt lgkmcnt(0)
	s_barrier
	s_waitcnt lgkmcnt(0)
	v_mfma_f32_16x16x32_bf16 v[64:67], v[154:157], v[186:189], v[64:67]
	v_mfma_f32_16x16x32_bf16 v[52:55], v[162:165], v[186:189], v[52:55]
	v_mfma_f32_16x16x32_bf16 v[44:47], v[154:157], v[194:197], v[44:47]
	v_mfma_f32_16x16x32_bf16 v[36:39], v[162:165], v[194:197], v[36:39]
	v_mfma_f32_16x16x32_bf16 v[28:31], v[154:157], v[202:205], v[28:31]
	v_mfma_f32_16x16x32_bf16 v[20:23], v[162:165], v[202:205], v[20:23]
	v_mfma_f32_16x16x32_bf16 v[12:15], v[154:157], v[210:213], v[12:15]
	v_mfma_f32_16x16x32_bf16 v[2:5], v[162:165], v[210:213], v[2:5]
	v_mfma_f32_16x16x32_bf16 v[64:67], v[158:161], v[190:193], v[64:67]
	v_mfma_f32_16x16x32_bf16 v[52:55], v[166:169], v[190:193], v[52:55]
	v_mfma_f32_16x16x32_bf16 v[44:47], v[158:161], v[198:201], v[44:47]
	v_mfma_f32_16x16x32_bf16 v[36:39], v[166:169], v[198:201], v[36:39]
	v_mfma_f32_16x16x32_bf16 v[28:31], v[158:161], v[206:209], v[28:31]
	v_mfma_f32_16x16x32_bf16 v[20:23], v[166:169], v[206:209], v[20:23]
	v_mfma_f32_16x16x32_bf16 v[12:15], v[158:161], v[214:217], v[12:15]
	v_mfma_f32_16x16x32_bf16 v[4:7], v[166:169], v[214:217], v[2:5]
	v_mfma_f32_16x16x32_bf16 v[72:75], v[170:173], v[186:189], v[72:75]
	v_mfma_f32_16x16x32_bf16 v[56:59], v[178:181], v[186:189], v[56:59]
	v_mfma_f32_16x16x32_bf16 v[48:51], v[170:173], v[194:197], v[48:51]
	v_mfma_f32_16x16x32_bf16 v[40:43], v[178:181], v[194:197], v[40:43]
	v_mfma_f32_16x16x32_bf16 v[32:35], v[170:173], v[202:205], v[32:35]
	v_mfma_f32_16x16x32_bf16 v[24:27], v[178:181], v[202:205], v[24:27]
	v_mfma_f32_16x16x32_bf16 v[16:19], v[170:173], v[210:213], v[16:19]
	v_mfma_f32_16x16x32_bf16 v[8:11], v[178:181], v[210:213], v[8:11]
	v_mfma_f32_16x16x32_bf16 v[72:75], v[174:177], v[190:193], v[72:75]
	v_mfma_f32_16x16x32_bf16 v[56:59], v[182:185], v[190:193], v[56:59]
	v_mfma_f32_16x16x32_bf16 v[48:51], v[174:177], v[198:201], v[48:51]
	v_mfma_f32_16x16x32_bf16 v[40:43], v[182:185], v[198:201], v[40:43]
	v_mfma_f32_16x16x32_bf16 v[32:35], v[174:177], v[206:209], v[32:35]
	v_mfma_f32_16x16x32_bf16 v[24:27], v[182:185], v[206:209], v[24:27]
	v_mfma_f32_16x16x32_bf16 v[16:19], v[174:177], v[214:217], v[16:19]
	v_mfma_f32_16x16x32_bf16 v[8:11], v[182:185], v[214:217], v[8:11]
	s_barrier
	s_add_i32 s70, s70, 2
	s_add_u32 s71, s71, 0x100
	s_addc_u32 s72, s72, 0
	s_cmp_gt_u32 s70, 13
	s_mov_b64 s[34:35], s[24:25]
	s_cbranch_scc0 .LBB0_2390
	s_and_b64 vcc, exec, s[12:13]
	s_cbranch_vccz .LBB0_2393
	s_barrier

; #define PG8_STAGE(bufoff, gbase, voff) do { const char* gb_ = (const char*)(gbase); asm volatile("" : "+s"(gb_));   \
;         _Pragma("unroll") for (int _i = 0; _i < 2; ++_i) \
;         __builtin_amdgcn_global_load_lds((const unsigned*)(gb_ + (voff)[_i]), (PG8_LAS unsigned*)(lds + (bufoff) + ldsw + _i * 8192), 16, 0, 0); } while (0)
; #define PG8_WAIT_V(n) asm volatile("s_waitcnt vmcnt(" #n ")" ::: "memory")
; #define PG8_BAR __builtin_amdgcn_s_barrier()
; template <class Epi, class Sched, bool ALIGN_EPI = false, bool SP2 = false>
; __device__ __forceinline__ void gemm_phase(PG8_LAS unsigned char* lds, const Gemm g, const Sched& S, const Epi& E, int wave_s) {
;     ...
;     const int wid = __builtin_amdgcn_readfirstlane(tid >> 6), lane = tid & 63, wr = wid >> 2, wc = wid & 3, fr = lane & 15, fq = lane >> 4;
;     const int K = g.K, nt = K / BK;
;     unsigned voffA[2], voffB[2];
; #pragma unroll
;     for (int i = 0; i < 2; ++i) { int R, C; stage_rc(tid * 16 + i * 8192, R, C); const int Rb = Epi::PERM ? ((R & ~31) + perm32(R & 31)) : R;
;         voffA[i] = (unsigned)(R * K + C) * 2u; voffB[i] = (unsigned)(Rb * K + C) * 2u; }
;     const size_t kstep = (size_t)(BK * 2);
;     const size_t hstep = (size_t)HALF * K * 2;
;     const size_t tstep = 2 * hstep;
;     const unsigned ldsw = (unsigned)wid * 1024u;
;     const int aoff = lds_byte(wr * 64 + fr, fq * 8), boff = lds_byte(wc * 32 + fr, fq * 8);
;     ...
;         PG8_WAIT_V(2); PG8_BAR;
;         PG8_STAGE(PG8_SB(1, 0), cB + kstep, voffB); PG8_STAGE(PG8_SA(1, 0), cA + kstep, voffA); PG8_STAGE(PG8_SB(1, 1), cB + hstep + kstep, voffB);
;         PG8_WAIT_V(6); PG8_BAR;
.LBB0_2458:
	s_lshl_b32 s2, s2, 5
	s_and_b32 s10, s2, 0x60
	s_lshl_b32 s9, s0, 13
	s_lshl_b32 s11, s10, 7
	s_add_u32 s2, s22, 0x80
	s_addc_u32 s3, s23, 0
	s_waitcnt vmcnt(2)
	s_barrier
	s_setprio 1
	s_add_i32 m0, s36, 0x18000
	s_nop 0
	global_load_lds_dwordx4 v130, s[2:3]
	s_add_i32 m0, s36, 0x1a000
	s_nop 0
	global_load_lds_dwordx4 v134, s[2:3]
	s_add_u32 s2, s20, 0x80
	s_addc_u32 s3, s21, 0
	s_add_i32 s41, s36, 0x8000
	s_mov_b32 m0, s41
	s_add_i32 s42, s36, 0xa000
	global_load_lds_dwordx4 v128, s[2:3]
	s_mov_b64 s[98:99], s[2:3]
	s_add_u32 s2, s22, 0xb0080
	s_mov_b32 m0, s42
	s_addc_u32 s3, s23, 0
	global_load_lds_dwordx4 v132, s[98:99]
	s_add_i32 m0, s36, 0x1c000
	s_nop 0
	global_load_lds_dwordx4 v130, s[2:3]
	s_add_i32 m0, s36, 0x1e000
	v_and_b32_e32 v1, 15, v0
	global_load_lds_dwordx4 v134, s[2:3]
	v_lshrrev_b32_e32 v2, 1, v0
	v_and_b32_e32 v2, 24, v2
	v_lshlrev_b32_e32 v3, 1, v2
	v_lshlrev_b32_e32 v0, 2, v0
	v_lshl_or_b32 v146, s0, 6, v1
	v_lshl_or_b32 v1, v1, 6, v3
	v_and_b32_e32 v0, 32, v0
	s_setprio 0
	s_waitcnt vmcnt(6)
	s_cmpk_lt_u32 s8, 0x100
	v_bitop3_b32 v3, v1, s9, v0 bitop3:0xde
	v_bitop3_b32 v147, v1, s11, v0 bitop3:0xde
	s_cselect_b64 s[8:9], -1, 0
	s_add_i32 s43, 0, 0x10000
	s_add_i32 s44, 0, 0x14000
	s_sext_i32_i8 s53, s1
	v_or_b32_e32 v148, s10, v2
	v_mov_b64_e32 v[136:137], 0x100
	v_mov_b64_e32 v[138:139], 0xff
	v_add_u32_e32 v149, s43, v147
	v_add_u32_e32 v150, s44, v147
	v_add_u32_e32 v151, 0, v3
	s_mov_b64 s[10:11], 0x20000
	s_mov_b64 s[12:13], 0x24000
	s_mov_b64 s[14:15], 0x28000
	s_mov_b64 s[16:17], 0x2c000
	s_barrier
	s_branch .LBB0_2461

; template <class Epi, class Sched, bool ALIGN_EPI = false, bool SP2 = false>
; __device__ __forceinline__ void gemm_phase(PG8_LAS unsigned char* lds, const Gemm g, const Sched& S, const Epi& E, int wave_s) {
;     ...
;             const bool last = (t == nt - 2);
;             const char* a1 = cA + (size_t)(t + 1) * kstep;
;             const char* a2 = last ? nA : cA + (size_t)(t + 2) * kstep; const char* b2 = last ? nB : cB + (size_t)(t + 2) * kstep;
;             const char* a3 = a2 + kstep; const char* b3 = b2 + kstep;
.LBB0_2472:
	ds_read_b128 v[140:143], v149
	ds_read_b128 v[152:155], v149 offset:1024
	ds_read_b128 v[156:159], v149 offset:2048
	ds_read_b128 v[160:163], v149 offset:3072
	ds_read_b128 v[164:167], v150
	ds_read_b128 v[168:171], v150 offset:1024
	ds_read_b128 v[172:175], v150 offset:2048
	ds_read_b128 v[176:179], v150 offset:3072
	s_add_u32 s22, s20, 0x100
	s_addc_u32 s23, s21, 0
	s_cmp_eq_u32 s56, 40
	s_cselect_b32 s28, s2, s22
	s_cselect_b32 s29, s3, s23
	s_cselect_b32 s26, s18, s54
	s_cselect_b32 s27, s19, s55
	s_add_u32 s24, s28, 0x80
	s_addc_u32 s25, s29, 0
	s_add_u32 s20, s20, 0xb0080
	s_addc_u32 s21, s21, 0
	ds_read_b128 v[180:183], v151
	ds_read_b128 v[184:187], v151 offset:1024
	ds_read_b128 v[188:191], v151 offset:2048
	ds_read_b128 v[192:195], v151 offset:3072
	ds_read_b128 v[196:199], v151 offset:4096
	ds_read_b128 v[200:203], v151 offset:5120
	ds_read_b128 v[204:207], v151 offset:6144
	ds_read_b128 v[208:211], v151 offset:7168
	s_add_i32 m0, s36, 0xc000
	s_nop 0
	global_load_lds_dwordx4 v128, s[20:21]
	s_add_i32 m0, s36, 0xe000
	s_nop 0
	global_load_lds_dwordx4 v132, s[20:21]
	s_waitcnt vmcnt(8)
	s_waitcnt lgkmcnt(0)
	s_barrier
	s_waitcnt lgkmcnt(0)
	v_mfma_f32_16x16x32_bf16 v[124:127], v[140:143], v[180:183], v[124:127]
	v_mfma_f32_16x16x32_bf16 v[120:123], v[156:159], v[180:183], v[120:123]
	v_mfma_f32_16x16x32_bf16 v[108:111], v[140:143], v[188:191], v[108:111]
	v_mfma_f32_16x16x32_bf16 v[104:107], v[156:159], v[188:191], v[104:107]
	v_mfma_f32_16x16x32_bf16 v[92:95], v[140:143], v[196:199], v[92:95]
	v_mfma_f32_16x16x32_bf16 v[88:91], v[156:159], v[196:199], v[88:91]
	v_mfma_f32_16x16x32_bf16 v[76:79], v[140:143], v[204:207], v[76:79]
	v_mfma_f32_16x16x32_bf16 v[72:75], v[156:159], v[204:207], v[72:75]
	v_mfma_f32_16x16x32_bf16 v[124:127], v[152:155], v[184:187], v[124:127]
	v_mfma_f32_16x16x32_bf16 v[120:123], v[160:163], v[184:187], v[120:123]
	v_mfma_f32_16x16x32_bf16 v[108:111], v[152:155], v[192:195], v[108:111]
	v_mfma_f32_16x16x32_bf16 v[104:107], v[160:163], v[192:195], v[104:107]
	v_mfma_f32_16x16x32_bf16 v[92:95], v[152:155], v[200:203], v[92:95]
	v_mfma_f32_16x16x32_bf16 v[88:91], v[160:163], v[200:203], v[88:91]
	v_mfma_f32_16x16x32_bf16 v[76:79], v[152:155], v[208:211], v[76:79]
	v_mfma_f32_16x16x32_bf16 v[72:75], v[160:163], v[208:211], v[72:75]
	v_mfma_f32_16x16x32_bf16 v[116:119], v[164:167], v[180:183], v[116:119]
	v_mfma_f32_16x16x32_bf16 v[112:115], v[172:175], v[180:183], v[112:115]
	v_mfma_f32_16x16x32_bf16 v[100:103], v[164:167], v[188:191], v[100:103]
	v_mfma_f32_16x16x32_bf16 v[96:99], v[172:175], v[188:191], v[96:99]
	v_mfma_f32_16x16x32_bf16 v[84:87], v[164:167], v[196:199], v[84:87]
	v_mfma_f32_16x16x32_bf16 v[80:83], v[172:175], v[196:199], v[80:83]
	v_mfma_f32_16x16x32_bf16 v[68:71], v[164:167], v[204:207], v[68:71]
	v_mfma_f32_16x16x32_bf16 v[64:67], v[172:175], v[204:207], v[64:67]
	v_mfma_f32_16x16x32_bf16 v[116:119], v[168:171], v[184:187], v[116:119]
	v_mfma_f32_16x16x32_bf16 v[112:115], v[176:179], v[184:187], v[112:115]
	v_mfma_f32_16x16x32_bf16 v[100:103], v[168:171], v[192:195], v[100:103]
	v_mfma_f32_16x16x32_bf16 v[96:99], v[176:179], v[192:195], v[96:99]
	v_mfma_f32_16x16x32_bf16 v[84:87], v[168:171], v[200:203], v[84:87]
	v_mfma_f32_16x16x32_bf16 v[80:83], v[176:179], v[200:203], v[80:83]
	v_mfma_f32_16x16x32_bf16 v[68:71], v[168:171], v[208:211], v[68:71]
	v_mfma_f32_16x16x32_bf16 v[64:67], v[176:179], v[208:211], v[64:67]
	s_barrier
	s_setprio 1
	s_mov_b64 s[20:21], s[26:27]
	s_add_i32 s57, s43, s35
	ds_read_b128 v[180:183], v151 offset:16384
	ds_read_b128 v[184:187], v151 offset:17408
	ds_read_b128 v[188:191], v151 offset:18432
	ds_read_b128 v[192:195], v151 offset:19456
	ds_read_b128 v[196:199], v151 offset:20480
	ds_read_b128 v[200:203], v151 offset:21504
	ds_read_b128 v[204:207], v151 offset:22528
	ds_read_b128 v[208:211], v151 offset:23552
	s_mov_b32 m0, s57
	s_nop 0
	global_load_lds_dwordx4 v130, s[20:21]
	s_add_i32 m0, s57, 0x2000
	s_nop 0
	global_load_lds_dwordx4 v134, s[20:21]
	s_add_u32 s20, s26, 0xb0000
	s_addc_u32 s21, s27, 0
	s_add_i32 s57, s44, s35
	s_mov_b32 m0, s57
	s_nop 0
	global_load_lds_dwordx4 v130, s[20:21]
	s_mov_b64 s[98:99], s[20:21]
	s_add_i32 m0, s57, 0x2000
	s_mov_b64 s[20:21], s[28:29]
	global_load_lds_dwordx4 v134, s[98:99]
	s_mov_b32 m0, s36
	s_nop 0
	global_load_lds_dwordx4 v128, s[20:21]
	s_mov_b32 m0, s37
	s_nop 0
	global_load_lds_dwordx4 v132, s[20:21]
	s_setprio 0
	s_waitcnt vmcnt(8)
	s_waitcnt lgkmcnt(0)
	s_barrier
	s_waitcnt lgkmcnt(0)
	v_mfma_f32_16x16x32_bf16 v[60:63], v[140:143], v[180:183], v[60:63]
	v_mfma_f32_16x16x32_bf16 v[56:59], v[156:159], v[180:183], v[56:59]
	v_mfma_f32_16x16x32_bf16 v[44:47], v[140:143], v[188:191], v[44:47]
	v_mfma_f32_16x16x32_bf16 v[40:43], v[156:159], v[188:191], v[40:43]
	v_mfma_f32_16x16x32_bf16 v[28:31], v[140:143], v[196:199], v[28:31]
	v_mfma_f32_16x16x32_bf16 v[24:27], v[156:159], v[196:199], v[24:27]
	v_mfma_f32_16x16x32_bf16 v[12:15], v[140:143], v[204:207], v[12:15]
	v_mfma_f32_16x16x32_bf16 v[8:11], v[156:159], v[204:207], v[8:11]
	v_mfma_f32_16x16x32_bf16 v[60:63], v[152:155], v[184:187], v[60:63]
	v_mfma_f32_16x16x32_bf16 v[56:59], v[160:163], v[184:187], v[56:59]
	v_mfma_f32_16x16x32_bf16 v[44:47], v[152:155], v[192:195], v[44:47]
	v_mfma_f32_16x16x32_bf16 v[40:43], v[160:163], v[192:195], v[40:43]
	v_mfma_f32_16x16x32_bf16 v[28:31], v[152:155], v[200:203], v[28:31]
	v_mfma_f32_16x16x32_bf16 v[24:27], v[160:163], v[200:203], v[24:27]
	v_mfma_f32_16x16x32_bf16 v[12:15], v[152:155], v[208:211], v[12:15]
	v_mfma_f32_16x16x32_bf16 v[8:11], v[160:163], v[208:211], v[8:11]
	v_mfma_f32_16x16x32_bf16 v[52:55], v[164:167], v[180:183], v[52:55]
	v_mfma_f32_16x16x32_bf16 v[48:51], v[172:175], v[180:183], v[48:51]
	v_mfma_f32_16x16x32_bf16 v[36:39], v[164:167], v[188:191], v[36:39]
	v_mfma_f32_16x16x32_bf16 v[32:35], v[172:175], v[188:191], v[32:35]
	v_mfma_f32_16x16x32_bf16 v[20:23], v[164:167], v[196:199], v[20:23]
	v_mfma_f32_16x16x32_bf16 v[16:19], v[172:175], v[196:199], v[16:19]
	v_mfma_f32_16x16x32_bf16 v[4:7], v[164:167], v[204:207], v[4:7]
	v_mfma_f32_16x16x32_bf16 v[0:3], v[172:175], v[204:207], v[0:3]
	v_mfma_f32_16x16x32_bf16 v[52:55], v[168:171], v[184:187], v[52:55]
	v_mfma_f32_16x16x32_bf16 v[48:51], v[176:179], v[184:187], v[48:51]
	v_mfma_f32_16x16x32_bf16 v[36:39], v[168:171], v[192:195], v[36:39]
	v_mfma_f32_16x16x32_bf16 v[32:35], v[176:179], v[192:195], v[32:35]
	v_mfma_f32_16x16x32_bf16 v[20:23], v[168:171], v[200:203], v[20:23]
	v_mfma_f32_16x16x32_bf16 v[16:19], v[176:179], v[200:203], v[16:19]
	v_mfma_f32_16x16x32_bf16 v[4:7], v[168:171], v[208:211], v[4:7]
	v_mfma_f32_16x16x32_bf16 v[0:3], v[176:179], v[208:211], v[0:3]
	s_barrier
	s_add_i32 s57, 0, 0x18000
	v_add_u32_e32 v144, s57, v147
	s_add_i32 s58, 0, 0x1c000
	ds_read_b128 v[140:143], v144
	ds_read_b128 v[152:155], v144 offset:1024
	ds_read_b128 v[156:159], v144 offset:2048
	ds_read_b128 v[160:163], v144 offset:3072
	v_add_u32_e32 v144, s58, v147
	ds_read_b128 v[164:167], v144
	ds_read_b128 v[168:171], v144 offset:1024
	ds_read_b128 v[172:175], v144 offset:2048
	ds_read_b128 v[176:179], v144 offset:3072
	s_add_u32 s20, s28, 0xb0000
	s_addc_u32 s21, s29, 0
	s_mov_b32 m0, s38
	ds_read_b128 v[180:183], v151 offset:32768
	ds_read_b128 v[184:187], v151 offset:33792
	ds_read_b128 v[188:191], v151 offset:34816
	ds_read_b128 v[192:195], v151 offset:35840
	ds_read_b128 v[196:199], v151 offset:36864
	ds_read_b128 v[200:203], v151 offset:37888
	ds_read_b128 v[204:207], v151 offset:38912
	ds_read_b128 v[208:211], v151 offset:39936
	s_nop 0
	global_load_lds_dwordx4 v128, s[20:21]
	s_mov_b32 m0, s39
	s_nop 0
	global_load_lds_dwordx4 v132, s[20:21]
	s_waitcnt vmcnt(8)
	s_waitcnt lgkmcnt(0)
	s_barrier
	s_waitcnt lgkmcnt(0)
	v_mfma_f32_16x16x32_bf16 v[124:127], v[140:143], v[180:183], v[124:127]
	v_mfma_f32_16x16x32_bf16 v[120:123], v[156:159], v[180:183], v[120:123]
	v_mfma_f32_16x16x32_bf16 v[108:111], v[140:143], v[188:191], v[108:111]
	v_mfma_f32_16x16x32_bf16 v[104:107], v[156:159], v[188:191], v[104:107]
	v_mfma_f32_16x16x32_bf16 v[92:95], v[140:143], v[196:199], v[92:95]
	v_mfma_f32_16x16x32_bf16 v[88:91], v[156:159], v[196:199], v[88:91]
	v_mfma_f32_16x16x32_bf16 v[76:79], v[140:143], v[204:207], v[76:79]
	v_mfma_f32_16x16x32_bf16 v[72:75], v[156:159], v[204:207], v[72:75]
	v_mfma_f32_16x16x32_bf16 v[124:127], v[152:155], v[184:187], v[124:127]
	v_mfma_f32_16x16x32_bf16 v[120:123], v[160:163], v[184:187], v[120:123]
	v_mfma_f32_16x16x32_bf16 v[108:111], v[152:155], v[192:195], v[108:111]
	v_mfma_f32_16x16x32_bf16 v[104:107], v[160:163], v[192:195], v[104:107]
	v_mfma_f32_16x16x32_bf16 v[92:95], v[152:155], v[200:203], v[92:95]
	v_mfma_f32_16x16x32_bf16 v[88:91], v[160:163], v[200:203], v[88:91]
	v_mfma_f32_16x16x32_bf16 v[76:79], v[152:155], v[208:211], v[76:79]
	v_mfma_f32_16x16x32_bf16 v[72:75], v[160:163], v[208:211], v[72:75]
	v_mfma_f32_16x16x32_bf16 v[116:119], v[164:167], v[180:183], v[116:119]
	v_mfma_f32_16x16x32_bf16 v[112:115], v[172:175], v[180:183], v[112:115]
	v_mfma_f32_16x16x32_bf16 v[100:103], v[164:167], v[188:191], v[100:103]
	v_mfma_f32_16x16x32_bf16 v[96:99], v[172:175], v[188:191], v[96:99]
	v_mfma_f32_16x16x32_bf16 v[84:87], v[164:167], v[196:199], v[84:87]
	v_mfma_f32_16x16x32_bf16 v[80:83], v[172:175], v[196:199], v[80:83]
	v_mfma_f32_16x16x32_bf16 v[68:71], v[164:167], v[204:207], v[68:71]
	v_mfma_f32_16x16x32_bf16 v[64:67], v[172:175], v[204:207], v[64:67]
	v_mfma_f32_16x16x32_bf16 v[116:119], v[168:171], v[184:187], v[116:119]
	v_mfma_f32_16x16x32_bf16 v[112:115], v[176:179], v[184:187], v[112:115]
	v_mfma_f32_16x16x32_bf16 v[100:103], v[168:171], v[192:195], v[100:103]
	v_mfma_f32_16x16x32_bf16 v[96:99], v[176:179], v[192:195], v[96:99]
	v_mfma_f32_16x16x32_bf16 v[84:87], v[168:171], v[200:203], v[84:87]
	v_mfma_f32_16x16x32_bf16 v[80:83], v[176:179], v[200:203], v[80:83]
	v_mfma_f32_16x16x32_bf16 v[68:71], v[168:171], v[208:211], v[68:71]
	v_mfma_f32_16x16x32_bf16 v[64:67], v[176:179], v[208:211], v[64:67]
	s_barrier
	s_setprio 1
	s_add_u32 s20, s26, 0x80
	s_addc_u32 s21, s27, 0
	s_add_i32 s28, s57, s35
	ds_read_b128 v[180:183], v151 offset:49152
	ds_read_b128 v[184:187], v151 offset:50176
	ds_read_b128 v[188:191], v151 offset:51200
	ds_read_b128 v[192:195], v151 offset:52224
	ds_read_b128 v[196:199], v151 offset:53248
	ds_read_b128 v[200:203], v151 offset:54272
	ds_read_b128 v[204:207], v151 offset:55296
	ds_read_b128 v[208:211], v151 offset:56320
	s_mov_b32 m0, s28
	s_nop 0
	global_load_lds_dwordx4 v130, s[20:21]
	s_add_i32 m0, s28, 0x2000
	s_nop 0
	global_load_lds_dwordx4 v134, s[20:21]
	s_add_u32 s20, s26, 0xb0080
	s_addc_u32 s21, s27, 0
	s_add_i32 s26, s58, s35
	s_mov_b32 m0, s26
	s_nop 0
	global_load_lds_dwordx4 v130, s[20:21]
	s_add_i32 m0, s26, 0x2000
	s_nop 0
	global_load_lds_dwordx4 v134, s[20:21]
	s_mov_b32 m0, s41
	s_nop 0
	global_load_lds_dwordx4 v128, s[24:25]
	s_mov_b32 m0, s42
	s_nop 0
	global_load_lds_dwordx4 v132, s[24:25]
	s_setprio 0
	s_waitcnt vmcnt(8)
	s_waitcnt lgkmcnt(0)
	s_barrier
	s_waitcnt lgkmcnt(0)
	v_mfma_f32_16x16x32_bf16 v[60:63], v[140:143], v[180:183], v[60:63]
	v_mfma_f32_16x16x32_bf16 v[56:59], v[156:159], v[180:183], v[56:59]
	v_mfma_f32_16x16x32_bf16 v[44:47], v[140:143], v[188:191], v[44:47]
	v_mfma_f32_16x16x32_bf16 v[40:43], v[156:159], v[188:191], v[40:43]
	v_mfma_f32_16x16x32_bf16 v[28:31], v[140:143], v[196:199], v[28:31]
	v_mfma_f32_16x16x32_bf16 v[24:27], v[156:159], v[196:199], v[24:27]
	v_mfma_f32_16x16x32_bf16 v[12:15], v[140:143], v[204:207], v[12:15]
	v_mfma_f32_16x16x32_bf16 v[8:11], v[156:159], v[204:207], v[8:11]
	v_mfma_f32_16x16x32_bf16 v[60:63], v[152:155], v[184:187], v[60:63]
	v_mfma_f32_16x16x32_bf16 v[56:59], v[160:163], v[184:187], v[56:59]
	v_mfma_f32_16x16x32_bf16 v[44:47], v[152:155], v[192:195], v[44:47]
	v_mfma_f32_16x16x32_bf16 v[40:43], v[160:163], v[192:195], v[40:43]
	v_mfma_f32_16x16x32_bf16 v[28:31], v[152:155], v[200:203], v[28:31]
	v_mfma_f32_16x16x32_bf16 v[24:27], v[160:163], v[200:203], v[24:27]
	v_mfma_f32_16x16x32_bf16 v[12:15], v[152:155], v[208:211], v[12:15]
	v_mfma_f32_16x16x32_bf16 v[8:11], v[160:163], v[208:211], v[8:11]
	v_mfma_f32_16x16x32_bf16 v[52:55], v[164:167], v[180:183], v[52:55]
	v_mfma_f32_16x16x32_bf16 v[48:51], v[172:175], v[180:183], v[48:51]
	v_mfma_f32_16x16x32_bf16 v[36:39], v[164:167], v[188:191], v[36:39]
	v_mfma_f32_16x16x32_bf16 v[32:35], v[172:175], v[188:191], v[32:35]
	v_mfma_f32_16x16x32_bf16 v[20:23], v[164:167], v[196:199], v[20:23]
	v_mfma_f32_16x16x32_bf16 v[16:19], v[172:175], v[196:199], v[16:19]
	v_mfma_f32_16x16x32_bf16 v[4:7], v[164:167], v[204:207], v[4:7]
	v_mfma_f32_16x16x32_bf16 v[0:3], v[172:175], v[204:207], v[0:3]
	v_mfma_f32_16x16x32_bf16 v[52:55], v[168:171], v[184:187], v[52:55]
	v_mfma_f32_16x16x32_bf16 v[48:51], v[176:179], v[184:187], v[48:51]
	v_mfma_f32_16x16x32_bf16 v[36:39], v[168:171], v[192:195], v[36:39]
	v_mfma_f32_16x16x32_bf16 v[32:35], v[176:179], v[192:195], v[32:35]
	v_mfma_f32_16x16x32_bf16 v[20:23], v[168:171], v[200:203], v[20:23]
	v_mfma_f32_16x16x32_bf16 v[16:19], v[176:179], v[200:203], v[16:19]
	v_mfma_f32_16x16x32_bf16 v[4:7], v[168:171], v[208:211], v[4:7]
	v_mfma_f32_16x16x32_bf16 v[0:3], v[176:179], v[208:211], v[0:3]
	s_barrier
	s_add_i32 s56, s56, 2
	s_add_u32 s54, s54, 0x100
	s_addc_u32 s55, s55, 0
	s_cmp_gt_u32 s56, 41
	s_mov_b64 s[20:21], s[22:23]
	s_cbranch_scc0 .LBB0_2472
	s_and_b64 vcc, exec, s[8:9]
	s_cbranch_vccz .LBB0_2475
	s_barrier
